# unpack all v_pk_{mul,add,fma}_f32 in step loop into scalar f32 pairs (bit-identical math)
# speedup vs baseline: 1.0020x; 1.0020x over previous
.LBB0_236:
	s_lshl_b32 s10, s13, 8
	s_add_i32 s18, s10, 0xfffffe00
	s_mov_b32 s19, s85
	s_lshl_b64 s[6:7], s[18:19], 1
	v_readlane_b32 s8, v242, 3
	s_add_u32 s20, s8, s6
	v_readlane_b32 s6, v242, 4
	s_addc_u32 s21, s6, s7
	s_ashr_i32 s11, s10, 31
	s_lshl_b64 s[6:7], s[10:11], 1
	v_readlane_b32 s8, v242, 5
	s_add_u32 s22, s8, s6
	v_readlane_b32 s8, v242, 6
	s_addc_u32 s23, s8, s7
	s_add_i32 s84, s10, 0xfffffb00
	s_lshl_b64 s[8:9], s[84:85], 1
	v_readlane_b32 s11, v242, 7
	s_add_u32 s24, s11, s8
	v_readlane_b32 s8, v242, 8
	s_addc_u32 s25, s8, s9
	s_ashr_i32 s19, s18, 31
	s_lshl_b64 s[8:9], s[18:19], 1
	v_readlane_b32 s11, v242, 11
	s_add_u32 s64, s11, s8
	v_readlane_b32 s8, v242, 12
	s_addc_u32 s65, s8, s9
	s_add_u32 s28, s2, s6
	s_addc_u32 s29, s3, s7
	s_waitcnt vmcnt(0)
	v_mul_f32_e32 v147, 0x3e16c740, v146
	v_cndmask_b32_e64 v178, v146, v147, s[52:53]
	v_lshlrev_b64 v[146:147], 11, v[144:145]
	s_cmp_lt_i32 s13, 2
	v_lshl_add_u64 v[170:171], s[88:89], 0, v[146:147]
	v_lshl_add_u64 v[168:169], s[34:35], 0, v[146:147]
	v_lshlrev_b64 v[146:147], 13, v[144:145]
	v_readlane_b32 s6, v243, 44
	s_cselect_b64 s[40:41], -1, 0
	s_cmp_gt_i32 s13, 1
	v_lshl_add_u64 v[182:183], s[28:29], 0, v[146:147]
	v_lshl_add_u32 v146, v194, 3, s6
	s_cselect_b64 s[6:7], -1, 0
	s_cmp_lg_u32 s13, 0
	s_cselect_b64 s[14:15], -1, 0
	s_cmp_gt_i32 s13, 3
	s_cselect_b64 s[8:9], -1, 0
	s_cmp_lg_u32 s13, 4
	s_cselect_b64 s[16:17], -1, 0
	s_cmp_eq_u32 s13, 1
	v_lshlrev_b64 v[154:155], 10, v[144:145]
	v_lshlrev_b64 v[150:151], 12, v[144:145]
	v_writelane_b32 v242, s16, 16
	s_cselect_b64 s[42:43], -1, 0
	s_cmp_lg_u32 s13, 1
	v_lshl_add_u64 v[174:175], v[148:149], 0, v[150:151]
	v_lshl_add_u64 v[162:163], s[2:3], 0, v[154:155]
	v_mul_f32_e32 v172, v128, v178
	v_mul_f32_e32 v173, v129, v178
	v_mul_f32_e32 v176, v126, v178
	v_mul_f32_e32 v177, v127, v178
	v_mul_f32_e32 v186, v124, v178
	v_mul_f32_e32 v187, v125, v178
	v_mul_f32_e32 v188, v122, v178
	v_mul_f32_e32 v189, v123, v178
	v_cmp_ne_u64_e64 s[38:39], 0, v[148:149]
	v_writelane_b32 v242, s17, 17
	s_cselect_b64 s[16:17], -1, 0
	s_cmp_lt_i32 s62, 4
	s_mov_b64 s[82:83], -1
	s_cbranch_scc1 .LBB0_255
	s_cmp_lt_i32 s62, 6
	s_mov_b64 s[50:51], -1
	s_cbranch_scc1 .LBB0_246
	s_cmp_gt_i32 s62, 6
	s_cbranch_scc0 .LBB0_240
	v_max_f32_e32 v123, v188, v188
	v_max_f32_e32 v127, v186, v186
	v_max_f32_e32 v122, v176, v176
	v_max_f32_e32 v124, 0, v123
	v_max_f32_e32 v123, v177, v177
	v_max_f32_e32 v125, v189, v189
	v_max_f32_e32 v126, v172, v172
	v_max_f32_e32 v128, 0, v127
	v_max_f32_e32 v127, v173, v173
	v_max_f32_e32 v129, v187, v187
	v_max_f32_e32 v122, 0, v122
	v_max_f32_e32 v123, 0, v123
	v_max_f32_e32 v125, 0, v125
	v_max_f32_e32 v126, 0, v126
	v_max_f32_e32 v127, 0, v127
	v_max_f32_e32 v129, 0, v129
	v_mul_f32_e32 v122, v122, v122
	v_mul_f32_e32 v123, v123, v123
	v_mul_f32_e32 v124, v124, v124
	v_mul_f32_e32 v125, v125, v125
	v_mul_f32_e32 v126, v126, v126
	v_mul_f32_e32 v127, v127, v127
	v_mul_f32_e32 v128, v128, v128
	v_mul_f32_e32 v129, v129, v129
	v_ashrrev_i32_e32 v147, 31, v146
	v_lshl_add_u64 v[150:151], v[146:147], 1, v[182:183]
	v_cvt_pk_bf16_f32 v122, v122, v123
	v_cvt_pk_bf16_f32 v123, v126, v127
	v_cvt_pk_bf16_f32 v124, v124, v125
	v_cvt_pk_bf16_f32 v125, v128, v129
	s_mov_b64 s[50:51], 0
	global_store_dwordx4 v[150:151], v[122:125], off

.LBB0_244:
	s_waitcnt vmcnt(0)
	v_add_f32_e32 v152, v172, v124
	v_add_f32_e32 v153, v173, v125
	v_add_f32_e32 v156, v176, v122
	v_add_f32_e32 v157, v177, v123
	v_add_f32_e32 v128, v186, v128
	v_add_f32_e32 v129, v187, v129
	v_add_f32_e32 v126, v188, v126
	v_add_f32_e32 v127, v189, v127
	v_cvt_pk_bf16_f32 v122, v156, v157
	v_cvt_pk_bf16_f32 v123, v152, v153
	v_cvt_pk_bf16_f32 v124, v126, v127
	v_cvt_pk_bf16_f32 v125, v128, v129
	global_store_dwordx4 v[150:151], v[122:125], off
	v_mul_f32_e32 v126, v126, v126
	v_mul_f32_e32 v127, v127, v127
	s_nop 0
	v_mul_f32_e32 v122, v152, v152
	v_mul_f32_e32 v123, v153, v153
	v_mul_f32_e32 v124, v156, v156
	v_mul_f32_e32 v125, v157, v157
	s_nop 0
	v_pk_mov_b32 v[150:151], v[124:125], v[122:123] op_sel:[1,0]
	v_mov_b32_e32 v125, v123
	v_add_f32_e32 v122, v150, v124
	v_add_f32_e32 v123, v151, v125
	v_mul_f32_e32 v124, v128, v128
	v_mul_f32_e32 v125, v129, v129
	v_mov_b32_e32 v129, v126
	v_mov_b32_e32 v128, v124
	v_mov_b32_e32 v126, v125
	v_add_f32_e32 v124, v128, v126
	v_add_f32_e32 v125, v129, v127
	v_add_f32_e32 v122, v122, v123
	v_add_f32_e32 v122, v122, v125
	v_add_f32_e32 v195, v124, v122

.LBB0_250:
	s_waitcnt vmcnt(0)
	v_cvt_f32_ubyte3_e32 v157, v126
	v_cvt_f32_ubyte2_e32 v156, v126
	v_cvt_f32_ubyte1_e32 v159, v126
	v_cvt_f32_ubyte0_e32 v158, v126
	v_mul_f32_e32 v158, s26, v158
	v_mul_f32_e32 v159, s26, v159
	v_mul_f32_e32 v156, s26, v156
	v_mul_f32_e32 v157, s26, v157
	v_fma_f32 v150, v176, v158, v150
	v_fma_f32 v151, v177, v159, v151
	v_fma_f32 v152, v172, v156, v152
	v_fma_f32 v153, v173, v157, v153
	v_cvt_f32_ubyte3_e32 v157, v127
	v_cvt_f32_ubyte2_e32 v156, v127
	v_cvt_f32_ubyte1_e32 v159, v127
	v_cvt_f32_ubyte0_e32 v158, v127
	v_mul_f32_e32 v126, s26, v158
	v_mul_f32_e32 v127, s26, v159
	v_mul_f32_e32 v156, s26, v156
	v_mul_f32_e32 v157, s26, v157
	v_fma_f32 v126, v188, v126, v124
	v_fma_f32 v127, v189, v127, v125
	v_fma_f32 v128, v186, v156, v128
	v_fma_f32 v129, v187, v157, v129
	v_cvt_pk_bf16_f32 v124, v150, v151
	v_cvt_pk_bf16_f32 v125, v152, v153
	v_cvt_pk_bf16_f32 v126, v126, v127
	v_cvt_pk_bf16_f32 v127, v128, v129
	s_mov_b64 s[50:51], 0
	global_store_dwordx4 v[122:123], v[124:127], off

.LBB0_263:
	s_andn2_b64 vcc, exec, s[50:51]
	s_cbranch_vccnz .LBB0_268
	s_mov_b64 s[50:51], -1
	s_and_b64 vcc, exec, s[6:7]
	s_cbranch_vccz .LBB0_266
	global_load_dwordx4 v[122:125], v[156:157], off offset:16
	global_load_dwordx4 v[196:199], v[156:157], off
	v_readlane_b32 s11, v243, 49
	s_lshl_b32 s84, s11, 1
	s_mov_b64 s[50:51], 0x6800080
	s_waitcnt vmcnt(0)
	v_mov_b32_e32 v201, v198
	v_mov_b32_e32 v198, v197
	v_mov_b32_e32 v200, v196
	v_mul_f32_e32 v196, v188, v198
	v_mul_f32_e32 v197, v189, v199
	v_mul_f32_e32 v198, v176, v198
	v_mul_f32_e32 v199, v177, v199
	v_fma_f32 v196, v176, v200, -v196
	v_fma_f32 v197, v177, v201, -v197
	v_fma_f32 v198, v188, v200, v198
	v_fma_f32 v199, v189, v201, v199
	v_mov_b32_e32 v201, v124
	v_mov_b32_e32 v124, v123
	v_mov_b32_e32 v200, v122
	v_mul_f32_e32 v122, v186, v124
	v_mul_f32_e32 v123, v187, v125
	v_mul_f32_e32 v124, v172, v124
	v_mul_f32_e32 v125, v173, v125
	v_fma_f32 v122, v172, v200, -v122
	v_fma_f32 v123, v173, v201, -v123
	v_fma_f32 v124, v186, v200, v124
	v_fma_f32 v125, v187, v201, v125
	v_cvt_pk_bf16_f32 v196, v196, v197
	v_cvt_pk_bf16_f32 v197, v122, v123
	v_cvt_pk_bf16_f32 v123, v124, v125
	v_lshl_add_u64 v[124:125], v[158:159], 0, s[84:85]
	v_lshl_add_u64 v[124:125], v[126:127], 1, v[124:125]
	v_cvt_pk_bf16_f32 v122, v198, v199
	v_lshl_add_u64 v[198:199], v[124:125], 0, s[50:51]
	v_add_co_u32_e32 v124, vcc, 0x6800000, v124
	s_mov_b64 s[50:51], 0
	s_nop 0
	v_addc_co_u32_e32 v125, vcc, 0, v125, vcc
	global_store_dwordx2 v[124:125], v[196:197], off offset:128
	global_store_dwordx2 v[198:199], v[122:123], off offset:32

.LBB0_269:
	s_andn2_b64 vcc, exec, s[50:51]
	v_mov_b32_e32 v195, 0
	s_cbranch_vccnz .LBB0_293
	s_cmp_lg_u32 s62, 1
	s_mov_b64 s[50:51], -1
	s_cbranch_scc0 .LBB0_287
	v_ashrrev_i32_e32 v147, 31, v146
	s_and_b64 vcc, exec, s[14:15]
	s_cbranch_vccz .LBB0_1271
	v_lshlrev_b64 v[122:123], 8, v[144:145]
	s_and_b64 vcc, exec, s[16:17]
	s_cbranch_vccz .LBB0_282
	s_and_b64 vcc, exec, s[8:9]
	s_cbranch_vccz .LBB0_279
	v_readlane_b32 s82, v242, 16
	v_readlane_b32 s83, v242, 17
	s_and_b64 vcc, exec, s[82:83]
	s_cbranch_vccz .LBB0_276
	s_mov_b32 s50, 0x3e0293ee
	v_mul_f32_e32 v198, s50, v172
	v_mul_f32_e32 v199, s50, v173
	v_mul_f32_e32 v196, s50, v176
	v_mul_f32_e32 v197, s50, v177
	v_mul_f32_e32 v200, s50, v186
	v_mul_f32_e32 v201, s50, v187
	v_mul_f32_e32 v204, s50, v188
	v_mul_f32_e32 v205, s50, v189
	v_lshl_add_u64 v[124:125], v[146:147], 1, v[164:165]
	v_cvt_pk_bf16_f32 v196, v196, v197
	v_cvt_pk_bf16_f32 v197, v198, v199
	v_cvt_pk_bf16_f32 v198, v204, v205
	v_cvt_pk_bf16_f32 v199, v200, v201
	global_store_dwordx4 v[124:125], v[196:199], off
	s_mov_b64 s[50:51], 0

.LBB0_279:
	s_andn2_b64 vcc, exec, s[50:51]
	s_cbranch_vccnz .LBB0_281
	s_mov_b32 s50, 0x3e38aa3b
	v_mul_f32_e32 v198, s50, v172
	v_mul_f32_e32 v199, s50, v173
	v_mul_f32_e32 v196, s50, v176
	v_mul_f32_e32 v197, s50, v177
	v_mul_f32_e32 v200, s50, v186
	v_mul_f32_e32 v201, s50, v187
	v_mul_f32_e32 v204, s50, v188
	v_mul_f32_e32 v205, s50, v189
	v_lshl_add_u64 v[124:125], v[146:147], 1, v[160:161]
	v_cvt_pk_bf16_f32 v196, v196, v197
	v_cvt_pk_bf16_f32 v197, v198, v199
	v_cvt_pk_bf16_f32 v198, v204, v205
	v_cvt_pk_bf16_f32 v199, v200, v201
	global_store_dwordx4 v[124:125], v[196:199], off

.LBB0_282:
	s_andn2_b64 vcc, exec, s[50:51]
	v_mov_b32_e32 v195, 0
	s_cbranch_vccnz .LBB0_284
	v_readlane_b32 s50, v242, 13
	v_readlane_b32 s51, v242, 14
	v_cvt_pk_bf16_f32 v124, v188, v189
	v_cvt_pk_bf16_f32 v125, v186, v187
	v_lshl_add_u64 v[122:123], s[50:51], 0, v[122:123]
	v_lshl_add_u64 v[196:197], v[146:147], 1, v[122:123]
	v_cvt_pk_bf16_f32 v122, v176, v177
	v_cvt_pk_bf16_f32 v123, v172, v173
	global_store_dwordx4 v[196:197], v[122:125], off
	s_nop 1
	v_mul_f32_e32 v122, v172, v172
	v_mul_f32_e32 v123, v173, v173
	v_mul_f32_e32 v124, v176, v176
	v_mul_f32_e32 v125, v177, v177
	s_nop 0
	v_pk_mov_b32 v[196:197], v[124:125], v[122:123] op_sel:[1,0]
	v_mov_b32_e32 v125, v123
	v_add_f32_e32 v122, v196, v124
	v_add_f32_e32 v123, v197, v125
	v_mul_f32_e32 v124, v186, v186
	v_mul_f32_e32 v125, v187, v187
	v_mul_f32_e32 v196, v188, v188
	v_mul_f32_e32 v197, v189, v189
	v_mov_b32_e32 v198, v124
	v_mov_b32_e32 v199, v196
	v_mov_b32_e32 v196, v125
	v_add_f32_e32 v124, v198, v196
	v_add_f32_e32 v125, v199, v197
	v_add_f32_e32 v122, v122, v123
	v_add_f32_e32 v122, v125, v122
	v_add_f32_e32 v195, v124, v122

.LBB0_285:
	v_lshl_add_u64 v[196:197], v[146:147], 1, v[154:155]
	v_cvt_pk_bf16_f32 v122, v176, v177
	v_cvt_pk_bf16_f32 v123, v172, v173
	v_cvt_pk_bf16_f32 v124, v188, v189
	v_cvt_pk_bf16_f32 v125, v186, v187
	global_store_dwordx4 v[196:197], v[122:125], off
	s_nop 1
	v_mul_f32_e32 v122, v172, v172
	v_mul_f32_e32 v123, v173, v173
	v_mul_f32_e32 v124, v176, v176
	v_mul_f32_e32 v125, v177, v177
	s_nop 0
	v_pk_mov_b32 v[196:197], v[124:125], v[122:123] op_sel:[1,0]
	v_mov_b32_e32 v125, v123
	v_add_f32_e32 v122, v196, v124
	v_add_f32_e32 v123, v197, v125
	v_mul_f32_e32 v124, v186, v186
	v_mul_f32_e32 v125, v187, v187
	v_mul_f32_e32 v196, v188, v188
	v_mul_f32_e32 v197, v189, v189
	v_mov_b32_e32 v198, v124
	v_mov_b32_e32 v199, v196
	v_mov_b32_e32 v196, v125
	v_add_f32_e32 v124, v198, v196
	v_add_f32_e32 v125, v199, v197
	v_add_f32_e32 v122, v122, v123
	v_add_f32_e32 v122, v125, v122
	v_add_f32_e32 v195, v124, v122

.LBB0_293:
	v_mov_b32_e32 v179, v178
	v_mov_b32_e32 v176, v178
	v_mov_b32_e32 v177, v178
	v_add_u32_e32 v122, 0x80, v146
	v_mul_f32_e32 v124, v120, v176
	v_mul_f32_e32 v125, v121, v177
	v_mul_f32_e32 v172, v118, v178
	v_mul_f32_e32 v173, v119, v179
	v_mul_f32_e32 v176, v116, v176
	v_mul_f32_e32 v177, v117, v177
	v_mul_f32_e32 v178, v114, v178
	v_mul_f32_e32 v179, v115, v179
	s_cmp_lt_i32 s62, 4
	s_mov_b64 s[50:51], -1
	s_cbranch_scc1 .LBB0_312
	s_cmp_lt_i32 s62, 6
	s_cbranch_scc1 .LBB0_303
	s_cmp_gt_i32 s62, 6
	s_cbranch_scc0 .LBB0_297
	v_max_f32_e32 v115, v178, v178
	v_max_f32_e32 v119, v176, v176
	v_max_f32_e32 v114, v172, v172
	v_max_f32_e32 v116, 0, v115
	v_max_f32_e32 v115, v173, v173
	v_max_f32_e32 v117, v179, v179
	v_max_f32_e32 v118, v124, v124
	v_max_f32_e32 v120, 0, v119
	v_max_f32_e32 v119, v125, v125
	v_max_f32_e32 v121, v177, v177
	v_max_f32_e32 v114, 0, v114
	v_max_f32_e32 v115, 0, v115
	v_max_f32_e32 v117, 0, v117
	v_max_f32_e32 v118, 0, v118
	v_max_f32_e32 v119, 0, v119
	v_max_f32_e32 v121, 0, v121
	v_mul_f32_e32 v114, v114, v114
	v_mul_f32_e32 v115, v115, v115
	v_mul_f32_e32 v116, v116, v116
	v_mul_f32_e32 v117, v117, v117
	v_mul_f32_e32 v118, v118, v118
	v_mul_f32_e32 v119, v119, v119
	v_mul_f32_e32 v120, v120, v120
	v_mul_f32_e32 v121, v121, v121
	v_ashrrev_i32_e32 v147, 31, v146
	v_lshl_add_u64 v[182:183], v[146:147], 1, v[182:183]
	v_cvt_pk_bf16_f32 v114, v114, v115
	v_cvt_pk_bf16_f32 v115, v118, v119
	v_cvt_pk_bf16_f32 v116, v116, v117
	v_cvt_pk_bf16_f32 v117, v120, v121
	global_store_dwordx4 v[182:183], v[114:117], off offset:256
	s_mov_b64 s[50:51], 0

.LBB0_301:
	s_waitcnt vmcnt(0)
	v_add_f32_e32 v174, v124, v116
	v_add_f32_e32 v175, v125, v117
	v_add_f32_e32 v182, v172, v114
	v_add_f32_e32 v183, v173, v115
	v_add_f32_e32 v120, v176, v120
	v_add_f32_e32 v121, v177, v121
	v_add_f32_e32 v118, v178, v118
	v_add_f32_e32 v119, v179, v119
	v_cvt_pk_bf16_f32 v114, v182, v183
	v_cvt_pk_bf16_f32 v115, v174, v175
	v_cvt_pk_bf16_f32 v116, v118, v119
	v_cvt_pk_bf16_f32 v117, v120, v121
	global_store_dwordx4 v[170:171], v[114:117], off
	v_mul_f32_e32 v118, v118, v118
	v_mul_f32_e32 v119, v119, v119
	s_nop 0
	v_mul_f32_e32 v114, v174, v174
	v_mul_f32_e32 v115, v175, v175
	v_mul_f32_e32 v116, v182, v182
	v_mul_f32_e32 v117, v183, v183
	s_nop 0
	v_pk_mov_b32 v[170:171], v[116:117], v[114:115] op_sel:[1,0]
	v_mov_b32_e32 v117, v115
	v_add_f32_e32 v114, v170, v116
	v_add_f32_e32 v115, v171, v117
	v_mul_f32_e32 v116, v120, v120
	v_mul_f32_e32 v117, v121, v121
	v_mov_b32_e32 v121, v118
	v_mov_b32_e32 v120, v116
	v_mov_b32_e32 v118, v117
	v_add_f32_e32 v116, v120, v118
	v_add_f32_e32 v117, v121, v119
	v_add_f32_e32 v114, v114, v115
	v_add_f32_e32 v114, v114, v117
	v_add_f32_e32 v114, v116, v114
	v_add_f32_e32 v114, v195, v114

.LBB0_307:
	s_waitcnt vmcnt(0)
	v_cvt_f32_ubyte3_e32 v175, v118
	v_cvt_f32_ubyte2_e32 v174, v118
	v_cvt_f32_ubyte1_e32 v183, v118
	v_cvt_f32_ubyte0_e32 v182, v118
	v_mul_f32_e32 v182, s26, v182
	v_mul_f32_e32 v183, s26, v183
	v_mul_f32_e32 v174, s26, v174
	v_mul_f32_e32 v175, s26, v175
	v_fma_f32 v168, v172, v182, v168
	v_fma_f32 v169, v173, v183, v169
	v_fma_f32 v170, v124, v174, v170
	v_fma_f32 v171, v125, v175, v171
	v_cvt_f32_ubyte3_e32 v175, v119
	v_cvt_f32_ubyte2_e32 v174, v119
	v_cvt_f32_ubyte1_e32 v183, v119
	v_cvt_f32_ubyte0_e32 v182, v119
	v_mul_f32_e32 v118, s26, v182
	v_mul_f32_e32 v119, s26, v183
	v_mul_f32_e32 v174, s26, v174
	v_mul_f32_e32 v175, s26, v175
	v_fma_f32 v118, v178, v118, v116
	v_fma_f32 v119, v179, v119, v117
	v_fma_f32 v120, v176, v174, v120
	v_fma_f32 v121, v177, v175, v121
	v_cvt_pk_bf16_f32 v116, v168, v169
	v_cvt_pk_bf16_f32 v117, v170, v171
	v_cvt_pk_bf16_f32 v118, v118, v119
	v_cvt_pk_bf16_f32 v119, v120, v121
	s_mov_b64 s[50:51], 0
	global_store_dwordx4 v[114:115], v[116:119], off

.LBB0_320:
	s_andn2_b64 vcc, exec, s[50:51]
	s_cbranch_vccnz .LBB0_325
	s_andn2_b64 vcc, exec, s[6:7]
	s_mov_b64 s[50:51], -1
	s_cbranch_vccnz .LBB0_323
	global_load_dwordx4 v[114:117], v[156:157], off offset:16
	global_load_dwordx4 v[118:121], v[156:157], off
	v_readlane_b32 s11, v243, 49
	s_lshl_b32 s84, s11, 1
	s_mov_b64 s[50:51], 0x6800380
	s_waitcnt vmcnt(0)
	v_mov_b32_e32 v163, v120
	v_mov_b32_e32 v120, v119
	v_mov_b32_e32 v162, v118
	v_mul_f32_e32 v118, v178, v120
	v_mul_f32_e32 v119, v179, v121
	v_mul_f32_e32 v120, v172, v120
	v_mul_f32_e32 v121, v173, v121
	v_fma_f32 v118, v172, v162, -v118
	v_fma_f32 v119, v173, v163, -v119
	v_fma_f32 v120, v178, v162, v120
	v_fma_f32 v121, v179, v163, v121
	v_mov_b32_e32 v163, v116
	v_mov_b32_e32 v116, v115
	v_mov_b32_e32 v162, v114
	v_mul_f32_e32 v114, v176, v116
	v_mul_f32_e32 v115, v177, v117
	v_mul_f32_e32 v116, v124, v116
	v_mul_f32_e32 v117, v125, v117
	v_fma_f32 v114, v124, v162, -v114
	v_fma_f32 v115, v125, v163, -v115
	v_fma_f32 v116, v176, v162, v116
	v_fma_f32 v117, v177, v163, v117
	v_cvt_pk_bf16_f32 v118, v118, v119
	v_cvt_pk_bf16_f32 v119, v114, v115
	v_cvt_pk_bf16_f32 v115, v116, v117
	v_lshl_add_u64 v[116:117], v[158:159], 0, s[84:85]
	v_lshl_add_u64 v[116:117], v[126:127], 1, v[116:117]
	v_cvt_pk_bf16_f32 v114, v120, v121
	v_lshl_add_u64 v[120:121], v[116:117], 0, s[50:51]
	v_add_co_u32_e32 v116, vcc, 0x6800000, v116
	s_mov_b64 s[50:51], 0
	s_nop 0
	v_addc_co_u32_e32 v117, vcc, 0, v117, vcc
	global_store_dwordx2 v[116:117], v[118:119], off offset:896
	global_store_dwordx2 v[120:121], v[114:115], off offset:32

.LBB0_326:
	s_andn2_b64 vcc, exec, s[50:51]
	s_cbranch_vccnz .LBB0_353
	s_cmp_lg_u32 s62, 1
	s_mov_b64 s[50:51], -1
	s_cbranch_scc0 .LBB0_346
	s_andn2_b64 vcc, exec, s[14:15]
	s_cbranch_vccnz .LBB0_343
	s_andn2_b64 vcc, exec, s[16:17]
	s_cbranch_vccnz .LBB0_339
	s_andn2_b64 vcc, exec, s[8:9]
	s_cbranch_vccnz .LBB0_336
	v_readlane_b32 s50, v242, 16
	v_readlane_b32 s51, v242, 17
	s_andn2_b64 vcc, exec, s[50:51]
	s_mov_b64 s[50:51], -1
	s_cbranch_vccnz .LBB0_333
	s_mov_b32 s50, 0x3e0293ee
	v_ashrrev_i32_e32 v147, 31, v146
	v_mul_f32_e32 v116, s50, v124
	v_mul_f32_e32 v117, s50, v125
	v_mul_f32_e32 v114, s50, v172
	v_mul_f32_e32 v115, s50, v173
	v_mul_f32_e32 v120, s50, v176
	v_mul_f32_e32 v121, s50, v177
	v_mul_f32_e32 v162, s50, v178
	v_mul_f32_e32 v163, s50, v179
	v_lshl_add_u64 v[118:119], v[146:147], 1, v[164:165]
	v_cvt_pk_bf16_f32 v114, v114, v115
	v_cvt_pk_bf16_f32 v115, v116, v117
	v_cvt_pk_bf16_f32 v116, v162, v163
	v_cvt_pk_bf16_f32 v117, v120, v121
	s_mov_b64 s[50:51], 0
	global_store_dwordx4 v[118:119], v[114:117], off offset:256

.LBB0_336:
	s_andn2_b64 vcc, exec, s[50:51]
	s_cbranch_vccnz .LBB0_338
	v_ashrrev_i32_e32 v147, 31, v146
	s_mov_b32 s50, 0x3e38aa3b
	v_lshl_add_u64 v[118:119], v[146:147], 1, v[160:161]
	v_mul_f32_e32 v116, s50, v124
	v_mul_f32_e32 v117, s50, v125
	v_mul_f32_e32 v114, s50, v172
	v_mul_f32_e32 v115, s50, v173
	v_mul_f32_e32 v120, s50, v176
	v_mul_f32_e32 v121, s50, v177
	v_mul_f32_e32 v160, s50, v178
	v_mul_f32_e32 v161, s50, v179
	v_cvt_pk_bf16_f32 v114, v114, v115
	v_cvt_pk_bf16_f32 v115, v116, v117
	v_cvt_pk_bf16_f32 v116, v160, v161
	v_cvt_pk_bf16_f32 v117, v120, v121
	global_store_dwordx4 v[118:119], v[114:117], off offset:256

.LBB0_339:
	s_andn2_b64 vcc, exec, s[50:51]
	s_cbranch_vccnz .LBB0_342
	v_readlane_b32 s50, v243, 47
	v_readlane_b32 s51, v243, 48
	s_andn2_b64 vcc, exec, s[50:51]
	s_cbranch_vccnz .LBB0_342
	global_load_dwordx4 v[114:117], v[156:157], off offset:16
	global_load_dwordx4 v[118:121], v[156:157], off
	v_lshl_add_u64 v[158:159], v[126:127], 1, v[158:159]
	s_brev_b32 s11, 16
	s_mov_b64 s[50:51], 0x8000080
	v_lshl_add_u64 v[160:161], v[158:159], 0, s[50:51]
	s_waitcnt vmcnt(0)
	v_mov_b32_e32 v157, v120
	v_mov_b32_e32 v120, v119
	v_mov_b32_e32 v156, v118
	v_mul_f32_e32 v118, v178, v120
	v_mul_f32_e32 v119, v179, v121
	v_mul_f32_e32 v120, v172, v120
	v_mul_f32_e32 v121, v173, v121
	v_fma_f32 v118, v172, v156, -v118
	v_fma_f32 v119, v173, v157, -v119
	v_fma_f32 v120, v178, v156, v120
	v_fma_f32 v121, v179, v157, v121
	v_mov_b32_e32 v157, v116
	v_mov_b32_e32 v116, v115
	v_mov_b32_e32 v156, v114
	v_mul_f32_e32 v114, v176, v116
	v_mul_f32_e32 v115, v177, v117
	v_mul_f32_e32 v116, v124, v116
	v_mul_f32_e32 v117, v125, v117
	v_fma_f32 v114, v124, v156, -v114
	v_fma_f32 v115, v125, v157, -v115
	v_fma_f32 v116, v176, v156, v116
	v_fma_f32 v117, v177, v157, v117
	v_cvt_pk_bf16_f32 v118, v118, v119
	v_cvt_pk_bf16_f32 v119, v114, v115
	v_cvt_pk_bf16_f32 v115, v116, v117
	v_add_co_u32_e32 v116, vcc, s11, v158
	v_cvt_pk_bf16_f32 v114, v120, v121
	s_nop 0
	v_addc_co_u32_e32 v117, vcc, 0, v159, vcc
	global_store_dwordx2 v[116:117], v[118:119], off offset:128
	global_store_dwordx2 v[160:161], v[114:115], off offset:32
	global_store_dwordx2 v[160:161], v[118:119], off offset:192
	global_store_dwordx2 v[160:161], v[114:115], off offset:224
	global_store_dwordx2 v[160:161], v[118:119], off offset:384
	global_store_dwordx2 v[160:161], v[114:115], off offset:416
	global_store_dwordx2 v[160:161], v[118:119], off offset:576
	global_store_dwordx2 v[160:161], v[114:115], off offset:608
	global_store_dwordx2 v[160:161], v[118:119], off offset:768
	global_store_dwordx2 v[160:161], v[114:115], off offset:800
	global_store_dwordx2 v[160:161], v[118:119], off offset:960
	global_store_dwordx2 v[160:161], v[114:115], off offset:992
	global_store_dwordx2 v[160:161], v[118:119], off offset:1152
	global_store_dwordx2 v[160:161], v[114:115], off offset:1184
	global_store_dwordx2 v[160:161], v[118:119], off offset:1344
	global_store_dwordx2 v[160:161], v[114:115], off offset:1376

.LBB0_343:
	s_andn2_b64 vcc, exec, s[50:51]
	v_mov_b32_e32 v114, v195
	s_cbranch_vccnz .LBB0_345
	v_ashrrev_i32_e32 v147, 31, v146
	v_lshl_add_u64 v[118:119], v[146:147], 1, v[154:155]
	v_cvt_pk_bf16_f32 v114, v172, v173
	v_cvt_pk_bf16_f32 v115, v124, v125
	v_cvt_pk_bf16_f32 v116, v178, v179
	v_cvt_pk_bf16_f32 v117, v176, v177
	global_store_dwordx4 v[118:119], v[114:117], off offset:256
	s_nop 1
	v_mul_f32_e32 v114, v124, v124
	v_mul_f32_e32 v115, v125, v125
	v_mul_f32_e32 v116, v172, v172
	v_mul_f32_e32 v117, v173, v173
	s_nop 0
	v_pk_mov_b32 v[118:119], v[116:117], v[114:115] op_sel:[1,0]
	v_mov_b32_e32 v117, v115
	v_add_f32_e32 v114, v118, v116
	v_add_f32_e32 v115, v119, v117
	v_mul_f32_e32 v116, v176, v176
	v_mul_f32_e32 v117, v177, v177
	v_mul_f32_e32 v118, v178, v178
	v_mul_f32_e32 v119, v179, v179
	v_mov_b32_e32 v120, v116
	v_mov_b32_e32 v121, v118
	v_mov_b32_e32 v118, v117
	v_add_f32_e32 v116, v120, v118
	v_add_f32_e32 v117, v121, v119
	v_add_f32_e32 v114, v114, v115
	v_add_f32_e32 v114, v117, v114
	v_add_f32_e32 v114, v116, v114
	v_add_f32_e32 v114, v114, v195

.LBB0_366:
	v_mul_f32_e32 v119, 0x3e16c740, v118
	v_lshlrev_b64 v[120:121], 11, v[116:117]
	v_cndmask_b32_e64 v164, v118, v119, s[52:53]
	v_lshlrev_b64 v[118:119], 10, v[116:117]
	v_lshl_add_u64 v[160:161], s[88:89], 0, v[120:121]
	v_lshlrev_b64 v[124:125], 12, v[116:117]
	v_lshl_add_u64 v[158:159], s[34:35], 0, v[120:121]
	v_lshlrev_b64 v[120:121], 13, v[116:117]
	v_lshl_add_u64 v[168:169], v[148:149], 0, v[124:125]
	v_lshl_add_u64 v[152:153], s[2:3], 0, v[118:119]
	v_lshl_add_u64 v[170:171], s[28:29], 0, v[120:121]
	v_mul_f32_e32 v162, v112, v164
	v_mul_f32_e32 v163, v113, v164
	v_mul_f32_e32 v174, v110, v164
	v_mul_f32_e32 v175, v111, v164
	v_mul_f32_e32 v176, v108, v164
	v_mul_f32_e32 v177, v109, v164
	v_mul_f32_e32 v178, v106, v164
	v_mul_f32_e32 v179, v107, v164
	s_cmp_lt_i32 s62, 4
	s_mov_b64 s[50:51], -1
	s_cbranch_scc1 .LBB0_385
	s_cmp_lt_i32 s62, 6
	s_cbranch_scc1 .LBB0_376
	s_cmp_gt_i32 s62, 6
	s_cbranch_scc0 .LBB0_370
	v_max_f32_e32 v107, v178, v178
	v_max_f32_e32 v111, v176, v176
	v_max_f32_e32 v106, v174, v174
	v_max_f32_e32 v108, 0, v107
	v_max_f32_e32 v107, v175, v175
	v_max_f32_e32 v109, v179, v179
	v_max_f32_e32 v110, v162, v162
	v_max_f32_e32 v112, 0, v111
	v_max_f32_e32 v111, v163, v163
	v_max_f32_e32 v113, v177, v177
	v_max_f32_e32 v106, 0, v106
	v_max_f32_e32 v107, 0, v107
	v_max_f32_e32 v109, 0, v109
	v_max_f32_e32 v110, 0, v110
	v_max_f32_e32 v111, 0, v111
	v_max_f32_e32 v113, 0, v113
	v_mul_f32_e32 v106, v106, v106
	v_mul_f32_e32 v107, v107, v107
	v_mul_f32_e32 v108, v108, v108
	v_mul_f32_e32 v109, v109, v109
	v_mul_f32_e32 v110, v110, v110
	v_mul_f32_e32 v111, v111, v111
	v_mul_f32_e32 v112, v112, v112
	v_mul_f32_e32 v113, v113, v113
	v_ashrrev_i32_e32 v147, 31, v146
	v_lshl_add_u64 v[120:121], v[146:147], 1, v[170:171]
	v_cvt_pk_bf16_f32 v106, v106, v107
	v_cvt_pk_bf16_f32 v107, v110, v111
	v_cvt_pk_bf16_f32 v108, v108, v109
	v_cvt_pk_bf16_f32 v109, v112, v113
	global_store_dwordx4 v[120:121], v[106:109], off
	s_mov_b64 s[50:51], 0

.LBB0_374:
	s_waitcnt vmcnt(0)
	v_add_f32_e32 v124, v162, v108
	v_add_f32_e32 v125, v163, v109
	v_add_f32_e32 v150, v174, v106
	v_add_f32_e32 v151, v175, v107
	v_add_f32_e32 v112, v176, v112
	v_add_f32_e32 v113, v177, v113
	v_add_f32_e32 v110, v178, v110
	v_add_f32_e32 v111, v179, v111
	v_cvt_pk_bf16_f32 v106, v150, v151
	v_cvt_pk_bf16_f32 v107, v124, v125
	v_cvt_pk_bf16_f32 v108, v110, v111
	v_cvt_pk_bf16_f32 v109, v112, v113
	global_store_dwordx4 v[120:121], v[106:109], off
	v_mul_f32_e32 v110, v110, v110
	v_mul_f32_e32 v111, v111, v111
	s_nop 0
	v_mul_f32_e32 v106, v124, v124
	v_mul_f32_e32 v107, v125, v125
	v_mul_f32_e32 v108, v150, v150
	v_mul_f32_e32 v109, v151, v151
	s_nop 0
	v_pk_mov_b32 v[120:121], v[108:109], v[106:107] op_sel:[1,0]
	v_mov_b32_e32 v109, v107
	v_add_f32_e32 v106, v120, v108
	v_add_f32_e32 v107, v121, v109
	v_mul_f32_e32 v108, v112, v112
	v_mul_f32_e32 v109, v113, v113
	v_mov_b32_e32 v113, v110
	v_mov_b32_e32 v112, v108
	v_mov_b32_e32 v110, v109
	v_add_f32_e32 v108, v112, v110
	v_add_f32_e32 v109, v113, v111
	v_add_f32_e32 v106, v106, v107
	v_add_f32_e32 v106, v106, v109
	v_add_f32_e32 v180, v108, v106

.LBB0_380:
	s_waitcnt vmcnt(0)
	v_cvt_f32_ubyte3_e32 v151, v110
	v_cvt_f32_ubyte2_e32 v150, v110
	v_cvt_f32_ubyte1_e32 v155, v110
	v_cvt_f32_ubyte0_e32 v154, v110
	v_mul_f32_e32 v154, s26, v154
	v_mul_f32_e32 v155, s26, v155
	v_mul_f32_e32 v150, s26, v150
	v_mul_f32_e32 v151, s26, v151
	v_fma_f32 v120, v174, v154, v120
	v_fma_f32 v121, v175, v155, v121
	v_fma_f32 v124, v162, v150, v124
	v_fma_f32 v125, v163, v151, v125
	v_cvt_f32_ubyte3_e32 v151, v111
	v_cvt_f32_ubyte2_e32 v150, v111
	v_cvt_f32_ubyte1_e32 v155, v111
	v_cvt_f32_ubyte0_e32 v154, v111
	v_mul_f32_e32 v110, s26, v154
	v_mul_f32_e32 v111, s26, v155
	v_mul_f32_e32 v150, s26, v150
	v_mul_f32_e32 v151, s26, v151
	v_fma_f32 v110, v178, v110, v108
	v_fma_f32 v111, v179, v111, v109
	v_fma_f32 v112, v176, v150, v112
	v_fma_f32 v113, v177, v151, v113
	v_cvt_pk_bf16_f32 v108, v120, v121
	v_cvt_pk_bf16_f32 v109, v124, v125
	v_cvt_pk_bf16_f32 v110, v110, v111
	v_cvt_pk_bf16_f32 v111, v112, v113
	s_mov_b64 s[50:51], 0
	global_store_dwordx4 v[106:107], v[108:111], off

.LBB0_393:
	s_andn2_b64 vcc, exec, s[50:51]
	s_cbranch_vccnz .LBB0_398
	s_andn2_b64 vcc, exec, s[6:7]
	s_mov_b64 s[50:51], -1
	s_cbranch_vccnz .LBB0_396
	global_load_dwordx4 v[106:109], v[120:121], off offset:16
	global_load_dwordx4 v[180:183], v[120:121], off
	v_readlane_b32 s11, v243, 49
	s_lshl_b32 s84, s11, 1
	s_mov_b64 s[50:51], 0x6800080
	s_waitcnt vmcnt(0)
	v_mov_b32_e32 v185, v182
	v_mov_b32_e32 v182, v181
	v_mov_b32_e32 v184, v180
	v_mul_f32_e32 v180, v178, v182
	v_mul_f32_e32 v181, v179, v183
	v_mul_f32_e32 v182, v174, v182
	v_mul_f32_e32 v183, v175, v183
	v_fma_f32 v180, v174, v184, -v180
	v_fma_f32 v181, v175, v185, -v181
	v_fma_f32 v182, v178, v184, v182
	v_fma_f32 v183, v179, v185, v183
	v_mov_b32_e32 v185, v108
	v_mov_b32_e32 v108, v107
	v_mov_b32_e32 v184, v106
	v_mul_f32_e32 v106, v176, v108
	v_mul_f32_e32 v107, v177, v109
	v_mul_f32_e32 v108, v162, v108
	v_mul_f32_e32 v109, v163, v109
	v_fma_f32 v106, v162, v184, -v106
	v_fma_f32 v107, v163, v185, -v107
	v_fma_f32 v108, v176, v184, v108
	v_fma_f32 v109, v177, v185, v109
	v_cvt_pk_bf16_f32 v180, v180, v181
	v_cvt_pk_bf16_f32 v181, v106, v107
	v_cvt_pk_bf16_f32 v107, v108, v109
	v_lshl_add_u64 v[108:109], v[124:125], 0, s[84:85]
	v_lshl_add_u64 v[108:109], v[126:127], 1, v[108:109]
	v_cvt_pk_bf16_f32 v106, v182, v183
	v_lshl_add_u64 v[182:183], v[108:109], 0, s[50:51]
	v_add_co_u32_e32 v108, vcc, 0x6800000, v108
	s_mov_b64 s[50:51], 0
	s_nop 0
	v_addc_co_u32_e32 v109, vcc, 0, v109, vcc
	global_store_dwordx2 v[108:109], v[180:181], off offset:128
	global_store_dwordx2 v[182:183], v[106:107], off offset:32

.LBB0_399:
	s_andn2_b64 vcc, exec, s[50:51]
	v_mov_b32_e32 v180, 0
	s_cbranch_vccnz .LBB0_423
	s_cmp_lg_u32 s62, 1
	s_mov_b64 s[50:51], -1
	s_cbranch_scc0 .LBB0_417
	s_andn2_b64 vcc, exec, s[14:15]
	v_ashrrev_i32_e32 v147, 31, v146
	s_cbranch_vccnz .LBB0_1274
	v_lshlrev_b64 v[106:107], 8, v[116:117]
	s_andn2_b64 vcc, exec, s[16:17]
	s_cbranch_vccnz .LBB0_412
	s_andn2_b64 vcc, exec, s[8:9]
	s_cbranch_vccnz .LBB0_409
	v_readlane_b32 s50, v242, 16
	v_readlane_b32 s51, v242, 17
	s_andn2_b64 vcc, exec, s[50:51]
	s_mov_b64 s[50:51], -1
	s_cbranch_vccnz .LBB0_406
	s_mov_b32 s50, 0x3e0293ee
	v_mul_f32_e32 v182, s50, v162
	v_mul_f32_e32 v183, s50, v163
	v_mul_f32_e32 v180, s50, v174
	v_mul_f32_e32 v181, s50, v175
	v_mul_f32_e32 v184, s50, v176
	v_mul_f32_e32 v185, s50, v177
	v_mul_f32_e32 v186, s50, v178
	v_mul_f32_e32 v187, s50, v179
	v_lshl_add_u64 v[108:109], v[146:147], 1, v[154:155]
	v_cvt_pk_bf16_f32 v180, v180, v181
	v_cvt_pk_bf16_f32 v181, v182, v183
	v_cvt_pk_bf16_f32 v182, v186, v187
	v_cvt_pk_bf16_f32 v183, v184, v185
	s_mov_b64 s[50:51], 0
	global_store_dwordx4 v[108:109], v[180:183], off

.LBB0_409:
	s_andn2_b64 vcc, exec, s[50:51]
	s_cbranch_vccnz .LBB0_411
	s_mov_b32 s50, 0x3e38aa3b
	v_mul_f32_e32 v182, s50, v162
	v_mul_f32_e32 v183, s50, v163
	v_mul_f32_e32 v180, s50, v174
	v_mul_f32_e32 v181, s50, v175
	v_mul_f32_e32 v184, s50, v176
	v_mul_f32_e32 v185, s50, v177
	v_mul_f32_e32 v186, s50, v178
	v_mul_f32_e32 v187, s50, v179
	v_lshl_add_u64 v[108:109], v[146:147], 1, v[150:151]
	v_cvt_pk_bf16_f32 v180, v180, v181
	v_cvt_pk_bf16_f32 v181, v182, v183
	v_cvt_pk_bf16_f32 v182, v186, v187
	v_cvt_pk_bf16_f32 v183, v184, v185
	global_store_dwordx4 v[108:109], v[180:183], off

.LBB0_412:
	s_andn2_b64 vcc, exec, s[50:51]
	v_mov_b32_e32 v180, 0
	s_cbranch_vccnz .LBB0_414
	v_readlane_b32 s50, v242, 13
	v_readlane_b32 s51, v242, 14
	v_cvt_pk_bf16_f32 v108, v178, v179
	v_cvt_pk_bf16_f32 v109, v176, v177
	v_lshl_add_u64 v[106:107], s[50:51], 0, v[106:107]
	v_lshl_add_u64 v[180:181], v[146:147], 1, v[106:107]
	v_cvt_pk_bf16_f32 v106, v174, v175
	v_cvt_pk_bf16_f32 v107, v162, v163
	global_store_dwordx4 v[180:181], v[106:109], off
	s_nop 1
	v_mul_f32_e32 v106, v162, v162
	v_mul_f32_e32 v107, v163, v163
	v_mul_f32_e32 v108, v174, v174
	v_mul_f32_e32 v109, v175, v175
	s_nop 0
	v_pk_mov_b32 v[180:181], v[108:109], v[106:107] op_sel:[1,0]
	v_mov_b32_e32 v109, v107
	v_add_f32_e32 v106, v180, v108
	v_add_f32_e32 v107, v181, v109
	v_mul_f32_e32 v108, v176, v176
	v_mul_f32_e32 v109, v177, v177
	v_mul_f32_e32 v180, v178, v178
	v_mul_f32_e32 v181, v179, v179
	v_mov_b32_e32 v182, v108
	v_mov_b32_e32 v183, v180
	v_mov_b32_e32 v180, v109
	v_add_f32_e32 v108, v182, v180
	v_add_f32_e32 v109, v183, v181
	v_add_f32_e32 v106, v106, v107
	v_add_f32_e32 v106, v109, v106
	v_add_f32_e32 v180, v108, v106

.LBB0_415:
	v_lshl_add_u64 v[180:181], v[146:147], 1, v[118:119]
	v_cvt_pk_bf16_f32 v106, v174, v175
	v_cvt_pk_bf16_f32 v107, v162, v163
	v_cvt_pk_bf16_f32 v108, v178, v179
	v_cvt_pk_bf16_f32 v109, v176, v177
	global_store_dwordx4 v[180:181], v[106:109], off
	s_nop 1
	v_mul_f32_e32 v106, v162, v162
	v_mul_f32_e32 v107, v163, v163
	v_mul_f32_e32 v108, v174, v174
	v_mul_f32_e32 v109, v175, v175
	s_nop 0
	v_pk_mov_b32 v[180:181], v[108:109], v[106:107] op_sel:[1,0]
	v_mov_b32_e32 v109, v107
	v_add_f32_e32 v106, v180, v108
	v_add_f32_e32 v107, v181, v109
	v_mul_f32_e32 v108, v176, v176
	v_mul_f32_e32 v109, v177, v177
	v_mul_f32_e32 v180, v178, v178
	v_mul_f32_e32 v181, v179, v179
	v_mov_b32_e32 v182, v108
	v_mov_b32_e32 v183, v180
	v_mov_b32_e32 v180, v109
	v_add_f32_e32 v108, v182, v180
	v_add_f32_e32 v109, v183, v181
	v_add_f32_e32 v106, v106, v107
	v_add_f32_e32 v106, v109, v106
	v_add_f32_e32 v180, v108, v106

.LBB0_423:
	v_mov_b32_e32 v165, v164
	v_mov_b32_e32 v162, v164
	v_mov_b32_e32 v163, v164
	v_mul_f32_e32 v106, v104, v162
	v_mul_f32_e32 v107, v105, v163
	v_mul_f32_e32 v108, v102, v164
	v_mul_f32_e32 v109, v103, v165
	v_mul_f32_e32 v162, v100, v162
	v_mul_f32_e32 v163, v101, v163
	v_mul_f32_e32 v164, v98, v164
	v_mul_f32_e32 v165, v99, v165
	s_cmp_lt_i32 s62, 4
	s_mov_b64 s[50:51], -1
	s_cbranch_scc0 .LBB0_426
	s_andn2_b64 vcc, exec, s[50:51]
	s_cbranch_vccz .LBB0_444

.LBB0_426:
	s_cmp_lt_i32 s62, 6
	s_cbranch_scc1 .LBB0_435
	s_cmp_gt_i32 s62, 6
	s_cbranch_scc0 .LBB0_429
	v_max_f32_e32 v99, v164, v164
	v_max_f32_e32 v103, v162, v162
	v_max_f32_e32 v98, v108, v108
	v_max_f32_e32 v100, 0, v99
	v_max_f32_e32 v99, v109, v109
	v_max_f32_e32 v101, v165, v165
	v_max_f32_e32 v102, v106, v106
	v_max_f32_e32 v104, 0, v103
	v_max_f32_e32 v103, v107, v107
	v_max_f32_e32 v105, v163, v163
	v_max_f32_e32 v98, 0, v98
	v_max_f32_e32 v99, 0, v99
	v_max_f32_e32 v101, 0, v101
	v_max_f32_e32 v102, 0, v102
	v_max_f32_e32 v103, 0, v103
	v_max_f32_e32 v105, 0, v105
	v_mul_f32_e32 v98, v98, v98
	v_mul_f32_e32 v99, v99, v99
	v_mul_f32_e32 v100, v100, v100
	v_mul_f32_e32 v101, v101, v101
	v_mul_f32_e32 v102, v102, v102
	v_mul_f32_e32 v103, v103, v103
	v_mul_f32_e32 v104, v104, v104
	v_mul_f32_e32 v105, v105, v105
	v_ashrrev_i32_e32 v147, 31, v146
	v_lshl_add_u64 v[170:171], v[146:147], 1, v[170:171]
	v_cvt_pk_bf16_f32 v98, v98, v99
	v_cvt_pk_bf16_f32 v99, v102, v103
	v_cvt_pk_bf16_f32 v100, v100, v101
	v_cvt_pk_bf16_f32 v101, v104, v105
	global_store_dwordx4 v[170:171], v[98:101], off offset:256
	s_mov_b64 s[50:51], 0

.LBB0_433:
	s_waitcnt vmcnt(0)
	v_add_f32_e32 v168, v106, v100
	v_add_f32_e32 v169, v107, v101
	v_add_f32_e32 v170, v108, v98
	v_add_f32_e32 v171, v109, v99
	v_add_f32_e32 v104, v162, v104
	v_add_f32_e32 v105, v163, v105
	v_add_f32_e32 v102, v164, v102
	v_add_f32_e32 v103, v165, v103
	v_cvt_pk_bf16_f32 v98, v170, v171
	v_cvt_pk_bf16_f32 v99, v168, v169
	v_cvt_pk_bf16_f32 v100, v102, v103
	v_cvt_pk_bf16_f32 v101, v104, v105
	global_store_dwordx4 v[160:161], v[98:101], off
	v_mul_f32_e32 v102, v102, v102
	v_mul_f32_e32 v103, v103, v103
	s_nop 0
	v_mul_f32_e32 v98, v168, v168
	v_mul_f32_e32 v99, v169, v169
	v_mul_f32_e32 v100, v170, v170
	v_mul_f32_e32 v101, v171, v171
	s_nop 0
	v_pk_mov_b32 v[160:161], v[100:101], v[98:99] op_sel:[1,0]
	v_mov_b32_e32 v101, v99
	v_add_f32_e32 v98, v160, v100
	v_add_f32_e32 v99, v161, v101
	v_mul_f32_e32 v100, v104, v104
	v_mul_f32_e32 v101, v105, v105
	v_mov_b32_e32 v105, v102
	v_mov_b32_e32 v104, v100
	v_mov_b32_e32 v102, v101
	v_add_f32_e32 v100, v104, v102
	v_add_f32_e32 v101, v105, v103
	v_add_f32_e32 v98, v98, v99
	v_add_f32_e32 v98, v98, v101
	v_add_f32_e32 v98, v100, v98
	v_add_f32_e32 v98, v180, v98

.LBB0_439:
	s_waitcnt vmcnt(0)
	v_cvt_f32_ubyte3_e32 v169, v102
	v_cvt_f32_ubyte2_e32 v168, v102
	v_cvt_f32_ubyte1_e32 v171, v102
	v_cvt_f32_ubyte0_e32 v170, v102
	v_mul_f32_e32 v170, s26, v170
	v_mul_f32_e32 v171, s26, v171
	v_mul_f32_e32 v168, s26, v168
	v_mul_f32_e32 v169, s26, v169
	v_fma_f32 v158, v108, v170, v158
	v_fma_f32 v159, v109, v171, v159
	v_fma_f32 v160, v106, v168, v160
	v_fma_f32 v161, v107, v169, v161
	v_cvt_f32_ubyte3_e32 v169, v103
	v_cvt_f32_ubyte2_e32 v168, v103
	v_cvt_f32_ubyte1_e32 v171, v103
	v_cvt_f32_ubyte0_e32 v170, v103
	v_mul_f32_e32 v102, s26, v170
	v_mul_f32_e32 v103, s26, v171
	v_mul_f32_e32 v168, s26, v168
	v_mul_f32_e32 v169, s26, v169
	v_fma_f32 v102, v164, v102, v100
	v_fma_f32 v103, v165, v103, v101
	v_fma_f32 v104, v162, v168, v104
	v_fma_f32 v105, v163, v169, v105
	v_cvt_pk_bf16_f32 v100, v158, v159
	v_cvt_pk_bf16_f32 v101, v160, v161
	v_cvt_pk_bf16_f32 v102, v102, v103
	v_cvt_pk_bf16_f32 v103, v104, v105
	s_mov_b64 s[50:51], 0
	global_store_dwordx4 v[98:99], v[100:103], off

.LBB0_451:
	s_andn2_b64 vcc, exec, s[50:51]
	s_cbranch_vccnz .LBB0_456
	s_andn2_b64 vcc, exec, s[6:7]
	s_mov_b64 s[50:51], -1
	s_cbranch_vccnz .LBB0_454
	global_load_dwordx4 v[98:101], v[120:121], off offset:16
	global_load_dwordx4 v[102:105], v[120:121], off
	v_readlane_b32 s11, v243, 49
	s_lshl_b32 s84, s11, 1
	s_mov_b64 s[50:51], 0x6800380
	s_waitcnt vmcnt(0)
	v_mov_b32_e32 v153, v104
	v_mov_b32_e32 v104, v103
	v_mov_b32_e32 v152, v102
	v_mul_f32_e32 v102, v164, v104
	v_mul_f32_e32 v103, v165, v105
	v_mul_f32_e32 v104, v108, v104
	v_mul_f32_e32 v105, v109, v105
	v_fma_f32 v102, v108, v152, -v102
	v_fma_f32 v103, v109, v153, -v103
	v_fma_f32 v104, v164, v152, v104
	v_fma_f32 v105, v165, v153, v105
	v_mov_b32_e32 v153, v100
	v_mov_b32_e32 v100, v99
	v_mov_b32_e32 v152, v98
	v_mul_f32_e32 v98, v162, v100
	v_mul_f32_e32 v99, v163, v101
	v_mul_f32_e32 v100, v106, v100
	v_mul_f32_e32 v101, v107, v101
	v_fma_f32 v98, v106, v152, -v98
	v_fma_f32 v99, v107, v153, -v99
	v_fma_f32 v100, v162, v152, v100
	v_fma_f32 v101, v163, v153, v101
	v_cvt_pk_bf16_f32 v102, v102, v103
	v_cvt_pk_bf16_f32 v103, v98, v99
	v_cvt_pk_bf16_f32 v99, v100, v101
	v_lshl_add_u64 v[100:101], v[124:125], 0, s[84:85]
	v_lshl_add_u64 v[100:101], v[126:127], 1, v[100:101]
	v_cvt_pk_bf16_f32 v98, v104, v105
	v_lshl_add_u64 v[104:105], v[100:101], 0, s[50:51]
	v_add_co_u32_e32 v100, vcc, 0x6800000, v100
	s_mov_b64 s[50:51], 0
	s_nop 0
	v_addc_co_u32_e32 v101, vcc, 0, v101, vcc
	global_store_dwordx2 v[100:101], v[102:103], off offset:896
	global_store_dwordx2 v[104:105], v[98:99], off offset:32

.LBB0_457:
	s_andn2_b64 vcc, exec, s[50:51]
	s_cbranch_vccnz .LBB0_484
	s_cmp_lg_u32 s62, 1
	s_mov_b64 s[50:51], -1
	s_cbranch_scc0 .LBB0_477
	s_andn2_b64 vcc, exec, s[14:15]
	s_cbranch_vccnz .LBB0_474
	s_andn2_b64 vcc, exec, s[16:17]
	s_cbranch_vccnz .LBB0_470
	s_andn2_b64 vcc, exec, s[8:9]
	s_cbranch_vccnz .LBB0_467
	v_readlane_b32 s50, v242, 16
	v_readlane_b32 s51, v242, 17
	s_andn2_b64 vcc, exec, s[50:51]
	s_mov_b64 s[50:51], -1
	s_cbranch_vccnz .LBB0_464
	s_mov_b32 s50, 0x3e0293ee
	v_ashrrev_i32_e32 v147, 31, v146
	v_mul_f32_e32 v100, s50, v106
	v_mul_f32_e32 v101, s50, v107
	v_mul_f32_e32 v98, s50, v108
	v_mul_f32_e32 v99, s50, v109
	v_mul_f32_e32 v104, s50, v162
	v_mul_f32_e32 v105, s50, v163
	v_mul_f32_e32 v152, s50, v164
	v_mul_f32_e32 v153, s50, v165
	v_lshl_add_u64 v[102:103], v[146:147], 1, v[154:155]
	v_cvt_pk_bf16_f32 v98, v98, v99
	v_cvt_pk_bf16_f32 v99, v100, v101
	v_cvt_pk_bf16_f32 v100, v152, v153
	v_cvt_pk_bf16_f32 v101, v104, v105
	s_mov_b64 s[50:51], 0
	global_store_dwordx4 v[102:103], v[98:101], off offset:256

.LBB0_467:
	s_andn2_b64 vcc, exec, s[50:51]
	s_cbranch_vccnz .LBB0_469
	s_mov_b32 s50, 0x3e38aa3b
	v_ashrrev_i32_e32 v147, 31, v146
	v_mul_f32_e32 v100, s50, v106
	v_mul_f32_e32 v101, s50, v107
	v_mul_f32_e32 v98, s50, v108
	v_mul_f32_e32 v99, s50, v109
	v_mul_f32_e32 v104, s50, v162
	v_mul_f32_e32 v105, s50, v163
	v_mul_f32_e32 v116, s50, v164
	v_mul_f32_e32 v117, s50, v165
	v_lshl_add_u64 v[102:103], v[146:147], 1, v[150:151]
	v_cvt_pk_bf16_f32 v98, v98, v99
	v_cvt_pk_bf16_f32 v99, v100, v101
	v_cvt_pk_bf16_f32 v100, v116, v117
	v_cvt_pk_bf16_f32 v101, v104, v105
	global_store_dwordx4 v[102:103], v[98:101], off offset:256

.LBB0_470:
	s_andn2_b64 vcc, exec, s[50:51]
	s_cbranch_vccnz .LBB0_473
	v_readlane_b32 s50, v243, 47
	v_readlane_b32 s51, v243, 48
	s_andn2_b64 vcc, exec, s[50:51]
	s_cbranch_vccnz .LBB0_473
	global_load_dwordx4 v[98:101], v[120:121], off offset:16
	global_load_dwordx4 v[102:105], v[120:121], off
	v_lshl_add_u64 v[116:117], v[126:127], 1, v[124:125]
	s_brev_b32 s11, 16
	s_mov_b64 s[50:51], 0x8000080
	v_lshl_add_u64 v[124:125], v[116:117], 0, s[50:51]
	s_waitcnt vmcnt(0)
	v_mov_b32_e32 v121, v104
	v_mov_b32_e32 v104, v103
	v_mov_b32_e32 v120, v102
	v_mul_f32_e32 v102, v164, v104
	v_mul_f32_e32 v103, v165, v105
	v_mul_f32_e32 v104, v108, v104
	v_mul_f32_e32 v105, v109, v105
	v_fma_f32 v102, v108, v120, -v102
	v_fma_f32 v103, v109, v121, -v103
	v_fma_f32 v104, v164, v120, v104
	v_fma_f32 v105, v165, v121, v105
	v_mov_b32_e32 v121, v100
	v_mov_b32_e32 v100, v99
	v_mov_b32_e32 v120, v98
	v_mul_f32_e32 v98, v162, v100
	v_mul_f32_e32 v99, v163, v101
	v_mul_f32_e32 v100, v106, v100
	v_mul_f32_e32 v101, v107, v101
	v_fma_f32 v98, v106, v120, -v98
	v_fma_f32 v99, v107, v121, -v99
	v_fma_f32 v100, v162, v120, v100
	v_fma_f32 v101, v163, v121, v101
	v_cvt_pk_bf16_f32 v102, v102, v103
	v_cvt_pk_bf16_f32 v103, v98, v99
	v_cvt_pk_bf16_f32 v99, v100, v101
	v_add_co_u32_e32 v100, vcc, s11, v116
	v_cvt_pk_bf16_f32 v98, v104, v105
	s_nop 0
	v_addc_co_u32_e32 v101, vcc, 0, v117, vcc
	global_store_dwordx2 v[100:101], v[102:103], off offset:128
	global_store_dwordx2 v[124:125], v[98:99], off offset:32
	global_store_dwordx2 v[124:125], v[102:103], off offset:192
	global_store_dwordx2 v[124:125], v[98:99], off offset:224
	global_store_dwordx2 v[124:125], v[102:103], off offset:384
	global_store_dwordx2 v[124:125], v[98:99], off offset:416
	global_store_dwordx2 v[124:125], v[102:103], off offset:576
	global_store_dwordx2 v[124:125], v[98:99], off offset:608
	global_store_dwordx2 v[124:125], v[102:103], off offset:768
	global_store_dwordx2 v[124:125], v[98:99], off offset:800
	global_store_dwordx2 v[124:125], v[102:103], off offset:960
	global_store_dwordx2 v[124:125], v[98:99], off offset:992
	global_store_dwordx2 v[124:125], v[102:103], off offset:1152
	global_store_dwordx2 v[124:125], v[98:99], off offset:1184
	global_store_dwordx2 v[124:125], v[102:103], off offset:1344
	global_store_dwordx2 v[124:125], v[98:99], off offset:1376

.LBB0_474:
	s_andn2_b64 vcc, exec, s[50:51]
	v_mov_b32_e32 v98, v180
	s_cbranch_vccnz .LBB0_476
	v_ashrrev_i32_e32 v147, 31, v146
	v_lshl_add_u64 v[102:103], v[146:147], 1, v[118:119]
	v_cvt_pk_bf16_f32 v98, v108, v109
	v_cvt_pk_bf16_f32 v99, v106, v107
	v_cvt_pk_bf16_f32 v100, v164, v165
	v_cvt_pk_bf16_f32 v101, v162, v163
	global_store_dwordx4 v[102:103], v[98:101], off offset:256
	s_nop 1
	v_mul_f32_e32 v98, v106, v106
	v_mul_f32_e32 v99, v107, v107
	v_mul_f32_e32 v100, v108, v108
	v_mul_f32_e32 v101, v109, v109
	s_nop 0
	v_pk_mov_b32 v[102:103], v[100:101], v[98:99] op_sel:[1,0]
	v_mov_b32_e32 v101, v99
	v_add_f32_e32 v98, v102, v100
	v_add_f32_e32 v99, v103, v101
	v_mul_f32_e32 v100, v162, v162
	v_mul_f32_e32 v101, v163, v163
	v_mul_f32_e32 v102, v164, v164
	v_mul_f32_e32 v103, v165, v165
	v_mov_b32_e32 v104, v100
	v_mov_b32_e32 v105, v102
	v_mov_b32_e32 v102, v101
	v_add_f32_e32 v100, v104, v102
	v_add_f32_e32 v101, v105, v103
	v_add_f32_e32 v98, v98, v99
	v_add_f32_e32 v98, v101, v98
	v_add_f32_e32 v98, v100, v98
	v_add_f32_e32 v98, v98, v180

.LBB0_493:
	v_mul_f32_e32 v101, 0x3e16c740, v100
	v_lshlrev_b64 v[102:103], 11, v[98:99]
	v_cndmask_b32_e64 v124, v100, v101, s[52:53]
	v_lshlrev_b64 v[100:101], 10, v[98:99]
	v_lshl_add_u64 v[118:119], s[88:89], 0, v[102:103]
	v_lshlrev_b64 v[104:105], 12, v[98:99]
	v_lshl_add_u64 v[116:117], s[34:35], 0, v[102:103]
	v_lshlrev_b64 v[102:103], 13, v[98:99]
	v_lshl_add_u64 v[152:153], v[148:149], 0, v[104:105]
	v_lshl_add_u64 v[108:109], s[2:3], 0, v[100:101]
	v_lshl_add_u64 v[154:155], s[28:29], 0, v[102:103]
	v_mul_f32_e32 v120, v96, v124
	v_mul_f32_e32 v121, v97, v124
	v_mul_f32_e32 v158, v94, v124
	v_mul_f32_e32 v159, v95, v124
	v_mul_f32_e32 v160, v92, v124
	v_mul_f32_e32 v161, v93, v124
	v_mul_f32_e32 v162, v90, v124
	v_mul_f32_e32 v163, v91, v124
	s_cmp_lt_i32 s62, 4
	s_mov_b64 s[50:51], -1
	s_cbranch_scc1 .LBB0_512
	s_cmp_lt_i32 s62, 6
	s_cbranch_scc1 .LBB0_503
	s_cmp_gt_i32 s62, 6
	s_cbranch_scc0 .LBB0_497
	v_max_f32_e32 v91, v162, v162
	v_max_f32_e32 v95, v160, v160
	v_max_f32_e32 v90, v158, v158
	v_max_f32_e32 v92, 0, v91
	v_max_f32_e32 v91, v159, v159
	v_max_f32_e32 v93, v163, v163
	v_max_f32_e32 v94, v120, v120
	v_max_f32_e32 v96, 0, v95
	v_max_f32_e32 v95, v121, v121
	v_max_f32_e32 v97, v161, v161
	v_max_f32_e32 v90, 0, v90
	v_max_f32_e32 v91, 0, v91
	v_max_f32_e32 v93, 0, v93
	v_max_f32_e32 v94, 0, v94
	v_max_f32_e32 v95, 0, v95
	v_max_f32_e32 v97, 0, v97
	v_mul_f32_e32 v90, v90, v90
	v_mul_f32_e32 v91, v91, v91
	v_mul_f32_e32 v92, v92, v92
	v_mul_f32_e32 v93, v93, v93
	v_mul_f32_e32 v94, v94, v94
	v_mul_f32_e32 v95, v95, v95
	v_mul_f32_e32 v96, v96, v96
	v_mul_f32_e32 v97, v97, v97
	v_ashrrev_i32_e32 v147, 31, v146
	v_lshl_add_u64 v[102:103], v[146:147], 1, v[154:155]
	v_cvt_pk_bf16_f32 v90, v90, v91
	v_cvt_pk_bf16_f32 v91, v94, v95
	v_cvt_pk_bf16_f32 v92, v92, v93
	v_cvt_pk_bf16_f32 v93, v96, v97
	global_store_dwordx4 v[102:103], v[90:93], off
	s_mov_b64 s[50:51], 0

.LBB0_501:
	s_waitcnt vmcnt(0)
	v_add_f32_e32 v104, v120, v92
	v_add_f32_e32 v105, v121, v93
	v_add_f32_e32 v106, v158, v90
	v_add_f32_e32 v107, v159, v91
	v_add_f32_e32 v96, v160, v96
	v_add_f32_e32 v97, v161, v97
	v_add_f32_e32 v94, v162, v94
	v_add_f32_e32 v95, v163, v95
	v_cvt_pk_bf16_f32 v90, v106, v107
	v_cvt_pk_bf16_f32 v91, v104, v105
	v_cvt_pk_bf16_f32 v92, v94, v95
	v_cvt_pk_bf16_f32 v93, v96, v97
	global_store_dwordx4 v[102:103], v[90:93], off
	v_mul_f32_e32 v94, v94, v94
	v_mul_f32_e32 v95, v95, v95
	s_nop 0
	v_mul_f32_e32 v90, v104, v104
	v_mul_f32_e32 v91, v105, v105
	v_mul_f32_e32 v92, v106, v106
	v_mul_f32_e32 v93, v107, v107
	s_nop 0
	v_pk_mov_b32 v[102:103], v[92:93], v[90:91] op_sel:[1,0]
	v_mov_b32_e32 v93, v91
	v_add_f32_e32 v90, v102, v92
	v_add_f32_e32 v91, v103, v93
	v_mul_f32_e32 v92, v96, v96
	v_mul_f32_e32 v93, v97, v97
	v_mov_b32_e32 v97, v94
	v_mov_b32_e32 v96, v92
	v_mov_b32_e32 v94, v93
	v_add_f32_e32 v92, v96, v94
	v_add_f32_e32 v93, v97, v95
	v_add_f32_e32 v90, v90, v91
	v_add_f32_e32 v90, v90, v93
	v_add_f32_e32 v164, v92, v90

.LBB0_507:
	s_waitcnt vmcnt(0)
	v_cvt_f32_ubyte3_e32 v107, v94
	v_cvt_f32_ubyte2_e32 v106, v94
	v_cvt_f32_ubyte1_e32 v111, v94
	v_cvt_f32_ubyte0_e32 v110, v94
	v_mul_f32_e32 v110, s26, v110
	v_mul_f32_e32 v111, s26, v111
	v_mul_f32_e32 v106, s26, v106
	v_mul_f32_e32 v107, s26, v107
	v_fma_f32 v102, v158, v110, v102
	v_fma_f32 v103, v159, v111, v103
	v_fma_f32 v104, v120, v106, v104
	v_fma_f32 v105, v121, v107, v105
	v_cvt_f32_ubyte3_e32 v107, v95
	v_cvt_f32_ubyte2_e32 v106, v95
	v_cvt_f32_ubyte1_e32 v111, v95
	v_cvt_f32_ubyte0_e32 v110, v95
	v_mul_f32_e32 v94, s26, v110
	v_mul_f32_e32 v95, s26, v111
	v_mul_f32_e32 v106, s26, v106
	v_mul_f32_e32 v107, s26, v107
	v_fma_f32 v94, v162, v94, v92
	v_fma_f32 v95, v163, v95, v93
	v_fma_f32 v96, v160, v106, v96
	v_fma_f32 v97, v161, v107, v97
	v_cvt_pk_bf16_f32 v92, v102, v103
	v_cvt_pk_bf16_f32 v93, v104, v105
	v_cvt_pk_bf16_f32 v94, v94, v95
	v_cvt_pk_bf16_f32 v95, v96, v97
	s_mov_b64 s[50:51], 0
	global_store_dwordx4 v[90:91], v[92:95], off

.LBB0_520:
	s_andn2_b64 vcc, exec, s[50:51]
	s_cbranch_vccnz .LBB0_525
	s_andn2_b64 vcc, exec, s[6:7]
	s_mov_b64 s[50:51], -1
	s_cbranch_vccnz .LBB0_523
	global_load_dwordx4 v[90:93], v[102:103], off offset:16
	global_load_dwordx4 v[164:167], v[102:103], off
	v_readlane_b32 s11, v243, 49
	s_lshl_b32 s84, s11, 1
	s_mov_b64 s[50:51], 0x6800080
	s_waitcnt vmcnt(0)
	v_mov_b32_e32 v169, v166
	v_mov_b32_e32 v166, v165
	v_mov_b32_e32 v168, v164
	v_mul_f32_e32 v164, v162, v166
	v_mul_f32_e32 v165, v163, v167
	v_mul_f32_e32 v166, v158, v166
	v_mul_f32_e32 v167, v159, v167
	v_fma_f32 v164, v158, v168, -v164
	v_fma_f32 v165, v159, v169, -v165
	v_fma_f32 v166, v162, v168, v166
	v_fma_f32 v167, v163, v169, v167
	v_mov_b32_e32 v169, v92
	v_mov_b32_e32 v92, v91
	v_mov_b32_e32 v168, v90
	v_mul_f32_e32 v90, v160, v92
	v_mul_f32_e32 v91, v161, v93
	v_mul_f32_e32 v92, v120, v92
	v_mul_f32_e32 v93, v121, v93
	v_fma_f32 v90, v120, v168, -v90
	v_fma_f32 v91, v121, v169, -v91
	v_fma_f32 v92, v160, v168, v92
	v_fma_f32 v93, v161, v169, v93
	v_cvt_pk_bf16_f32 v164, v164, v165
	v_cvt_pk_bf16_f32 v165, v90, v91
	v_cvt_pk_bf16_f32 v91, v92, v93
	v_lshl_add_u64 v[92:93], v[104:105], 0, s[84:85]
	v_lshl_add_u64 v[92:93], v[126:127], 1, v[92:93]
	v_cvt_pk_bf16_f32 v90, v166, v167
	v_lshl_add_u64 v[166:167], v[92:93], 0, s[50:51]
	v_add_co_u32_e32 v92, vcc, 0x6800000, v92
	s_mov_b64 s[50:51], 0
	s_nop 0
	v_addc_co_u32_e32 v93, vcc, 0, v93, vcc
	global_store_dwordx2 v[92:93], v[164:165], off offset:128
	global_store_dwordx2 v[166:167], v[90:91], off offset:32

.LBB0_526:
	s_andn2_b64 vcc, exec, s[50:51]
	v_mov_b32_e32 v164, 0
	s_cbranch_vccnz .LBB0_550
	s_cmp_lg_u32 s62, 1
	s_mov_b64 s[50:51], -1
	s_cbranch_scc0 .LBB0_544
	s_andn2_b64 vcc, exec, s[14:15]
	v_ashrrev_i32_e32 v147, 31, v146
	s_cbranch_vccnz .LBB0_1277
	v_lshlrev_b64 v[90:91], 8, v[98:99]
	s_andn2_b64 vcc, exec, s[16:17]
	s_cbranch_vccnz .LBB0_539
	s_andn2_b64 vcc, exec, s[8:9]
	s_cbranch_vccnz .LBB0_536
	v_readlane_b32 s50, v242, 16
	v_readlane_b32 s51, v242, 17
	s_andn2_b64 vcc, exec, s[50:51]
	s_mov_b64 s[50:51], -1
	s_cbranch_vccnz .LBB0_533
	s_mov_b32 s50, 0x3e0293ee
	v_mul_f32_e32 v166, s50, v120
	v_mul_f32_e32 v167, s50, v121
	v_mul_f32_e32 v164, s50, v158
	v_mul_f32_e32 v165, s50, v159
	v_mul_f32_e32 v168, s50, v160
	v_mul_f32_e32 v169, s50, v161
	v_mul_f32_e32 v170, s50, v162
	v_mul_f32_e32 v171, s50, v163
	v_lshl_add_u64 v[92:93], v[146:147], 1, v[110:111]
	v_cvt_pk_bf16_f32 v164, v164, v165
	v_cvt_pk_bf16_f32 v165, v166, v167
	v_cvt_pk_bf16_f32 v166, v170, v171
	v_cvt_pk_bf16_f32 v167, v168, v169
	s_mov_b64 s[50:51], 0
	global_store_dwordx4 v[92:93], v[164:167], off

.LBB0_536:
	s_andn2_b64 vcc, exec, s[50:51]
	s_cbranch_vccnz .LBB0_538
	s_mov_b32 s50, 0x3e38aa3b
	v_mul_f32_e32 v166, s50, v120
	v_mul_f32_e32 v167, s50, v121
	v_mul_f32_e32 v164, s50, v158
	v_mul_f32_e32 v165, s50, v159
	v_mul_f32_e32 v168, s50, v160
	v_mul_f32_e32 v169, s50, v161
	v_mul_f32_e32 v170, s50, v162
	v_mul_f32_e32 v171, s50, v163
	v_lshl_add_u64 v[92:93], v[146:147], 1, v[106:107]
	v_cvt_pk_bf16_f32 v164, v164, v165
	v_cvt_pk_bf16_f32 v165, v166, v167
	v_cvt_pk_bf16_f32 v166, v170, v171
	v_cvt_pk_bf16_f32 v167, v168, v169
	global_store_dwordx4 v[92:93], v[164:167], off

.LBB0_539:
	s_andn2_b64 vcc, exec, s[50:51]
	v_mov_b32_e32 v164, 0
	s_cbranch_vccnz .LBB0_541
	v_readlane_b32 s50, v242, 13
	v_readlane_b32 s51, v242, 14
	v_cvt_pk_bf16_f32 v92, v162, v163
	v_cvt_pk_bf16_f32 v93, v160, v161
	v_lshl_add_u64 v[90:91], s[50:51], 0, v[90:91]
	v_lshl_add_u64 v[164:165], v[146:147], 1, v[90:91]
	v_cvt_pk_bf16_f32 v90, v158, v159
	v_cvt_pk_bf16_f32 v91, v120, v121
	global_store_dwordx4 v[164:165], v[90:93], off
	s_nop 1
	v_mul_f32_e32 v90, v120, v120
	v_mul_f32_e32 v91, v121, v121
	v_mul_f32_e32 v92, v158, v158
	v_mul_f32_e32 v93, v159, v159
	s_nop 0
	v_pk_mov_b32 v[164:165], v[92:93], v[90:91] op_sel:[1,0]
	v_mov_b32_e32 v93, v91
	v_add_f32_e32 v90, v164, v92
	v_add_f32_e32 v91, v165, v93
	v_mul_f32_e32 v92, v160, v160
	v_mul_f32_e32 v93, v161, v161
	v_mul_f32_e32 v164, v162, v162
	v_mul_f32_e32 v165, v163, v163
	v_mov_b32_e32 v166, v92
	v_mov_b32_e32 v167, v164
	v_mov_b32_e32 v164, v93
	v_add_f32_e32 v92, v166, v164
	v_add_f32_e32 v93, v167, v165
	v_add_f32_e32 v90, v90, v91
	v_add_f32_e32 v90, v93, v90
	v_add_f32_e32 v164, v92, v90

.LBB0_542:
	v_lshl_add_u64 v[164:165], v[146:147], 1, v[100:101]
	v_cvt_pk_bf16_f32 v90, v158, v159
	v_cvt_pk_bf16_f32 v91, v120, v121
	v_cvt_pk_bf16_f32 v92, v162, v163
	v_cvt_pk_bf16_f32 v93, v160, v161
	global_store_dwordx4 v[164:165], v[90:93], off
	s_nop 1
	v_mul_f32_e32 v90, v120, v120
	v_mul_f32_e32 v91, v121, v121
	v_mul_f32_e32 v92, v158, v158
	v_mul_f32_e32 v93, v159, v159
	s_nop 0
	v_pk_mov_b32 v[164:165], v[92:93], v[90:91] op_sel:[1,0]
	v_mov_b32_e32 v93, v91
	v_add_f32_e32 v90, v164, v92
	v_add_f32_e32 v91, v165, v93
	v_mul_f32_e32 v92, v160, v160
	v_mul_f32_e32 v93, v161, v161
	v_mul_f32_e32 v164, v162, v162
	v_mul_f32_e32 v165, v163, v163
	v_mov_b32_e32 v166, v92
	v_mov_b32_e32 v167, v164
	v_mov_b32_e32 v164, v93
	v_add_f32_e32 v92, v166, v164
	v_add_f32_e32 v93, v167, v165
	v_add_f32_e32 v90, v90, v91
	v_add_f32_e32 v90, v93, v90
	v_add_f32_e32 v164, v92, v90

.LBB0_550:
	v_mov_b32_e32 v125, v124
	v_mov_b32_e32 v120, v124
	v_mov_b32_e32 v121, v124
	v_mul_f32_e32 v90, v88, v120
	v_mul_f32_e32 v91, v89, v121
	v_mul_f32_e32 v92, v86, v124
	v_mul_f32_e32 v93, v87, v125
	v_mul_f32_e32 v120, v84, v120
	v_mul_f32_e32 v121, v85, v121
	v_mul_f32_e32 v124, v82, v124
	v_mul_f32_e32 v125, v83, v125
	s_cmp_lt_i32 s62, 4
	s_mov_b64 s[50:51], -1
	s_cbranch_scc0 .LBB0_556
	s_andn2_b64 vcc, exec, s[50:51]
	s_cbranch_vccz .LBB0_574

.LBB0_556:
	s_cmp_lt_i32 s62, 6
	s_cbranch_scc1 .LBB0_565
	s_cmp_gt_i32 s62, 6
	s_cbranch_scc0 .LBB0_559
	v_max_f32_e32 v83, v124, v124
	v_max_f32_e32 v87, v120, v120
	v_max_f32_e32 v82, v92, v92
	v_max_f32_e32 v84, 0, v83
	v_max_f32_e32 v83, v93, v93
	v_max_f32_e32 v85, v125, v125
	v_max_f32_e32 v86, v90, v90
	v_max_f32_e32 v88, 0, v87
	v_max_f32_e32 v87, v91, v91
	v_max_f32_e32 v89, v121, v121
	v_max_f32_e32 v82, 0, v82
	v_max_f32_e32 v83, 0, v83
	v_max_f32_e32 v85, 0, v85
	v_max_f32_e32 v86, 0, v86
	v_max_f32_e32 v87, 0, v87
	v_max_f32_e32 v89, 0, v89
	v_mul_f32_e32 v82, v82, v82
	v_mul_f32_e32 v83, v83, v83
	v_mul_f32_e32 v84, v84, v84
	v_mul_f32_e32 v85, v85, v85
	v_mul_f32_e32 v86, v86, v86
	v_mul_f32_e32 v87, v87, v87
	v_mul_f32_e32 v88, v88, v88
	v_mul_f32_e32 v89, v89, v89
	v_ashrrev_i32_e32 v147, 31, v146
	v_lshl_add_u64 v[154:155], v[146:147], 1, v[154:155]
	v_cvt_pk_bf16_f32 v82, v82, v83
	v_cvt_pk_bf16_f32 v83, v86, v87
	v_cvt_pk_bf16_f32 v84, v84, v85
	v_cvt_pk_bf16_f32 v85, v88, v89
	global_store_dwordx4 v[154:155], v[82:85], off offset:256
	s_mov_b64 s[50:51], 0

.LBB0_563:
	s_waitcnt vmcnt(0)
	v_add_f32_e32 v152, v90, v84
	v_add_f32_e32 v153, v91, v85
	v_add_f32_e32 v154, v92, v82
	v_add_f32_e32 v155, v93, v83
	v_add_f32_e32 v88, v120, v88
	v_add_f32_e32 v89, v121, v89
	v_add_f32_e32 v86, v124, v86
	v_add_f32_e32 v87, v125, v87
	v_cvt_pk_bf16_f32 v82, v154, v155
	v_cvt_pk_bf16_f32 v83, v152, v153
	v_cvt_pk_bf16_f32 v84, v86, v87
	v_cvt_pk_bf16_f32 v85, v88, v89
	global_store_dwordx4 v[118:119], v[82:85], off
	v_mul_f32_e32 v86, v86, v86
	v_mul_f32_e32 v87, v87, v87
	s_nop 0
	v_mul_f32_e32 v82, v152, v152
	v_mul_f32_e32 v83, v153, v153
	v_mul_f32_e32 v84, v154, v154
	v_mul_f32_e32 v85, v155, v155
	s_nop 0
	v_pk_mov_b32 v[118:119], v[84:85], v[82:83] op_sel:[1,0]
	v_mov_b32_e32 v85, v83
	v_add_f32_e32 v82, v118, v84
	v_add_f32_e32 v83, v119, v85
	v_mul_f32_e32 v84, v88, v88
	v_mul_f32_e32 v85, v89, v89
	v_mov_b32_e32 v89, v86
	v_mov_b32_e32 v88, v84
	v_mov_b32_e32 v86, v85
	v_add_f32_e32 v84, v88, v86
	v_add_f32_e32 v85, v89, v87
	v_add_f32_e32 v82, v82, v83
	v_add_f32_e32 v82, v82, v85
	v_add_f32_e32 v82, v84, v82
	v_add_f32_e32 v82, v164, v82

.LBB0_569:
	s_waitcnt vmcnt(0)
	v_cvt_f32_ubyte3_e32 v153, v86
	v_cvt_f32_ubyte2_e32 v152, v86
	v_cvt_f32_ubyte1_e32 v155, v86
	v_cvt_f32_ubyte0_e32 v154, v86
	v_mul_f32_e32 v154, s26, v154
	v_mul_f32_e32 v155, s26, v155
	v_mul_f32_e32 v152, s26, v152
	v_mul_f32_e32 v153, s26, v153
	v_fma_f32 v116, v92, v154, v116
	v_fma_f32 v117, v93, v155, v117
	v_fma_f32 v118, v90, v152, v118
	v_fma_f32 v119, v91, v153, v119
	v_cvt_f32_ubyte3_e32 v153, v87
	v_cvt_f32_ubyte2_e32 v152, v87
	v_cvt_f32_ubyte1_e32 v155, v87
	v_cvt_f32_ubyte0_e32 v154, v87
	v_mul_f32_e32 v86, s26, v154
	v_mul_f32_e32 v87, s26, v155
	v_mul_f32_e32 v152, s26, v152
	v_mul_f32_e32 v153, s26, v153
	v_fma_f32 v86, v124, v86, v84
	v_fma_f32 v87, v125, v87, v85
	v_fma_f32 v88, v120, v152, v88
	v_fma_f32 v89, v121, v153, v89
	v_cvt_pk_bf16_f32 v84, v116, v117
	v_cvt_pk_bf16_f32 v85, v118, v119
	v_cvt_pk_bf16_f32 v86, v86, v87
	v_cvt_pk_bf16_f32 v87, v88, v89
	s_mov_b64 s[50:51], 0
	global_store_dwordx4 v[82:83], v[84:87], off

.LBB0_581:
	s_andn2_b64 vcc, exec, s[50:51]
	s_cbranch_vccnz .LBB0_586
	s_andn2_b64 vcc, exec, s[6:7]
	s_mov_b64 s[50:51], -1
	s_cbranch_vccnz .LBB0_584
	global_load_dwordx4 v[82:85], v[102:103], off offset:16
	global_load_dwordx4 v[86:89], v[102:103], off
	v_readlane_b32 s11, v243, 49
	s_lshl_b32 s84, s11, 1
	s_mov_b64 s[50:51], 0x6800380
	s_waitcnt vmcnt(0)
	v_mov_b32_e32 v109, v88
	v_mov_b32_e32 v88, v87
	v_mov_b32_e32 v108, v86
	v_mul_f32_e32 v86, v124, v88
	v_mul_f32_e32 v87, v125, v89
	v_mul_f32_e32 v88, v92, v88
	v_mul_f32_e32 v89, v93, v89
	v_fma_f32 v86, v92, v108, -v86
	v_fma_f32 v87, v93, v109, -v87
	v_fma_f32 v88, v124, v108, v88
	v_fma_f32 v89, v125, v109, v89
	v_mov_b32_e32 v109, v84
	v_mov_b32_e32 v84, v83
	v_mov_b32_e32 v108, v82
	v_mul_f32_e32 v82, v120, v84
	v_mul_f32_e32 v83, v121, v85
	v_mul_f32_e32 v84, v90, v84
	v_mul_f32_e32 v85, v91, v85
	v_fma_f32 v82, v90, v108, -v82
	v_fma_f32 v83, v91, v109, -v83
	v_fma_f32 v84, v120, v108, v84
	v_fma_f32 v85, v121, v109, v85
	v_cvt_pk_bf16_f32 v86, v86, v87
	v_cvt_pk_bf16_f32 v87, v82, v83
	v_cvt_pk_bf16_f32 v83, v84, v85
	v_lshl_add_u64 v[84:85], v[104:105], 0, s[84:85]
	v_lshl_add_u64 v[84:85], v[126:127], 1, v[84:85]
	v_cvt_pk_bf16_f32 v82, v88, v89
	v_lshl_add_u64 v[88:89], v[84:85], 0, s[50:51]
	v_add_co_u32_e32 v84, vcc, 0x6800000, v84
	s_mov_b64 s[50:51], 0
	s_nop 0
	v_addc_co_u32_e32 v85, vcc, 0, v85, vcc
	global_store_dwordx2 v[84:85], v[86:87], off offset:896
	global_store_dwordx2 v[88:89], v[82:83], off offset:32

.LBB0_587:
	s_andn2_b64 vcc, exec, s[50:51]
	s_cbranch_vccnz .LBB0_614
	s_cmp_lg_u32 s62, 1
	s_mov_b64 s[50:51], -1
	s_cbranch_scc0 .LBB0_607
	s_andn2_b64 vcc, exec, s[14:15]
	s_cbranch_vccnz .LBB0_604
	s_andn2_b64 vcc, exec, s[16:17]
	s_cbranch_vccnz .LBB0_600
	s_andn2_b64 vcc, exec, s[8:9]
	s_cbranch_vccnz .LBB0_597
	v_readlane_b32 s50, v242, 16
	v_readlane_b32 s51, v242, 17
	s_andn2_b64 vcc, exec, s[50:51]
	s_mov_b64 s[50:51], -1
	s_cbranch_vccnz .LBB0_594
	s_mov_b32 s50, 0x3e0293ee
	v_ashrrev_i32_e32 v147, 31, v146
	v_mul_f32_e32 v84, s50, v90
	v_mul_f32_e32 v85, s50, v91
	v_mul_f32_e32 v82, s50, v92
	v_mul_f32_e32 v83, s50, v93
	v_mul_f32_e32 v88, s50, v120
	v_mul_f32_e32 v89, s50, v121
	v_mul_f32_e32 v108, s50, v124
	v_mul_f32_e32 v109, s50, v125
	v_lshl_add_u64 v[86:87], v[146:147], 1, v[110:111]
	v_cvt_pk_bf16_f32 v82, v82, v83
	v_cvt_pk_bf16_f32 v83, v84, v85
	v_cvt_pk_bf16_f32 v84, v108, v109
	v_cvt_pk_bf16_f32 v85, v88, v89
	s_mov_b64 s[50:51], 0
	global_store_dwordx4 v[86:87], v[82:85], off offset:256

.LBB0_597:
	s_andn2_b64 vcc, exec, s[50:51]
	s_cbranch_vccnz .LBB0_599
	s_mov_b32 s50, 0x3e38aa3b
	v_ashrrev_i32_e32 v147, 31, v146
	v_mul_f32_e32 v84, s50, v90
	v_mul_f32_e32 v85, s50, v91
	v_mul_f32_e32 v82, s50, v92
	v_mul_f32_e32 v83, s50, v93
	v_mul_f32_e32 v88, s50, v120
	v_mul_f32_e32 v89, s50, v121
	v_mul_f32_e32 v98, s50, v124
	v_mul_f32_e32 v99, s50, v125
	v_lshl_add_u64 v[86:87], v[146:147], 1, v[106:107]
	v_cvt_pk_bf16_f32 v82, v82, v83
	v_cvt_pk_bf16_f32 v83, v84, v85
	v_cvt_pk_bf16_f32 v84, v98, v99
	v_cvt_pk_bf16_f32 v85, v88, v89
	global_store_dwordx4 v[86:87], v[82:85], off offset:256

.LBB0_600:
	s_andn2_b64 vcc, exec, s[50:51]
	s_cbranch_vccnz .LBB0_603
	v_readlane_b32 s50, v243, 47
	v_readlane_b32 s51, v243, 48
	s_andn2_b64 vcc, exec, s[50:51]
	s_cbranch_vccnz .LBB0_603
	global_load_dwordx4 v[82:85], v[102:103], off offset:16
	global_load_dwordx4 v[86:89], v[102:103], off
	v_lshl_add_u64 v[98:99], v[126:127], 1, v[104:105]
	s_brev_b32 s11, 16
	s_mov_b64 s[50:51], 0x8000080
	v_lshl_add_u64 v[104:105], v[98:99], 0, s[50:51]
	s_waitcnt vmcnt(0)
	v_mov_b32_e32 v103, v88
	v_mov_b32_e32 v88, v87
	v_mov_b32_e32 v102, v86
	v_mul_f32_e32 v86, v124, v88
	v_mul_f32_e32 v87, v125, v89
	v_mul_f32_e32 v88, v92, v88
	v_mul_f32_e32 v89, v93, v89
	v_fma_f32 v86, v92, v102, -v86
	v_fma_f32 v87, v93, v103, -v87
	v_fma_f32 v88, v124, v102, v88
	v_fma_f32 v89, v125, v103, v89
	v_mov_b32_e32 v103, v84
	v_mov_b32_e32 v84, v83
	v_mov_b32_e32 v102, v82
	v_mul_f32_e32 v82, v120, v84
	v_mul_f32_e32 v83, v121, v85
	v_mul_f32_e32 v84, v90, v84
	v_mul_f32_e32 v85, v91, v85
	v_fma_f32 v82, v90, v102, -v82
	v_fma_f32 v83, v91, v103, -v83
	v_fma_f32 v84, v120, v102, v84
	v_fma_f32 v85, v121, v103, v85
	v_cvt_pk_bf16_f32 v86, v86, v87
	v_cvt_pk_bf16_f32 v87, v82, v83
	v_cvt_pk_bf16_f32 v83, v84, v85
	v_add_co_u32_e32 v84, vcc, s11, v98
	v_cvt_pk_bf16_f32 v82, v88, v89
	s_nop 0
	v_addc_co_u32_e32 v85, vcc, 0, v99, vcc
	global_store_dwordx2 v[84:85], v[86:87], off offset:128
	global_store_dwordx2 v[104:105], v[82:83], off offset:32
	global_store_dwordx2 v[104:105], v[86:87], off offset:192
	global_store_dwordx2 v[104:105], v[82:83], off offset:224
	global_store_dwordx2 v[104:105], v[86:87], off offset:384
	global_store_dwordx2 v[104:105], v[82:83], off offset:416
	global_store_dwordx2 v[104:105], v[86:87], off offset:576
	global_store_dwordx2 v[104:105], v[82:83], off offset:608
	global_store_dwordx2 v[104:105], v[86:87], off offset:768
	global_store_dwordx2 v[104:105], v[82:83], off offset:800
	global_store_dwordx2 v[104:105], v[86:87], off offset:960
	global_store_dwordx2 v[104:105], v[82:83], off offset:992
	global_store_dwordx2 v[104:105], v[86:87], off offset:1152
	global_store_dwordx2 v[104:105], v[82:83], off offset:1184
	global_store_dwordx2 v[104:105], v[86:87], off offset:1344
	global_store_dwordx2 v[104:105], v[82:83], off offset:1376

.LBB0_604:
	s_andn2_b64 vcc, exec, s[50:51]
	v_mov_b32_e32 v82, v164
	s_cbranch_vccnz .LBB0_606
	v_ashrrev_i32_e32 v147, 31, v146
	v_lshl_add_u64 v[86:87], v[146:147], 1, v[100:101]
	v_cvt_pk_bf16_f32 v82, v92, v93
	v_cvt_pk_bf16_f32 v83, v90, v91
	v_cvt_pk_bf16_f32 v84, v124, v125
	v_cvt_pk_bf16_f32 v85, v120, v121
	global_store_dwordx4 v[86:87], v[82:85], off offset:256
	s_nop 1
	v_mul_f32_e32 v82, v90, v90
	v_mul_f32_e32 v83, v91, v91
	v_mul_f32_e32 v84, v92, v92
	v_mul_f32_e32 v85, v93, v93
	s_nop 0
	v_pk_mov_b32 v[86:87], v[84:85], v[82:83] op_sel:[1,0]
	v_mov_b32_e32 v85, v83
	v_add_f32_e32 v82, v86, v84
	v_add_f32_e32 v83, v87, v85
	v_mul_f32_e32 v84, v120, v120
	v_mul_f32_e32 v85, v121, v121
	v_mul_f32_e32 v86, v124, v124
	v_mul_f32_e32 v87, v125, v125
	v_mov_b32_e32 v88, v84
	v_mov_b32_e32 v89, v86
	v_mov_b32_e32 v86, v85
	v_add_f32_e32 v84, v88, v86
	v_add_f32_e32 v85, v89, v87
	v_add_f32_e32 v82, v82, v83
	v_add_f32_e32 v82, v85, v82
	v_add_f32_e32 v82, v84, v82
	v_add_f32_e32 v82, v82, v164

.LBB0_623:
	v_mul_f32_e32 v85, 0x3e16c740, v84
	v_lshlrev_b64 v[86:87], 11, v[82:83]
	v_cndmask_b32_e64 v104, v84, v85, s[52:53]
	v_lshlrev_b64 v[84:85], 10, v[82:83]
	v_lshl_add_u64 v[100:101], s[88:89], 0, v[86:87]
	v_lshlrev_b64 v[88:89], 12, v[82:83]
	v_lshl_add_u64 v[98:99], s[34:35], 0, v[86:87]
	v_lshlrev_b64 v[86:87], 13, v[82:83]
	v_lshl_add_u64 v[108:109], v[148:149], 0, v[88:89]
	v_lshl_add_u64 v[92:93], s[2:3], 0, v[84:85]
	v_lshl_add_u64 v[110:111], s[28:29], 0, v[86:87]
	v_mul_f32_e32 v102, v80, v104
	v_mul_f32_e32 v103, v81, v104
	v_mul_f32_e32 v116, v78, v104
	v_mul_f32_e32 v117, v79, v104
	v_mul_f32_e32 v118, v76, v104
	v_mul_f32_e32 v119, v77, v104
	v_mul_f32_e32 v120, v74, v104
	v_mul_f32_e32 v121, v75, v104
	s_cmp_lt_i32 s62, 4
	s_mov_b64 s[50:51], -1
	s_cbranch_scc1 .LBB0_642
	s_cmp_lt_i32 s62, 6
	s_cbranch_scc1 .LBB0_633
	s_cmp_gt_i32 s62, 6
	s_cbranch_scc0 .LBB0_627
	v_max_f32_e32 v75, v120, v120
	v_max_f32_e32 v79, v118, v118
	v_max_f32_e32 v74, v116, v116
	v_max_f32_e32 v76, 0, v75
	v_max_f32_e32 v75, v117, v117
	v_max_f32_e32 v77, v121, v121
	v_max_f32_e32 v78, v102, v102
	v_max_f32_e32 v80, 0, v79
	v_max_f32_e32 v79, v103, v103
	v_max_f32_e32 v81, v119, v119
	v_max_f32_e32 v74, 0, v74
	v_max_f32_e32 v75, 0, v75
	v_max_f32_e32 v77, 0, v77
	v_max_f32_e32 v78, 0, v78
	v_max_f32_e32 v79, 0, v79
	v_max_f32_e32 v81, 0, v81
	v_mul_f32_e32 v74, v74, v74
	v_mul_f32_e32 v75, v75, v75
	v_mul_f32_e32 v76, v76, v76
	v_mul_f32_e32 v77, v77, v77
	v_mul_f32_e32 v78, v78, v78
	v_mul_f32_e32 v79, v79, v79
	v_mul_f32_e32 v80, v80, v80
	v_mul_f32_e32 v81, v81, v81
	v_ashrrev_i32_e32 v147, 31, v146
	v_lshl_add_u64 v[86:87], v[146:147], 1, v[110:111]
	v_cvt_pk_bf16_f32 v74, v74, v75
	v_cvt_pk_bf16_f32 v75, v78, v79
	v_cvt_pk_bf16_f32 v76, v76, v77
	v_cvt_pk_bf16_f32 v77, v80, v81
	global_store_dwordx4 v[86:87], v[74:77], off
	s_mov_b64 s[50:51], 0

.LBB0_631:
	s_waitcnt vmcnt(0)
	v_add_f32_e32 v88, v102, v76
	v_add_f32_e32 v89, v103, v77
	v_add_f32_e32 v90, v116, v74
	v_add_f32_e32 v91, v117, v75
	v_add_f32_e32 v80, v118, v80
	v_add_f32_e32 v81, v119, v81
	v_add_f32_e32 v78, v120, v78
	v_add_f32_e32 v79, v121, v79
	v_cvt_pk_bf16_f32 v74, v90, v91
	v_cvt_pk_bf16_f32 v75, v88, v89
	v_cvt_pk_bf16_f32 v76, v78, v79
	v_cvt_pk_bf16_f32 v77, v80, v81
	global_store_dwordx4 v[86:87], v[74:77], off
	v_mul_f32_e32 v78, v78, v78
	v_mul_f32_e32 v79, v79, v79
	s_nop 0
	v_mul_f32_e32 v74, v88, v88
	v_mul_f32_e32 v75, v89, v89
	v_mul_f32_e32 v76, v90, v90
	v_mul_f32_e32 v77, v91, v91
	s_nop 0
	v_pk_mov_b32 v[86:87], v[76:77], v[74:75] op_sel:[1,0]
	v_mov_b32_e32 v77, v75
	v_add_f32_e32 v74, v86, v76
	v_add_f32_e32 v75, v87, v77
	v_mul_f32_e32 v76, v80, v80
	v_mul_f32_e32 v77, v81, v81
	v_mov_b32_e32 v81, v78
	v_mov_b32_e32 v80, v76
	v_mov_b32_e32 v78, v77
	v_add_f32_e32 v76, v80, v78
	v_add_f32_e32 v77, v81, v79
	v_add_f32_e32 v74, v74, v75
	v_add_f32_e32 v74, v74, v77
	v_add_f32_e32 v124, v76, v74

.LBB0_637:
	s_waitcnt vmcnt(0)
	v_cvt_f32_ubyte3_e32 v91, v78
	v_cvt_f32_ubyte2_e32 v90, v78
	v_cvt_f32_ubyte1_e32 v95, v78
	v_cvt_f32_ubyte0_e32 v94, v78
	v_mul_f32_e32 v94, s26, v94
	v_mul_f32_e32 v95, s26, v95
	v_mul_f32_e32 v90, s26, v90
	v_mul_f32_e32 v91, s26, v91
	v_fma_f32 v86, v116, v94, v86
	v_fma_f32 v87, v117, v95, v87
	v_fma_f32 v88, v102, v90, v88
	v_fma_f32 v89, v103, v91, v89
	v_cvt_f32_ubyte3_e32 v91, v79
	v_cvt_f32_ubyte2_e32 v90, v79
	v_cvt_f32_ubyte1_e32 v95, v79
	v_cvt_f32_ubyte0_e32 v94, v79
	v_mul_f32_e32 v78, s26, v94
	v_mul_f32_e32 v79, s26, v95
	v_mul_f32_e32 v90, s26, v90
	v_mul_f32_e32 v91, s26, v91
	v_fma_f32 v78, v120, v78, v76
	v_fma_f32 v79, v121, v79, v77
	v_fma_f32 v80, v118, v90, v80
	v_fma_f32 v81, v119, v91, v81
	v_cvt_pk_bf16_f32 v76, v86, v87
	v_cvt_pk_bf16_f32 v77, v88, v89
	v_cvt_pk_bf16_f32 v78, v78, v79
	v_cvt_pk_bf16_f32 v79, v80, v81
	s_mov_b64 s[50:51], 0
	global_store_dwordx4 v[74:75], v[76:79], off

.LBB0_650:
	s_andn2_b64 vcc, exec, s[50:51]
	s_cbranch_vccnz .LBB0_655
	s_andn2_b64 vcc, exec, s[6:7]
	s_mov_b64 s[50:51], -1
	s_cbranch_vccnz .LBB0_653
	global_load_dwordx4 v[74:77], v[86:87], off offset:16
	global_load_dwordx4 v[150:153], v[86:87], off
	v_readlane_b32 s11, v243, 49
	s_lshl_b32 s84, s11, 1
	s_mov_b64 s[50:51], 0x6800080
	s_waitcnt vmcnt(0)
	v_mov_b32_e32 v125, v152
	v_mov_b32_e32 v152, v151
	v_mov_b32_e32 v124, v150
	v_mul_f32_e32 v150, v120, v152
	v_mul_f32_e32 v151, v121, v153
	v_mul_f32_e32 v152, v116, v152
	v_mul_f32_e32 v153, v117, v153
	v_fma_f32 v150, v116, v124, -v150
	v_fma_f32 v151, v117, v125, -v151
	v_fma_f32 v124, v120, v124, v152
	v_fma_f32 v125, v121, v125, v153
	v_mov_b32_e32 v153, v76
	v_mov_b32_e32 v76, v75
	v_mov_b32_e32 v152, v74
	v_mul_f32_e32 v74, v118, v76
	v_mul_f32_e32 v75, v119, v77
	v_mul_f32_e32 v76, v102, v76
	v_mul_f32_e32 v77, v103, v77
	v_fma_f32 v74, v102, v152, -v74
	v_fma_f32 v75, v103, v153, -v75
	v_fma_f32 v76, v118, v152, v76
	v_fma_f32 v77, v119, v153, v77
	v_cvt_pk_bf16_f32 v150, v150, v151
	v_cvt_pk_bf16_f32 v151, v74, v75
	v_cvt_pk_bf16_f32 v75, v76, v77
	v_lshl_add_u64 v[76:77], v[88:89], 0, s[84:85]
	v_lshl_add_u64 v[76:77], v[126:127], 1, v[76:77]
	v_cvt_pk_bf16_f32 v74, v124, v125
	v_lshl_add_u64 v[124:125], v[76:77], 0, s[50:51]
	v_add_co_u32_e32 v76, vcc, 0x6800000, v76
	s_mov_b64 s[50:51], 0
	s_nop 0
	v_addc_co_u32_e32 v77, vcc, 0, v77, vcc
	global_store_dwordx2 v[76:77], v[150:151], off offset:128
	global_store_dwordx2 v[124:125], v[74:75], off offset:32

.LBB0_656:
	s_andn2_b64 vcc, exec, s[50:51]
	v_mov_b32_e32 v124, 0
	s_cbranch_vccnz .LBB0_680
	s_cmp_lg_u32 s62, 1
	s_mov_b64 s[50:51], -1
	s_cbranch_scc0 .LBB0_674
	s_andn2_b64 vcc, exec, s[14:15]
	v_ashrrev_i32_e32 v147, 31, v146
	s_cbranch_vccnz .LBB0_1280
	v_lshlrev_b64 v[74:75], 8, v[82:83]
	s_andn2_b64 vcc, exec, s[16:17]
	s_cbranch_vccnz .LBB0_669
	s_andn2_b64 vcc, exec, s[8:9]
	s_cbranch_vccnz .LBB0_666
	v_readlane_b32 s50, v242, 16
	v_readlane_b32 s51, v242, 17
	s_andn2_b64 vcc, exec, s[50:51]
	s_mov_b64 s[50:51], -1
	s_cbranch_vccnz .LBB0_663
	s_mov_b32 s50, 0x3e0293ee
	v_mul_f32_e32 v124, s50, v102
	v_mul_f32_e32 v125, s50, v103
	v_mul_f32_e32 v150, s50, v116
	v_mul_f32_e32 v151, s50, v117
	v_mul_f32_e32 v154, s50, v118
	v_mul_f32_e32 v155, s50, v119
	v_mul_f32_e32 v152, s50, v120
	v_mul_f32_e32 v153, s50, v121
	v_lshl_add_u64 v[76:77], v[146:147], 1, v[94:95]
	v_cvt_pk_bf16_f32 v150, v150, v151
	v_cvt_pk_bf16_f32 v151, v124, v125
	v_cvt_pk_bf16_f32 v152, v152, v153
	v_cvt_pk_bf16_f32 v153, v154, v155
	s_mov_b64 s[50:51], 0
	global_store_dwordx4 v[76:77], v[150:153], off

.LBB0_666:
	s_andn2_b64 vcc, exec, s[50:51]
	s_cbranch_vccnz .LBB0_668
	s_mov_b32 s50, 0x3e38aa3b
	v_mul_f32_e32 v124, s50, v102
	v_mul_f32_e32 v125, s50, v103
	v_mul_f32_e32 v150, s50, v116
	v_mul_f32_e32 v151, s50, v117
	v_mul_f32_e32 v154, s50, v118
	v_mul_f32_e32 v155, s50, v119
	v_mul_f32_e32 v152, s50, v120
	v_mul_f32_e32 v153, s50, v121
	v_lshl_add_u64 v[76:77], v[146:147], 1, v[90:91]
	v_cvt_pk_bf16_f32 v150, v150, v151
	v_cvt_pk_bf16_f32 v151, v124, v125
	v_cvt_pk_bf16_f32 v152, v152, v153
	v_cvt_pk_bf16_f32 v153, v154, v155
	global_store_dwordx4 v[76:77], v[150:153], off

.LBB0_669:
	s_andn2_b64 vcc, exec, s[50:51]
	v_mov_b32_e32 v124, 0
	s_cbranch_vccnz .LBB0_671
	v_readlane_b32 s50, v242, 13
	v_readlane_b32 s51, v242, 14
	v_cvt_pk_bf16_f32 v76, v120, v121
	v_cvt_pk_bf16_f32 v77, v118, v119
	v_lshl_add_u64 v[74:75], s[50:51], 0, v[74:75]
	v_lshl_add_u64 v[124:125], v[146:147], 1, v[74:75]
	v_cvt_pk_bf16_f32 v74, v116, v117
	v_cvt_pk_bf16_f32 v75, v102, v103
	global_store_dwordx4 v[124:125], v[74:77], off
	s_nop 1
	v_mul_f32_e32 v74, v102, v102
	v_mul_f32_e32 v75, v103, v103
	v_mul_f32_e32 v76, v116, v116
	v_mul_f32_e32 v77, v117, v117
	s_nop 0
	v_pk_mov_b32 v[124:125], v[76:77], v[74:75] op_sel:[1,0]
	v_mov_b32_e32 v77, v75
	v_add_f32_e32 v74, v124, v76
	v_add_f32_e32 v75, v125, v77
	v_mul_f32_e32 v76, v118, v118
	v_mul_f32_e32 v77, v119, v119
	v_mul_f32_e32 v124, v120, v120
	v_mul_f32_e32 v125, v121, v121
	v_mov_b32_e32 v150, v76
	v_mov_b32_e32 v151, v124
	v_mov_b32_e32 v124, v77
	v_add_f32_e32 v76, v150, v124
	v_add_f32_e32 v77, v151, v125
	v_add_f32_e32 v74, v74, v75
	v_add_f32_e32 v74, v77, v74
	v_add_f32_e32 v124, v76, v74

.LBB0_672:
	v_lshl_add_u64 v[124:125], v[146:147], 1, v[84:85]
	v_cvt_pk_bf16_f32 v74, v116, v117
	v_cvt_pk_bf16_f32 v75, v102, v103
	v_cvt_pk_bf16_f32 v76, v120, v121
	v_cvt_pk_bf16_f32 v77, v118, v119
	global_store_dwordx4 v[124:125], v[74:77], off
	s_nop 1
	v_mul_f32_e32 v74, v102, v102
	v_mul_f32_e32 v75, v103, v103
	v_mul_f32_e32 v76, v116, v116
	v_mul_f32_e32 v77, v117, v117
	s_nop 0
	v_pk_mov_b32 v[124:125], v[76:77], v[74:75] op_sel:[1,0]
	v_mov_b32_e32 v77, v75
	v_add_f32_e32 v74, v124, v76
	v_add_f32_e32 v75, v125, v77
	v_mul_f32_e32 v76, v118, v118
	v_mul_f32_e32 v77, v119, v119
	v_mul_f32_e32 v124, v120, v120
	v_mul_f32_e32 v125, v121, v121
	v_mov_b32_e32 v150, v76
	v_mov_b32_e32 v151, v124
	v_mov_b32_e32 v124, v77
	v_add_f32_e32 v76, v150, v124
	v_add_f32_e32 v77, v151, v125
	v_add_f32_e32 v74, v74, v75
	v_add_f32_e32 v74, v77, v74
	v_add_f32_e32 v124, v76, v74

.LBB0_680:
	v_mov_b32_e32 v105, v104
	v_mov_b32_e32 v102, v104
	v_mov_b32_e32 v103, v104
	v_mul_f32_e32 v74, v72, v102
	v_mul_f32_e32 v75, v73, v103
	v_mul_f32_e32 v76, v70, v104
	v_mul_f32_e32 v77, v71, v105
	v_mul_f32_e32 v102, v68, v102
	v_mul_f32_e32 v103, v69, v103
	v_mul_f32_e32 v104, v66, v104
	v_mul_f32_e32 v105, v67, v105
	s_cmp_lt_i32 s62, 4
	s_mov_b64 s[50:51], -1
	s_cbranch_scc0 .LBB0_686
	s_andn2_b64 vcc, exec, s[50:51]
	s_cbranch_vccz .LBB0_704

.LBB0_686:
	s_cmp_lt_i32 s62, 6
	s_cbranch_scc1 .LBB0_695
	s_cmp_gt_i32 s62, 6
	s_cbranch_scc0 .LBB0_689
	v_max_f32_e32 v67, v104, v104
	v_max_f32_e32 v71, v102, v102
	v_max_f32_e32 v66, v76, v76
	v_max_f32_e32 v68, 0, v67
	v_max_f32_e32 v67, v77, v77
	v_max_f32_e32 v69, v105, v105
	v_max_f32_e32 v70, v74, v74
	v_max_f32_e32 v72, 0, v71
	v_max_f32_e32 v71, v75, v75
	v_max_f32_e32 v73, v103, v103
	v_max_f32_e32 v66, 0, v66
	v_max_f32_e32 v67, 0, v67
	v_max_f32_e32 v69, 0, v69
	v_max_f32_e32 v70, 0, v70
	v_max_f32_e32 v71, 0, v71
	v_max_f32_e32 v73, 0, v73
	v_mul_f32_e32 v66, v66, v66
	v_mul_f32_e32 v67, v67, v67
	v_mul_f32_e32 v68, v68, v68
	v_mul_f32_e32 v69, v69, v69
	v_mul_f32_e32 v70, v70, v70
	v_mul_f32_e32 v71, v71, v71
	v_mul_f32_e32 v72, v72, v72
	v_mul_f32_e32 v73, v73, v73
	v_ashrrev_i32_e32 v147, 31, v146
	v_lshl_add_u64 v[110:111], v[146:147], 1, v[110:111]
	v_cvt_pk_bf16_f32 v66, v66, v67
	v_cvt_pk_bf16_f32 v67, v70, v71
	v_cvt_pk_bf16_f32 v68, v68, v69
	v_cvt_pk_bf16_f32 v69, v72, v73
	global_store_dwordx4 v[110:111], v[66:69], off offset:256
	s_mov_b64 s[50:51], 0

.LBB0_693:
	s_waitcnt vmcnt(0)
	v_add_f32_e32 v108, v74, v68
	v_add_f32_e32 v109, v75, v69
	v_add_f32_e32 v110, v76, v66
	v_add_f32_e32 v111, v77, v67
	v_add_f32_e32 v72, v102, v72
	v_add_f32_e32 v73, v103, v73
	v_add_f32_e32 v70, v104, v70
	v_add_f32_e32 v71, v105, v71
	v_cvt_pk_bf16_f32 v66, v110, v111
	v_cvt_pk_bf16_f32 v67, v108, v109
	v_cvt_pk_bf16_f32 v68, v70, v71
	v_cvt_pk_bf16_f32 v69, v72, v73
	global_store_dwordx4 v[100:101], v[66:69], off
	v_mul_f32_e32 v70, v70, v70
	v_mul_f32_e32 v71, v71, v71
	s_nop 0
	v_mul_f32_e32 v66, v108, v108
	v_mul_f32_e32 v67, v109, v109
	v_mul_f32_e32 v68, v110, v110
	v_mul_f32_e32 v69, v111, v111
	s_nop 0
	v_pk_mov_b32 v[100:101], v[68:69], v[66:67] op_sel:[1,0]
	v_mov_b32_e32 v69, v67
	v_add_f32_e32 v66, v100, v68
	v_add_f32_e32 v67, v101, v69
	v_mul_f32_e32 v68, v72, v72
	v_mul_f32_e32 v69, v73, v73
	v_mov_b32_e32 v73, v70
	v_mov_b32_e32 v72, v68
	v_mov_b32_e32 v70, v69
	v_add_f32_e32 v68, v72, v70
	v_add_f32_e32 v69, v73, v71
	v_add_f32_e32 v66, v66, v67
	v_add_f32_e32 v66, v66, v69
	v_add_f32_e32 v66, v68, v66
	v_add_f32_e32 v66, v124, v66

.LBB0_699:
	s_waitcnt vmcnt(0)
	v_cvt_f32_ubyte3_e32 v109, v70
	v_cvt_f32_ubyte2_e32 v108, v70
	v_cvt_f32_ubyte1_e32 v111, v70
	v_cvt_f32_ubyte0_e32 v110, v70
	v_mul_f32_e32 v110, s26, v110
	v_mul_f32_e32 v111, s26, v111
	v_mul_f32_e32 v108, s26, v108
	v_mul_f32_e32 v109, s26, v109
	v_fma_f32 v98, v76, v110, v98
	v_fma_f32 v99, v77, v111, v99
	v_fma_f32 v100, v74, v108, v100
	v_fma_f32 v101, v75, v109, v101
	v_cvt_f32_ubyte3_e32 v109, v71
	v_cvt_f32_ubyte2_e32 v108, v71
	v_cvt_f32_ubyte1_e32 v111, v71
	v_cvt_f32_ubyte0_e32 v110, v71
	v_mul_f32_e32 v70, s26, v110
	v_mul_f32_e32 v71, s26, v111
	v_mul_f32_e32 v108, s26, v108
	v_mul_f32_e32 v109, s26, v109
	v_fma_f32 v70, v104, v70, v68
	v_fma_f32 v71, v105, v71, v69
	v_fma_f32 v72, v102, v108, v72
	v_fma_f32 v73, v103, v109, v73
	v_cvt_pk_bf16_f32 v68, v98, v99
	v_cvt_pk_bf16_f32 v69, v100, v101
	v_cvt_pk_bf16_f32 v70, v70, v71
	v_cvt_pk_bf16_f32 v71, v72, v73
	s_mov_b64 s[50:51], 0
	global_store_dwordx4 v[66:67], v[68:71], off

.LBB0_711:
	s_andn2_b64 vcc, exec, s[50:51]
	s_cbranch_vccnz .LBB0_716
	s_andn2_b64 vcc, exec, s[6:7]
	s_mov_b64 s[50:51], -1
	s_cbranch_vccnz .LBB0_714
	global_load_dwordx4 v[66:69], v[86:87], off offset:16
	global_load_dwordx4 v[70:73], v[86:87], off
	v_readlane_b32 s11, v243, 49
	s_lshl_b32 s84, s11, 1
	s_mov_b64 s[50:51], 0x6800380
	s_waitcnt vmcnt(0)
	v_mov_b32_e32 v93, v72
	v_mov_b32_e32 v72, v71
	v_mov_b32_e32 v92, v70
	v_mul_f32_e32 v70, v104, v72
	v_mul_f32_e32 v71, v105, v73
	v_mul_f32_e32 v72, v76, v72
	v_mul_f32_e32 v73, v77, v73
	v_fma_f32 v70, v76, v92, -v70
	v_fma_f32 v71, v77, v93, -v71
	v_fma_f32 v72, v104, v92, v72
	v_fma_f32 v73, v105, v93, v73
	v_mov_b32_e32 v93, v68
	v_mov_b32_e32 v68, v67
	v_mov_b32_e32 v92, v66
	v_mul_f32_e32 v66, v102, v68
	v_mul_f32_e32 v67, v103, v69
	v_mul_f32_e32 v68, v74, v68
	v_mul_f32_e32 v69, v75, v69
	v_fma_f32 v66, v74, v92, -v66
	v_fma_f32 v67, v75, v93, -v67
	v_fma_f32 v68, v102, v92, v68
	v_fma_f32 v69, v103, v93, v69
	v_cvt_pk_bf16_f32 v70, v70, v71
	v_cvt_pk_bf16_f32 v71, v66, v67
	v_cvt_pk_bf16_f32 v67, v68, v69
	v_lshl_add_u64 v[68:69], v[88:89], 0, s[84:85]
	v_lshl_add_u64 v[68:69], v[126:127], 1, v[68:69]
	v_cvt_pk_bf16_f32 v66, v72, v73
	v_lshl_add_u64 v[72:73], v[68:69], 0, s[50:51]
	v_add_co_u32_e32 v68, vcc, 0x6800000, v68
	s_mov_b64 s[50:51], 0
	s_nop 0
	v_addc_co_u32_e32 v69, vcc, 0, v69, vcc
	global_store_dwordx2 v[68:69], v[70:71], off offset:896
	global_store_dwordx2 v[72:73], v[66:67], off offset:32

.LBB0_717:
	s_andn2_b64 vcc, exec, s[50:51]
	s_cbranch_vccnz .LBB0_744
	s_cmp_lg_u32 s62, 1
	s_mov_b64 s[50:51], -1
	s_cbranch_scc0 .LBB0_737
	s_andn2_b64 vcc, exec, s[14:15]
	s_cbranch_vccnz .LBB0_734
	s_andn2_b64 vcc, exec, s[16:17]
	s_cbranch_vccnz .LBB0_730
	s_andn2_b64 vcc, exec, s[8:9]
	s_cbranch_vccnz .LBB0_727
	v_readlane_b32 s50, v242, 16
	v_readlane_b32 s51, v242, 17
	s_andn2_b64 vcc, exec, s[50:51]
	s_mov_b64 s[50:51], -1
	s_cbranch_vccnz .LBB0_724
	s_mov_b32 s50, 0x3e0293ee
	v_ashrrev_i32_e32 v147, 31, v146
	v_mul_f32_e32 v68, s50, v74
	v_mul_f32_e32 v69, s50, v75
	v_mul_f32_e32 v66, s50, v76
	v_mul_f32_e32 v67, s50, v77
	v_mul_f32_e32 v72, s50, v102
	v_mul_f32_e32 v73, s50, v103
	v_mul_f32_e32 v92, s50, v104
	v_mul_f32_e32 v93, s50, v105
	v_lshl_add_u64 v[70:71], v[146:147], 1, v[94:95]
	v_cvt_pk_bf16_f32 v66, v66, v67
	v_cvt_pk_bf16_f32 v67, v68, v69
	v_cvt_pk_bf16_f32 v68, v92, v93
	v_cvt_pk_bf16_f32 v69, v72, v73
	s_mov_b64 s[50:51], 0
	global_store_dwordx4 v[70:71], v[66:69], off offset:256

.LBB0_727:
	s_andn2_b64 vcc, exec, s[50:51]
	s_cbranch_vccnz .LBB0_729
	s_mov_b32 s50, 0x3e38aa3b
	v_ashrrev_i32_e32 v147, 31, v146
	v_mul_f32_e32 v68, s50, v74
	v_mul_f32_e32 v69, s50, v75
	v_mul_f32_e32 v66, s50, v76
	v_mul_f32_e32 v67, s50, v77
	v_mul_f32_e32 v72, s50, v102
	v_mul_f32_e32 v73, s50, v103
	v_mul_f32_e32 v82, s50, v104
	v_mul_f32_e32 v83, s50, v105
	v_lshl_add_u64 v[70:71], v[146:147], 1, v[90:91]
	v_cvt_pk_bf16_f32 v66, v66, v67
	v_cvt_pk_bf16_f32 v67, v68, v69
	v_cvt_pk_bf16_f32 v68, v82, v83
	v_cvt_pk_bf16_f32 v69, v72, v73
	global_store_dwordx4 v[70:71], v[66:69], off offset:256

.LBB0_730:
	s_andn2_b64 vcc, exec, s[50:51]
	s_cbranch_vccnz .LBB0_733
	v_readlane_b32 s50, v243, 47
	v_readlane_b32 s51, v243, 48
	s_andn2_b64 vcc, exec, s[50:51]
	s_cbranch_vccnz .LBB0_733
	global_load_dwordx4 v[66:69], v[86:87], off offset:16
	global_load_dwordx4 v[70:73], v[86:87], off
	v_lshl_add_u64 v[82:83], v[126:127], 1, v[88:89]
	s_brev_b32 s11, 16
	s_mov_b64 s[50:51], 0x8000080
	v_lshl_add_u64 v[88:89], v[82:83], 0, s[50:51]
	s_waitcnt vmcnt(0)
	v_mov_b32_e32 v87, v72
	v_mov_b32_e32 v72, v71
	v_mov_b32_e32 v86, v70
	v_mul_f32_e32 v70, v104, v72
	v_mul_f32_e32 v71, v105, v73
	v_mul_f32_e32 v72, v76, v72
	v_mul_f32_e32 v73, v77, v73
	v_fma_f32 v70, v76, v86, -v70
	v_fma_f32 v71, v77, v87, -v71
	v_fma_f32 v72, v104, v86, v72
	v_fma_f32 v73, v105, v87, v73
	v_mov_b32_e32 v87, v68
	v_mov_b32_e32 v68, v67
	v_mov_b32_e32 v86, v66
	v_mul_f32_e32 v66, v102, v68
	v_mul_f32_e32 v67, v103, v69
	v_mul_f32_e32 v68, v74, v68
	v_mul_f32_e32 v69, v75, v69
	v_fma_f32 v66, v74, v86, -v66
	v_fma_f32 v67, v75, v87, -v67
	v_fma_f32 v68, v102, v86, v68
	v_fma_f32 v69, v103, v87, v69
	v_cvt_pk_bf16_f32 v70, v70, v71
	v_cvt_pk_bf16_f32 v71, v66, v67
	v_cvt_pk_bf16_f32 v67, v68, v69
	v_add_co_u32_e32 v68, vcc, s11, v82
	v_cvt_pk_bf16_f32 v66, v72, v73
	s_nop 0
	v_addc_co_u32_e32 v69, vcc, 0, v83, vcc
	global_store_dwordx2 v[68:69], v[70:71], off offset:128
	global_store_dwordx2 v[88:89], v[66:67], off offset:32
	global_store_dwordx2 v[88:89], v[70:71], off offset:192
	global_store_dwordx2 v[88:89], v[66:67], off offset:224
	global_store_dwordx2 v[88:89], v[70:71], off offset:384
	global_store_dwordx2 v[88:89], v[66:67], off offset:416
	global_store_dwordx2 v[88:89], v[70:71], off offset:576
	global_store_dwordx2 v[88:89], v[66:67], off offset:608
	global_store_dwordx2 v[88:89], v[70:71], off offset:768
	global_store_dwordx2 v[88:89], v[66:67], off offset:800
	global_store_dwordx2 v[88:89], v[70:71], off offset:960
	global_store_dwordx2 v[88:89], v[66:67], off offset:992
	global_store_dwordx2 v[88:89], v[70:71], off offset:1152
	global_store_dwordx2 v[88:89], v[66:67], off offset:1184
	global_store_dwordx2 v[88:89], v[70:71], off offset:1344
	global_store_dwordx2 v[88:89], v[66:67], off offset:1376

.LBB0_734:
	s_andn2_b64 vcc, exec, s[50:51]
	v_mov_b32_e32 v66, v124
	s_cbranch_vccnz .LBB0_736
	v_ashrrev_i32_e32 v147, 31, v146
	v_lshl_add_u64 v[70:71], v[146:147], 1, v[84:85]
	v_cvt_pk_bf16_f32 v66, v76, v77
	v_cvt_pk_bf16_f32 v67, v74, v75
	v_cvt_pk_bf16_f32 v68, v104, v105
	v_cvt_pk_bf16_f32 v69, v102, v103
	global_store_dwordx4 v[70:71], v[66:69], off offset:256
	s_nop 1
	v_mul_f32_e32 v66, v74, v74
	v_mul_f32_e32 v67, v75, v75
	v_mul_f32_e32 v68, v76, v76
	v_mul_f32_e32 v69, v77, v77
	s_nop 0
	v_pk_mov_b32 v[70:71], v[68:69], v[66:67] op_sel:[1,0]
	v_mov_b32_e32 v69, v67
	v_add_f32_e32 v66, v70, v68
	v_add_f32_e32 v67, v71, v69
	v_mul_f32_e32 v68, v102, v102
	v_mul_f32_e32 v69, v103, v103
	v_mul_f32_e32 v70, v104, v104
	v_mul_f32_e32 v71, v105, v105
	v_mov_b32_e32 v72, v68
	v_mov_b32_e32 v73, v70
	v_mov_b32_e32 v70, v69
	v_add_f32_e32 v68, v72, v70
	v_add_f32_e32 v69, v73, v71
	v_add_f32_e32 v66, v66, v67
	v_add_f32_e32 v66, v69, v66
	v_add_f32_e32 v66, v68, v66
	v_add_f32_e32 v66, v66, v124

.LBB0_753:
	v_mul_f32_e32 v69, 0x3e16c740, v68
	v_lshlrev_b64 v[70:71], 11, v[66:67]
	v_cndmask_b32_e64 v88, v68, v69, s[52:53]
	v_lshlrev_b64 v[68:69], 10, v[66:67]
	v_lshl_add_u64 v[84:85], s[88:89], 0, v[70:71]
	v_lshlrev_b64 v[72:73], 12, v[66:67]
	v_lshl_add_u64 v[82:83], s[34:35], 0, v[70:71]
	v_lshlrev_b64 v[70:71], 13, v[66:67]
	v_lshl_add_u64 v[92:93], v[148:149], 0, v[72:73]
	v_lshl_add_u64 v[76:77], s[2:3], 0, v[68:69]
	v_lshl_add_u64 v[94:95], s[28:29], 0, v[70:71]
	v_mul_f32_e32 v86, v64, v88
	v_mul_f32_e32 v87, v65, v88
	v_mul_f32_e32 v98, v62, v88
	v_mul_f32_e32 v99, v63, v88
	v_mul_f32_e32 v100, v60, v88
	v_mul_f32_e32 v101, v61, v88
	v_mul_f32_e32 v102, v58, v88
	v_mul_f32_e32 v103, v59, v88
	s_cmp_lt_i32 s62, 4
	s_mov_b64 s[50:51], -1
	s_cbranch_scc1 .LBB0_772
	s_cmp_lt_i32 s62, 6
	s_cbranch_scc1 .LBB0_763
	s_cmp_gt_i32 s62, 6
	s_cbranch_scc0 .LBB0_757
	v_max_f32_e32 v59, v102, v102
	v_max_f32_e32 v63, v100, v100
	v_max_f32_e32 v58, v98, v98
	v_max_f32_e32 v60, 0, v59
	v_max_f32_e32 v59, v99, v99
	v_max_f32_e32 v61, v103, v103
	v_max_f32_e32 v62, v86, v86
	v_max_f32_e32 v64, 0, v63
	v_max_f32_e32 v63, v87, v87
	v_max_f32_e32 v65, v101, v101
	v_max_f32_e32 v58, 0, v58
	v_max_f32_e32 v59, 0, v59
	v_max_f32_e32 v61, 0, v61
	v_max_f32_e32 v62, 0, v62
	v_max_f32_e32 v63, 0, v63
	v_max_f32_e32 v65, 0, v65
	v_mul_f32_e32 v58, v58, v58
	v_mul_f32_e32 v59, v59, v59
	v_mul_f32_e32 v60, v60, v60
	v_mul_f32_e32 v61, v61, v61
	v_mul_f32_e32 v62, v62, v62
	v_mul_f32_e32 v63, v63, v63
	v_mul_f32_e32 v64, v64, v64
	v_mul_f32_e32 v65, v65, v65
	v_ashrrev_i32_e32 v147, 31, v146
	v_lshl_add_u64 v[70:71], v[146:147], 1, v[94:95]
	v_cvt_pk_bf16_f32 v58, v58, v59
	v_cvt_pk_bf16_f32 v59, v62, v63
	v_cvt_pk_bf16_f32 v60, v60, v61
	v_cvt_pk_bf16_f32 v61, v64, v65
	global_store_dwordx4 v[70:71], v[58:61], off
	s_mov_b64 s[50:51], 0

.LBB0_761:
	s_waitcnt vmcnt(0)
	v_add_f32_e32 v72, v86, v60
	v_add_f32_e32 v73, v87, v61
	v_add_f32_e32 v74, v98, v58
	v_add_f32_e32 v75, v99, v59
	v_add_f32_e32 v64, v100, v64
	v_add_f32_e32 v65, v101, v65
	v_add_f32_e32 v62, v102, v62
	v_add_f32_e32 v63, v103, v63
	v_cvt_pk_bf16_f32 v58, v74, v75
	v_cvt_pk_bf16_f32 v59, v72, v73
	v_cvt_pk_bf16_f32 v60, v62, v63
	v_cvt_pk_bf16_f32 v61, v64, v65
	global_store_dwordx4 v[70:71], v[58:61], off
	v_mul_f32_e32 v62, v62, v62
	v_mul_f32_e32 v63, v63, v63
	s_nop 0
	v_mul_f32_e32 v58, v72, v72
	v_mul_f32_e32 v59, v73, v73
	v_mul_f32_e32 v60, v74, v74
	v_mul_f32_e32 v61, v75, v75
	s_nop 0
	v_pk_mov_b32 v[70:71], v[60:61], v[58:59] op_sel:[1,0]
	v_mov_b32_e32 v61, v59
	v_add_f32_e32 v58, v70, v60
	v_add_f32_e32 v59, v71, v61
	v_mul_f32_e32 v60, v64, v64
	v_mul_f32_e32 v61, v65, v65
	v_mov_b32_e32 v65, v62
	v_mov_b32_e32 v64, v60
	v_mov_b32_e32 v62, v61
	v_add_f32_e32 v60, v64, v62
	v_add_f32_e32 v61, v65, v63
	v_add_f32_e32 v58, v58, v59
	v_add_f32_e32 v58, v58, v61
	v_add_f32_e32 v104, v60, v58

.LBB0_767:
	s_waitcnt vmcnt(0)
	v_cvt_f32_ubyte3_e32 v75, v62
	v_cvt_f32_ubyte2_e32 v74, v62
	v_cvt_f32_ubyte1_e32 v79, v62
	v_cvt_f32_ubyte0_e32 v78, v62
	v_mul_f32_e32 v78, s26, v78
	v_mul_f32_e32 v79, s26, v79
	v_mul_f32_e32 v74, s26, v74
	v_mul_f32_e32 v75, s26, v75
	v_fma_f32 v70, v98, v78, v70
	v_fma_f32 v71, v99, v79, v71
	v_fma_f32 v72, v86, v74, v72
	v_fma_f32 v73, v87, v75, v73
	v_cvt_f32_ubyte3_e32 v75, v63
	v_cvt_f32_ubyte2_e32 v74, v63
	v_cvt_f32_ubyte1_e32 v79, v63
	v_cvt_f32_ubyte0_e32 v78, v63
	v_mul_f32_e32 v62, s26, v78
	v_mul_f32_e32 v63, s26, v79
	v_mul_f32_e32 v74, s26, v74
	v_mul_f32_e32 v75, s26, v75
	v_fma_f32 v62, v102, v62, v60
	v_fma_f32 v63, v103, v63, v61
	v_fma_f32 v64, v100, v74, v64
	v_fma_f32 v65, v101, v75, v65
	v_cvt_pk_bf16_f32 v60, v70, v71
	v_cvt_pk_bf16_f32 v61, v72, v73
	v_cvt_pk_bf16_f32 v62, v62, v63
	v_cvt_pk_bf16_f32 v63, v64, v65
	s_mov_b64 s[50:51], 0
	global_store_dwordx4 v[58:59], v[60:63], off

.LBB0_780:
	s_andn2_b64 vcc, exec, s[50:51]
	s_cbranch_vccnz .LBB0_785
	s_andn2_b64 vcc, exec, s[6:7]
	s_mov_b64 s[50:51], -1
	s_cbranch_vccnz .LBB0_783
	global_load_dwordx4 v[58:61], v[70:71], off offset:16
	global_load_dwordx4 v[104:107], v[70:71], off
	v_readlane_b32 s11, v243, 49
	s_lshl_b32 s84, s11, 1
	s_mov_b64 s[50:51], 0x6800080
	s_waitcnt vmcnt(0)
	v_mov_b32_e32 v109, v106
	v_mov_b32_e32 v106, v105
	v_mov_b32_e32 v108, v104
	v_mul_f32_e32 v104, v102, v106
	v_mul_f32_e32 v105, v103, v107
	v_mul_f32_e32 v106, v98, v106
	v_mul_f32_e32 v107, v99, v107
	v_fma_f32 v104, v98, v108, -v104
	v_fma_f32 v105, v99, v109, -v105
	v_fma_f32 v106, v102, v108, v106
	v_fma_f32 v107, v103, v109, v107
	v_mov_b32_e32 v109, v60
	v_mov_b32_e32 v60, v59
	v_mov_b32_e32 v108, v58
	v_mul_f32_e32 v58, v100, v60
	v_mul_f32_e32 v59, v101, v61
	v_mul_f32_e32 v60, v86, v60
	v_mul_f32_e32 v61, v87, v61
	v_fma_f32 v58, v86, v108, -v58
	v_fma_f32 v59, v87, v109, -v59
	v_fma_f32 v60, v100, v108, v60
	v_fma_f32 v61, v101, v109, v61
	v_cvt_pk_bf16_f32 v104, v104, v105
	v_cvt_pk_bf16_f32 v105, v58, v59
	v_cvt_pk_bf16_f32 v59, v60, v61
	v_lshl_add_u64 v[60:61], v[72:73], 0, s[84:85]
	v_lshl_add_u64 v[60:61], v[126:127], 1, v[60:61]
	v_cvt_pk_bf16_f32 v58, v106, v107
	v_lshl_add_u64 v[106:107], v[60:61], 0, s[50:51]
	v_add_co_u32_e32 v60, vcc, 0x6800000, v60
	s_mov_b64 s[50:51], 0
	s_nop 0
	v_addc_co_u32_e32 v61, vcc, 0, v61, vcc
	global_store_dwordx2 v[60:61], v[104:105], off offset:128
	global_store_dwordx2 v[106:107], v[58:59], off offset:32

.LBB0_786:
	s_andn2_b64 vcc, exec, s[50:51]
	v_mov_b32_e32 v104, 0
	s_cbranch_vccnz .LBB0_810
	s_cmp_lg_u32 s62, 1
	s_mov_b64 s[50:51], -1
	s_cbranch_scc0 .LBB0_804
	s_andn2_b64 vcc, exec, s[14:15]
	v_ashrrev_i32_e32 v147, 31, v146
	s_cbranch_vccnz .LBB0_1283
	v_lshlrev_b64 v[58:59], 8, v[66:67]
	s_andn2_b64 vcc, exec, s[16:17]
	s_cbranch_vccnz .LBB0_799
	s_andn2_b64 vcc, exec, s[8:9]
	s_cbranch_vccnz .LBB0_796
	v_readlane_b32 s50, v242, 16
	v_readlane_b32 s51, v242, 17
	s_andn2_b64 vcc, exec, s[50:51]
	s_mov_b64 s[50:51], -1
	s_cbranch_vccnz .LBB0_793
	s_mov_b32 s50, 0x3e0293ee
	v_mul_f32_e32 v106, s50, v86
	v_mul_f32_e32 v107, s50, v87
	v_mul_f32_e32 v104, s50, v98
	v_mul_f32_e32 v105, s50, v99
	v_mul_f32_e32 v108, s50, v100
	v_mul_f32_e32 v109, s50, v101
	v_mul_f32_e32 v110, s50, v102
	v_mul_f32_e32 v111, s50, v103
	v_lshl_add_u64 v[60:61], v[146:147], 1, v[78:79]
	v_cvt_pk_bf16_f32 v104, v104, v105
	v_cvt_pk_bf16_f32 v105, v106, v107
	v_cvt_pk_bf16_f32 v106, v110, v111
	v_cvt_pk_bf16_f32 v107, v108, v109
	s_mov_b64 s[50:51], 0
	global_store_dwordx4 v[60:61], v[104:107], off

.LBB0_796:
	s_andn2_b64 vcc, exec, s[50:51]
	s_cbranch_vccnz .LBB0_798
	s_mov_b32 s50, 0x3e38aa3b
	v_mul_f32_e32 v106, s50, v86
	v_mul_f32_e32 v107, s50, v87
	v_mul_f32_e32 v104, s50, v98
	v_mul_f32_e32 v105, s50, v99
	v_mul_f32_e32 v108, s50, v100
	v_mul_f32_e32 v109, s50, v101
	v_mul_f32_e32 v110, s50, v102
	v_mul_f32_e32 v111, s50, v103
	v_lshl_add_u64 v[60:61], v[146:147], 1, v[74:75]
	v_cvt_pk_bf16_f32 v104, v104, v105
	v_cvt_pk_bf16_f32 v105, v106, v107
	v_cvt_pk_bf16_f32 v106, v110, v111
	v_cvt_pk_bf16_f32 v107, v108, v109
	global_store_dwordx4 v[60:61], v[104:107], off

.LBB0_799:
	s_andn2_b64 vcc, exec, s[50:51]
	v_mov_b32_e32 v104, 0
	s_cbranch_vccnz .LBB0_801
	v_readlane_b32 s50, v242, 13
	v_readlane_b32 s51, v242, 14
	v_cvt_pk_bf16_f32 v60, v102, v103
	v_cvt_pk_bf16_f32 v61, v100, v101
	v_lshl_add_u64 v[58:59], s[50:51], 0, v[58:59]
	v_lshl_add_u64 v[104:105], v[146:147], 1, v[58:59]
	v_cvt_pk_bf16_f32 v58, v98, v99
	v_cvt_pk_bf16_f32 v59, v86, v87
	global_store_dwordx4 v[104:105], v[58:61], off
	s_nop 1
	v_mul_f32_e32 v58, v86, v86
	v_mul_f32_e32 v59, v87, v87
	v_mul_f32_e32 v60, v98, v98
	v_mul_f32_e32 v61, v99, v99
	s_nop 0
	v_pk_mov_b32 v[104:105], v[60:61], v[58:59] op_sel:[1,0]
	v_mov_b32_e32 v61, v59
	v_add_f32_e32 v58, v104, v60
	v_add_f32_e32 v59, v105, v61
	v_mul_f32_e32 v60, v100, v100
	v_mul_f32_e32 v61, v101, v101
	v_mul_f32_e32 v104, v102, v102
	v_mul_f32_e32 v105, v103, v103
	v_mov_b32_e32 v106, v60
	v_mov_b32_e32 v107, v104
	v_mov_b32_e32 v104, v61
	v_add_f32_e32 v60, v106, v104
	v_add_f32_e32 v61, v107, v105
	v_add_f32_e32 v58, v58, v59
	v_add_f32_e32 v58, v61, v58
	v_add_f32_e32 v104, v60, v58

.LBB0_802:
	v_lshl_add_u64 v[104:105], v[146:147], 1, v[68:69]
	v_cvt_pk_bf16_f32 v58, v98, v99
	v_cvt_pk_bf16_f32 v59, v86, v87
	v_cvt_pk_bf16_f32 v60, v102, v103
	v_cvt_pk_bf16_f32 v61, v100, v101
	global_store_dwordx4 v[104:105], v[58:61], off
	s_nop 1
	v_mul_f32_e32 v58, v86, v86
	v_mul_f32_e32 v59, v87, v87
	v_mul_f32_e32 v60, v98, v98
	v_mul_f32_e32 v61, v99, v99
	s_nop 0
	v_pk_mov_b32 v[104:105], v[60:61], v[58:59] op_sel:[1,0]
	v_mov_b32_e32 v61, v59
	v_add_f32_e32 v58, v104, v60
	v_add_f32_e32 v59, v105, v61
	v_mul_f32_e32 v60, v100, v100
	v_mul_f32_e32 v61, v101, v101
	v_mul_f32_e32 v104, v102, v102
	v_mul_f32_e32 v105, v103, v103
	v_mov_b32_e32 v106, v60
	v_mov_b32_e32 v107, v104
	v_mov_b32_e32 v104, v61
	v_add_f32_e32 v60, v106, v104
	v_add_f32_e32 v61, v107, v105
	v_add_f32_e32 v58, v58, v59
	v_add_f32_e32 v58, v61, v58
	v_add_f32_e32 v104, v60, v58

.LBB0_810:
	v_mov_b32_e32 v89, v88
	v_mov_b32_e32 v86, v88
	v_mov_b32_e32 v87, v88
	v_mul_f32_e32 v58, v56, v86
	v_mul_f32_e32 v59, v57, v87
	v_mul_f32_e32 v60, v54, v88
	v_mul_f32_e32 v61, v55, v89
	v_mul_f32_e32 v86, v52, v86
	v_mul_f32_e32 v87, v53, v87
	v_mul_f32_e32 v88, v50, v88
	v_mul_f32_e32 v89, v51, v89
	s_cmp_lt_i32 s62, 4
	s_mov_b64 s[50:51], -1
	s_cbranch_scc0 .LBB0_816
	s_andn2_b64 vcc, exec, s[50:51]
	s_cbranch_vccz .LBB0_834

.LBB0_816:
	s_cmp_lt_i32 s62, 6
	s_cbranch_scc1 .LBB0_825
	s_cmp_gt_i32 s62, 6
	s_cbranch_scc0 .LBB0_819
	v_max_f32_e32 v51, v88, v88
	v_max_f32_e32 v55, v86, v86
	v_max_f32_e32 v50, v60, v60
	v_max_f32_e32 v52, 0, v51
	v_max_f32_e32 v51, v61, v61
	v_max_f32_e32 v53, v89, v89
	v_max_f32_e32 v54, v58, v58
	v_max_f32_e32 v56, 0, v55
	v_max_f32_e32 v55, v59, v59
	v_max_f32_e32 v57, v87, v87
	v_max_f32_e32 v50, 0, v50
	v_max_f32_e32 v51, 0, v51
	v_max_f32_e32 v53, 0, v53
	v_max_f32_e32 v54, 0, v54
	v_max_f32_e32 v55, 0, v55
	v_max_f32_e32 v57, 0, v57
	v_mul_f32_e32 v50, v50, v50
	v_mul_f32_e32 v51, v51, v51
	v_mul_f32_e32 v52, v52, v52
	v_mul_f32_e32 v53, v53, v53
	v_mul_f32_e32 v54, v54, v54
	v_mul_f32_e32 v55, v55, v55
	v_mul_f32_e32 v56, v56, v56
	v_mul_f32_e32 v57, v57, v57
	v_ashrrev_i32_e32 v147, 31, v146
	v_lshl_add_u64 v[94:95], v[146:147], 1, v[94:95]
	v_cvt_pk_bf16_f32 v50, v50, v51
	v_cvt_pk_bf16_f32 v51, v54, v55
	v_cvt_pk_bf16_f32 v52, v52, v53
	v_cvt_pk_bf16_f32 v53, v56, v57
	global_store_dwordx4 v[94:95], v[50:53], off offset:256
	s_mov_b64 s[50:51], 0

.LBB0_823:
	s_waitcnt vmcnt(0)
	v_add_f32_e32 v92, v58, v52
	v_add_f32_e32 v93, v59, v53
	v_add_f32_e32 v94, v60, v50
	v_add_f32_e32 v95, v61, v51
	v_add_f32_e32 v56, v86, v56
	v_add_f32_e32 v57, v87, v57
	v_add_f32_e32 v54, v88, v54
	v_add_f32_e32 v55, v89, v55
	v_cvt_pk_bf16_f32 v50, v94, v95
	v_cvt_pk_bf16_f32 v51, v92, v93
	v_cvt_pk_bf16_f32 v52, v54, v55
	v_cvt_pk_bf16_f32 v53, v56, v57
	global_store_dwordx4 v[84:85], v[50:53], off
	v_mul_f32_e32 v54, v54, v54
	v_mul_f32_e32 v55, v55, v55
	s_nop 0
	v_mul_f32_e32 v50, v92, v92
	v_mul_f32_e32 v51, v93, v93
	v_mul_f32_e32 v52, v94, v94
	v_mul_f32_e32 v53, v95, v95
	s_nop 0
	v_pk_mov_b32 v[84:85], v[52:53], v[50:51] op_sel:[1,0]
	v_mov_b32_e32 v53, v51
	v_add_f32_e32 v50, v84, v52
	v_add_f32_e32 v51, v85, v53
	v_mul_f32_e32 v52, v56, v56
	v_mul_f32_e32 v53, v57, v57
	v_mov_b32_e32 v57, v54
	v_mov_b32_e32 v56, v52
	v_mov_b32_e32 v54, v53
	v_add_f32_e32 v52, v56, v54
	v_add_f32_e32 v53, v57, v55
	v_add_f32_e32 v50, v50, v51
	v_add_f32_e32 v50, v50, v53
	v_add_f32_e32 v50, v52, v50
	v_add_f32_e32 v50, v104, v50

.LBB0_829:
	s_waitcnt vmcnt(0)
	v_cvt_f32_ubyte3_e32 v93, v54
	v_cvt_f32_ubyte2_e32 v92, v54
	v_cvt_f32_ubyte1_e32 v95, v54
	v_cvt_f32_ubyte0_e32 v94, v54
	v_mul_f32_e32 v94, s26, v94
	v_mul_f32_e32 v95, s26, v95
	v_mul_f32_e32 v92, s26, v92
	v_mul_f32_e32 v93, s26, v93
	v_fma_f32 v82, v60, v94, v82
	v_fma_f32 v83, v61, v95, v83
	v_fma_f32 v84, v58, v92, v84
	v_fma_f32 v85, v59, v93, v85
	v_cvt_f32_ubyte3_e32 v93, v55
	v_cvt_f32_ubyte2_e32 v92, v55
	v_cvt_f32_ubyte1_e32 v95, v55
	v_cvt_f32_ubyte0_e32 v94, v55
	v_mul_f32_e32 v54, s26, v94
	v_mul_f32_e32 v55, s26, v95
	v_mul_f32_e32 v92, s26, v92
	v_mul_f32_e32 v93, s26, v93
	v_fma_f32 v54, v88, v54, v52
	v_fma_f32 v55, v89, v55, v53
	v_fma_f32 v56, v86, v92, v56
	v_fma_f32 v57, v87, v93, v57
	v_cvt_pk_bf16_f32 v52, v82, v83
	v_cvt_pk_bf16_f32 v53, v84, v85
	v_cvt_pk_bf16_f32 v54, v54, v55
	v_cvt_pk_bf16_f32 v55, v56, v57
	s_mov_b64 s[50:51], 0
	global_store_dwordx4 v[50:51], v[52:55], off

.LBB0_841:
	s_andn2_b64 vcc, exec, s[50:51]
	s_cbranch_vccnz .LBB0_846
	s_andn2_b64 vcc, exec, s[6:7]
	s_mov_b64 s[50:51], -1
	s_cbranch_vccnz .LBB0_844
	global_load_dwordx4 v[50:53], v[70:71], off offset:16
	global_load_dwordx4 v[54:57], v[70:71], off
	v_readlane_b32 s11, v243, 49
	s_lshl_b32 s84, s11, 1
	s_mov_b64 s[50:51], 0x6800380
	s_waitcnt vmcnt(0)
	v_mov_b32_e32 v77, v56
	v_mov_b32_e32 v56, v55
	v_mov_b32_e32 v76, v54
	v_mul_f32_e32 v54, v88, v56
	v_mul_f32_e32 v55, v89, v57
	v_mul_f32_e32 v56, v60, v56
	v_mul_f32_e32 v57, v61, v57
	v_fma_f32 v54, v60, v76, -v54
	v_fma_f32 v55, v61, v77, -v55
	v_fma_f32 v56, v88, v76, v56
	v_fma_f32 v57, v89, v77, v57
	v_mov_b32_e32 v77, v52
	v_mov_b32_e32 v52, v51
	v_mov_b32_e32 v76, v50
	v_mul_f32_e32 v50, v86, v52
	v_mul_f32_e32 v51, v87, v53
	v_mul_f32_e32 v52, v58, v52
	v_mul_f32_e32 v53, v59, v53
	v_fma_f32 v50, v58, v76, -v50
	v_fma_f32 v51, v59, v77, -v51
	v_fma_f32 v52, v86, v76, v52
	v_fma_f32 v53, v87, v77, v53
	v_cvt_pk_bf16_f32 v54, v54, v55
	v_cvt_pk_bf16_f32 v55, v50, v51
	v_cvt_pk_bf16_f32 v51, v52, v53
	v_lshl_add_u64 v[52:53], v[72:73], 0, s[84:85]
	v_lshl_add_u64 v[52:53], v[126:127], 1, v[52:53]
	v_cvt_pk_bf16_f32 v50, v56, v57
	v_lshl_add_u64 v[56:57], v[52:53], 0, s[50:51]
	v_add_co_u32_e32 v52, vcc, 0x6800000, v52
	s_mov_b64 s[50:51], 0
	s_nop 0
	v_addc_co_u32_e32 v53, vcc, 0, v53, vcc
	global_store_dwordx2 v[52:53], v[54:55], off offset:896
	global_store_dwordx2 v[56:57], v[50:51], off offset:32

.LBB0_847:
	s_andn2_b64 vcc, exec, s[50:51]
	s_cbranch_vccnz .LBB0_874
	s_cmp_lg_u32 s62, 1
	s_mov_b64 s[50:51], -1
	s_cbranch_scc0 .LBB0_867
	s_andn2_b64 vcc, exec, s[14:15]
	s_cbranch_vccnz .LBB0_864
	s_andn2_b64 vcc, exec, s[16:17]
	s_cbranch_vccnz .LBB0_860
	s_andn2_b64 vcc, exec, s[8:9]
	s_cbranch_vccnz .LBB0_857
	v_readlane_b32 s50, v242, 16
	v_readlane_b32 s51, v242, 17
	s_andn2_b64 vcc, exec, s[50:51]
	s_mov_b64 s[50:51], -1
	s_cbranch_vccnz .LBB0_854
	s_mov_b32 s50, 0x3e0293ee
	v_ashrrev_i32_e32 v147, 31, v146
	v_mul_f32_e32 v52, s50, v58
	v_mul_f32_e32 v53, s50, v59
	v_mul_f32_e32 v50, s50, v60
	v_mul_f32_e32 v51, s50, v61
	v_mul_f32_e32 v56, s50, v86
	v_mul_f32_e32 v57, s50, v87
	v_mul_f32_e32 v76, s50, v88
	v_mul_f32_e32 v77, s50, v89
	v_lshl_add_u64 v[54:55], v[146:147], 1, v[78:79]
	v_cvt_pk_bf16_f32 v50, v50, v51
	v_cvt_pk_bf16_f32 v51, v52, v53
	v_cvt_pk_bf16_f32 v52, v76, v77
	v_cvt_pk_bf16_f32 v53, v56, v57
	s_mov_b64 s[50:51], 0
	global_store_dwordx4 v[54:55], v[50:53], off offset:256

.LBB0_857:
	s_andn2_b64 vcc, exec, s[50:51]
	s_cbranch_vccnz .LBB0_859
	s_mov_b32 s50, 0x3e38aa3b
	v_ashrrev_i32_e32 v147, 31, v146
	v_mul_f32_e32 v52, s50, v58
	v_mul_f32_e32 v53, s50, v59
	v_mul_f32_e32 v50, s50, v60
	v_mul_f32_e32 v51, s50, v61
	v_mul_f32_e32 v56, s50, v86
	v_mul_f32_e32 v57, s50, v87
	v_mul_f32_e32 v66, s50, v88
	v_mul_f32_e32 v67, s50, v89
	v_lshl_add_u64 v[54:55], v[146:147], 1, v[74:75]
	v_cvt_pk_bf16_f32 v50, v50, v51
	v_cvt_pk_bf16_f32 v51, v52, v53
	v_cvt_pk_bf16_f32 v52, v66, v67
	v_cvt_pk_bf16_f32 v53, v56, v57
	global_store_dwordx4 v[54:55], v[50:53], off offset:256

.LBB0_860:
	s_andn2_b64 vcc, exec, s[50:51]
	s_cbranch_vccnz .LBB0_863
	v_readlane_b32 s50, v243, 47
	v_readlane_b32 s51, v243, 48
	s_andn2_b64 vcc, exec, s[50:51]
	s_cbranch_vccnz .LBB0_863
	global_load_dwordx4 v[50:53], v[70:71], off offset:16
	global_load_dwordx4 v[54:57], v[70:71], off
	v_lshl_add_u64 v[66:67], v[126:127], 1, v[72:73]
	s_brev_b32 s11, 16
	s_mov_b64 s[50:51], 0x8000080
	v_lshl_add_u64 v[72:73], v[66:67], 0, s[50:51]
	s_waitcnt vmcnt(0)
	v_mov_b32_e32 v71, v56
	v_mov_b32_e32 v56, v55
	v_mov_b32_e32 v70, v54
	v_mul_f32_e32 v54, v88, v56
	v_mul_f32_e32 v55, v89, v57
	v_mul_f32_e32 v56, v60, v56
	v_mul_f32_e32 v57, v61, v57
	v_fma_f32 v54, v60, v70, -v54
	v_fma_f32 v55, v61, v71, -v55
	v_fma_f32 v56, v88, v70, v56
	v_fma_f32 v57, v89, v71, v57
	v_mov_b32_e32 v71, v52
	v_mov_b32_e32 v52, v51
	v_mov_b32_e32 v70, v50
	v_mul_f32_e32 v50, v86, v52
	v_mul_f32_e32 v51, v87, v53
	v_mul_f32_e32 v52, v58, v52
	v_mul_f32_e32 v53, v59, v53
	v_fma_f32 v50, v58, v70, -v50
	v_fma_f32 v51, v59, v71, -v51
	v_fma_f32 v52, v86, v70, v52
	v_fma_f32 v53, v87, v71, v53
	v_cvt_pk_bf16_f32 v54, v54, v55
	v_cvt_pk_bf16_f32 v55, v50, v51
	v_cvt_pk_bf16_f32 v51, v52, v53
	v_add_co_u32_e32 v52, vcc, s11, v66
	v_cvt_pk_bf16_f32 v50, v56, v57
	s_nop 0
	v_addc_co_u32_e32 v53, vcc, 0, v67, vcc
	global_store_dwordx2 v[52:53], v[54:55], off offset:128
	global_store_dwordx2 v[72:73], v[50:51], off offset:32
	global_store_dwordx2 v[72:73], v[54:55], off offset:192
	global_store_dwordx2 v[72:73], v[50:51], off offset:224
	global_store_dwordx2 v[72:73], v[54:55], off offset:384
	global_store_dwordx2 v[72:73], v[50:51], off offset:416
	global_store_dwordx2 v[72:73], v[54:55], off offset:576
	global_store_dwordx2 v[72:73], v[50:51], off offset:608
	global_store_dwordx2 v[72:73], v[54:55], off offset:768
	global_store_dwordx2 v[72:73], v[50:51], off offset:800
	global_store_dwordx2 v[72:73], v[54:55], off offset:960
	global_store_dwordx2 v[72:73], v[50:51], off offset:992
	global_store_dwordx2 v[72:73], v[54:55], off offset:1152
	global_store_dwordx2 v[72:73], v[50:51], off offset:1184
	global_store_dwordx2 v[72:73], v[54:55], off offset:1344
	global_store_dwordx2 v[72:73], v[50:51], off offset:1376

.LBB0_864:
	s_andn2_b64 vcc, exec, s[50:51]
	v_mov_b32_e32 v50, v104
	s_cbranch_vccnz .LBB0_866
	v_ashrrev_i32_e32 v147, 31, v146
	v_lshl_add_u64 v[54:55], v[146:147], 1, v[68:69]
	v_cvt_pk_bf16_f32 v50, v60, v61
	v_cvt_pk_bf16_f32 v51, v58, v59
	v_cvt_pk_bf16_f32 v52, v88, v89
	v_cvt_pk_bf16_f32 v53, v86, v87
	global_store_dwordx4 v[54:55], v[50:53], off offset:256
	s_nop 1
	v_mul_f32_e32 v50, v58, v58
	v_mul_f32_e32 v51, v59, v59
	v_mul_f32_e32 v52, v60, v60
	v_mul_f32_e32 v53, v61, v61
	s_nop 0
	v_pk_mov_b32 v[54:55], v[52:53], v[50:51] op_sel:[1,0]
	v_mov_b32_e32 v53, v51
	v_add_f32_e32 v50, v54, v52
	v_add_f32_e32 v51, v55, v53
	v_mul_f32_e32 v52, v86, v86
	v_mul_f32_e32 v53, v87, v87
	v_mul_f32_e32 v54, v88, v88
	v_mul_f32_e32 v55, v89, v89
	v_mov_b32_e32 v56, v52
	v_mov_b32_e32 v57, v54
	v_mov_b32_e32 v54, v53
	v_add_f32_e32 v52, v56, v54
	v_add_f32_e32 v53, v57, v55
	v_add_f32_e32 v50, v50, v51
	v_add_f32_e32 v50, v53, v50
	v_add_f32_e32 v50, v52, v50
	v_add_f32_e32 v50, v50, v104

.LBB0_883:
	v_mul_f32_e32 v53, 0x3e16c740, v52
	v_lshlrev_b64 v[54:55], 11, v[50:51]
	v_cndmask_b32_e64 v72, v52, v53, s[52:53]
	v_lshlrev_b64 v[52:53], 10, v[50:51]
	v_lshl_add_u64 v[68:69], s[88:89], 0, v[54:55]
	v_lshlrev_b64 v[56:57], 12, v[50:51]
	v_lshl_add_u64 v[66:67], s[34:35], 0, v[54:55]
	v_lshlrev_b64 v[54:55], 13, v[50:51]
	v_lshl_add_u64 v[76:77], v[148:149], 0, v[56:57]
	v_lshl_add_u64 v[60:61], s[2:3], 0, v[52:53]
	v_lshl_add_u64 v[78:79], s[28:29], 0, v[54:55]
	v_mul_f32_e32 v70, v48, v72
	v_mul_f32_e32 v71, v49, v72
	v_mul_f32_e32 v82, v46, v72
	v_mul_f32_e32 v83, v47, v72
	v_mul_f32_e32 v84, v44, v72
	v_mul_f32_e32 v85, v45, v72
	v_mul_f32_e32 v86, v42, v72
	v_mul_f32_e32 v87, v43, v72
	s_cmp_lt_i32 s62, 4
	s_mov_b64 s[50:51], -1
	s_cbranch_scc1 .LBB0_902
	s_cmp_lt_i32 s62, 6
	s_cbranch_scc1 .LBB0_893
	s_cmp_gt_i32 s62, 6
	s_cbranch_scc0 .LBB0_887
	v_max_f32_e32 v43, v86, v86
	v_max_f32_e32 v47, v84, v84
	v_max_f32_e32 v42, v82, v82
	v_max_f32_e32 v44, 0, v43
	v_max_f32_e32 v43, v83, v83
	v_max_f32_e32 v45, v87, v87
	v_max_f32_e32 v46, v70, v70
	v_max_f32_e32 v48, 0, v47
	v_max_f32_e32 v47, v71, v71
	v_max_f32_e32 v49, v85, v85
	v_max_f32_e32 v42, 0, v42
	v_max_f32_e32 v43, 0, v43
	v_max_f32_e32 v45, 0, v45
	v_max_f32_e32 v46, 0, v46
	v_max_f32_e32 v47, 0, v47
	v_max_f32_e32 v49, 0, v49
	v_mul_f32_e32 v42, v42, v42
	v_mul_f32_e32 v43, v43, v43
	v_mul_f32_e32 v44, v44, v44
	v_mul_f32_e32 v45, v45, v45
	v_mul_f32_e32 v46, v46, v46
	v_mul_f32_e32 v47, v47, v47
	v_mul_f32_e32 v48, v48, v48
	v_mul_f32_e32 v49, v49, v49
	v_ashrrev_i32_e32 v147, 31, v146
	v_lshl_add_u64 v[54:55], v[146:147], 1, v[78:79]
	v_cvt_pk_bf16_f32 v42, v42, v43
	v_cvt_pk_bf16_f32 v43, v46, v47
	v_cvt_pk_bf16_f32 v44, v44, v45
	v_cvt_pk_bf16_f32 v45, v48, v49
	global_store_dwordx4 v[54:55], v[42:45], off
	s_mov_b64 s[50:51], 0

.LBB0_891:
	s_waitcnt vmcnt(0)
	v_add_f32_e32 v56, v70, v44
	v_add_f32_e32 v57, v71, v45
	v_add_f32_e32 v58, v82, v42
	v_add_f32_e32 v59, v83, v43
	v_add_f32_e32 v48, v84, v48
	v_add_f32_e32 v49, v85, v49
	v_add_f32_e32 v46, v86, v46
	v_add_f32_e32 v47, v87, v47
	v_cvt_pk_bf16_f32 v42, v58, v59
	v_cvt_pk_bf16_f32 v43, v56, v57
	v_cvt_pk_bf16_f32 v44, v46, v47
	v_cvt_pk_bf16_f32 v45, v48, v49
	global_store_dwordx4 v[54:55], v[42:45], off
	v_mul_f32_e32 v46, v46, v46
	v_mul_f32_e32 v47, v47, v47
	s_nop 0
	v_mul_f32_e32 v42, v56, v56
	v_mul_f32_e32 v43, v57, v57
	v_mul_f32_e32 v44, v58, v58
	v_mul_f32_e32 v45, v59, v59
	s_nop 0
	v_pk_mov_b32 v[54:55], v[44:45], v[42:43] op_sel:[1,0]
	v_mov_b32_e32 v45, v43
	v_add_f32_e32 v42, v54, v44
	v_add_f32_e32 v43, v55, v45
	v_mul_f32_e32 v44, v48, v48
	v_mul_f32_e32 v45, v49, v49
	v_mov_b32_e32 v49, v46
	v_mov_b32_e32 v48, v44
	v_mov_b32_e32 v46, v45
	v_add_f32_e32 v44, v48, v46
	v_add_f32_e32 v45, v49, v47
	v_add_f32_e32 v42, v42, v43
	v_add_f32_e32 v42, v42, v45
	v_add_f32_e32 v88, v44, v42

.LBB0_897:
	s_waitcnt vmcnt(0)
	v_cvt_f32_ubyte3_e32 v59, v46
	v_cvt_f32_ubyte2_e32 v58, v46
	v_cvt_f32_ubyte1_e32 v63, v46
	v_cvt_f32_ubyte0_e32 v62, v46
	v_mul_f32_e32 v62, s26, v62
	v_mul_f32_e32 v63, s26, v63
	v_mul_f32_e32 v58, s26, v58
	v_mul_f32_e32 v59, s26, v59
	v_fma_f32 v54, v82, v62, v54
	v_fma_f32 v55, v83, v63, v55
	v_fma_f32 v56, v70, v58, v56
	v_fma_f32 v57, v71, v59, v57
	v_cvt_f32_ubyte3_e32 v59, v47
	v_cvt_f32_ubyte2_e32 v58, v47
	v_cvt_f32_ubyte1_e32 v63, v47
	v_cvt_f32_ubyte0_e32 v62, v47
	v_mul_f32_e32 v46, s26, v62
	v_mul_f32_e32 v47, s26, v63
	v_mul_f32_e32 v58, s26, v58
	v_mul_f32_e32 v59, s26, v59
	v_fma_f32 v46, v86, v46, v44
	v_fma_f32 v47, v87, v47, v45
	v_fma_f32 v48, v84, v58, v48
	v_fma_f32 v49, v85, v59, v49
	v_cvt_pk_bf16_f32 v44, v54, v55
	v_cvt_pk_bf16_f32 v45, v56, v57
	v_cvt_pk_bf16_f32 v46, v46, v47
	v_cvt_pk_bf16_f32 v47, v48, v49
	s_mov_b64 s[50:51], 0
	global_store_dwordx4 v[42:43], v[44:47], off

.LBB0_910:
	s_andn2_b64 vcc, exec, s[50:51]
	s_cbranch_vccnz .LBB0_915
	s_andn2_b64 vcc, exec, s[6:7]
	s_mov_b64 s[50:51], -1
	s_cbranch_vccnz .LBB0_913
	global_load_dwordx4 v[42:45], v[54:55], off offset:16
	global_load_dwordx4 v[88:91], v[54:55], off
	v_readlane_b32 s11, v243, 49
	s_lshl_b32 s84, s11, 1
	s_mov_b64 s[50:51], 0x6800080
	s_waitcnt vmcnt(0)
	v_mov_b32_e32 v93, v90
	v_mov_b32_e32 v90, v89
	v_mov_b32_e32 v92, v88
	v_mul_f32_e32 v88, v86, v90
	v_mul_f32_e32 v89, v87, v91
	v_mul_f32_e32 v90, v82, v90
	v_mul_f32_e32 v91, v83, v91
	v_fma_f32 v88, v82, v92, -v88
	v_fma_f32 v89, v83, v93, -v89
	v_fma_f32 v90, v86, v92, v90
	v_fma_f32 v91, v87, v93, v91
	v_mov_b32_e32 v93, v44
	v_mov_b32_e32 v44, v43
	v_mov_b32_e32 v92, v42
	v_mul_f32_e32 v42, v84, v44
	v_mul_f32_e32 v43, v85, v45
	v_mul_f32_e32 v44, v70, v44
	v_mul_f32_e32 v45, v71, v45
	v_fma_f32 v42, v70, v92, -v42
	v_fma_f32 v43, v71, v93, -v43
	v_fma_f32 v44, v84, v92, v44
	v_fma_f32 v45, v85, v93, v45
	v_cvt_pk_bf16_f32 v88, v88, v89
	v_cvt_pk_bf16_f32 v89, v42, v43
	v_cvt_pk_bf16_f32 v43, v44, v45
	v_lshl_add_u64 v[44:45], v[56:57], 0, s[84:85]
	v_lshl_add_u64 v[44:45], v[126:127], 1, v[44:45]
	v_cvt_pk_bf16_f32 v42, v90, v91
	v_lshl_add_u64 v[90:91], v[44:45], 0, s[50:51]
	v_add_co_u32_e32 v44, vcc, 0x6800000, v44
	s_mov_b64 s[50:51], 0
	s_nop 0
	v_addc_co_u32_e32 v45, vcc, 0, v45, vcc
	global_store_dwordx2 v[44:45], v[88:89], off offset:128
	global_store_dwordx2 v[90:91], v[42:43], off offset:32

.LBB0_916:
	s_andn2_b64 vcc, exec, s[50:51]
	v_mov_b32_e32 v88, 0
	s_cbranch_vccnz .LBB0_940
	s_cmp_lg_u32 s62, 1
	s_mov_b64 s[50:51], -1
	s_cbranch_scc0 .LBB0_934
	s_andn2_b64 vcc, exec, s[14:15]
	v_ashrrev_i32_e32 v147, 31, v146
	s_cbranch_vccnz .LBB0_1286
	v_lshlrev_b64 v[42:43], 8, v[50:51]
	s_andn2_b64 vcc, exec, s[16:17]
	s_cbranch_vccnz .LBB0_929
	s_andn2_b64 vcc, exec, s[8:9]
	s_cbranch_vccnz .LBB0_926
	v_readlane_b32 s50, v242, 16
	v_readlane_b32 s51, v242, 17
	s_andn2_b64 vcc, exec, s[50:51]
	s_mov_b64 s[50:51], -1
	s_cbranch_vccnz .LBB0_923
	s_mov_b32 s50, 0x3e0293ee
	v_mul_f32_e32 v90, s50, v70
	v_mul_f32_e32 v91, s50, v71
	v_mul_f32_e32 v88, s50, v82
	v_mul_f32_e32 v89, s50, v83
	v_mul_f32_e32 v92, s50, v84
	v_mul_f32_e32 v93, s50, v85
	v_mul_f32_e32 v94, s50, v86
	v_mul_f32_e32 v95, s50, v87
	v_lshl_add_u64 v[44:45], v[146:147], 1, v[62:63]
	v_cvt_pk_bf16_f32 v88, v88, v89
	v_cvt_pk_bf16_f32 v89, v90, v91
	v_cvt_pk_bf16_f32 v90, v94, v95
	v_cvt_pk_bf16_f32 v91, v92, v93
	s_mov_b64 s[50:51], 0
	global_store_dwordx4 v[44:45], v[88:91], off

.LBB0_926:
	s_andn2_b64 vcc, exec, s[50:51]
	s_cbranch_vccnz .LBB0_928
	s_mov_b32 s50, 0x3e38aa3b
	v_mul_f32_e32 v90, s50, v70
	v_mul_f32_e32 v91, s50, v71
	v_mul_f32_e32 v88, s50, v82
	v_mul_f32_e32 v89, s50, v83
	v_mul_f32_e32 v92, s50, v84
	v_mul_f32_e32 v93, s50, v85
	v_mul_f32_e32 v94, s50, v86
	v_mul_f32_e32 v95, s50, v87
	v_lshl_add_u64 v[44:45], v[146:147], 1, v[58:59]
	v_cvt_pk_bf16_f32 v88, v88, v89
	v_cvt_pk_bf16_f32 v89, v90, v91
	v_cvt_pk_bf16_f32 v90, v94, v95
	v_cvt_pk_bf16_f32 v91, v92, v93
	global_store_dwordx4 v[44:45], v[88:91], off

.LBB0_929:
	s_andn2_b64 vcc, exec, s[50:51]
	v_mov_b32_e32 v88, 0
	s_cbranch_vccnz .LBB0_931
	v_readlane_b32 s50, v242, 13
	v_readlane_b32 s51, v242, 14
	v_cvt_pk_bf16_f32 v44, v86, v87
	v_cvt_pk_bf16_f32 v45, v84, v85
	v_lshl_add_u64 v[42:43], s[50:51], 0, v[42:43]
	v_lshl_add_u64 v[88:89], v[146:147], 1, v[42:43]
	v_cvt_pk_bf16_f32 v42, v82, v83
	v_cvt_pk_bf16_f32 v43, v70, v71
	global_store_dwordx4 v[88:89], v[42:45], off
	s_nop 1
	v_mul_f32_e32 v42, v70, v70
	v_mul_f32_e32 v43, v71, v71
	v_mul_f32_e32 v44, v82, v82
	v_mul_f32_e32 v45, v83, v83
	s_nop 0
	v_pk_mov_b32 v[88:89], v[44:45], v[42:43] op_sel:[1,0]
	v_mov_b32_e32 v45, v43
	v_add_f32_e32 v42, v88, v44
	v_add_f32_e32 v43, v89, v45
	v_mul_f32_e32 v44, v84, v84
	v_mul_f32_e32 v45, v85, v85
	v_mul_f32_e32 v88, v86, v86
	v_mul_f32_e32 v89, v87, v87
	v_mov_b32_e32 v90, v44
	v_mov_b32_e32 v91, v88
	v_mov_b32_e32 v88, v45
	v_add_f32_e32 v44, v90, v88
	v_add_f32_e32 v45, v91, v89
	v_add_f32_e32 v42, v42, v43
	v_add_f32_e32 v42, v45, v42
	v_add_f32_e32 v88, v44, v42

.LBB0_932:
	v_lshl_add_u64 v[88:89], v[146:147], 1, v[52:53]
	v_cvt_pk_bf16_f32 v42, v82, v83
	v_cvt_pk_bf16_f32 v43, v70, v71
	v_cvt_pk_bf16_f32 v44, v86, v87
	v_cvt_pk_bf16_f32 v45, v84, v85
	global_store_dwordx4 v[88:89], v[42:45], off
	s_nop 1
	v_mul_f32_e32 v42, v70, v70
	v_mul_f32_e32 v43, v71, v71
	v_mul_f32_e32 v44, v82, v82
	v_mul_f32_e32 v45, v83, v83
	s_nop 0
	v_pk_mov_b32 v[88:89], v[44:45], v[42:43] op_sel:[1,0]
	v_mov_b32_e32 v45, v43
	v_add_f32_e32 v42, v88, v44
	v_add_f32_e32 v43, v89, v45
	v_mul_f32_e32 v44, v84, v84
	v_mul_f32_e32 v45, v85, v85
	v_mul_f32_e32 v88, v86, v86
	v_mul_f32_e32 v89, v87, v87
	v_mov_b32_e32 v90, v44
	v_mov_b32_e32 v91, v88
	v_mov_b32_e32 v88, v45
	v_add_f32_e32 v44, v90, v88
	v_add_f32_e32 v45, v91, v89
	v_add_f32_e32 v42, v42, v43
	v_add_f32_e32 v42, v45, v42
	v_add_f32_e32 v88, v44, v42

.LBB0_940:
	v_mov_b32_e32 v73, v72
	v_mov_b32_e32 v70, v72
	v_mov_b32_e32 v71, v72
	v_mul_f32_e32 v42, v40, v70
	v_mul_f32_e32 v43, v41, v71
	v_mul_f32_e32 v44, v38, v72
	v_mul_f32_e32 v45, v39, v73
	v_mul_f32_e32 v70, v36, v70
	v_mul_f32_e32 v71, v37, v71
	v_mul_f32_e32 v72, v34, v72
	v_mul_f32_e32 v73, v35, v73
	s_cmp_lt_i32 s62, 4
	s_mov_b64 s[50:51], -1
	s_cbranch_scc0 .LBB0_946
	s_andn2_b64 vcc, exec, s[50:51]
	s_cbranch_vccz .LBB0_964

.LBB0_946:
	s_cmp_lt_i32 s62, 6
	s_cbranch_scc1 .LBB0_955
	s_cmp_gt_i32 s62, 6
	s_cbranch_scc0 .LBB0_949
	v_max_f32_e32 v35, v72, v72
	v_max_f32_e32 v39, v70, v70
	v_max_f32_e32 v34, v44, v44
	v_max_f32_e32 v36, 0, v35
	v_max_f32_e32 v35, v45, v45
	v_max_f32_e32 v37, v73, v73
	v_max_f32_e32 v38, v42, v42
	v_max_f32_e32 v40, 0, v39
	v_max_f32_e32 v39, v43, v43
	v_max_f32_e32 v41, v71, v71
	v_max_f32_e32 v34, 0, v34
	v_max_f32_e32 v35, 0, v35
	v_max_f32_e32 v37, 0, v37
	v_max_f32_e32 v38, 0, v38
	v_max_f32_e32 v39, 0, v39
	v_max_f32_e32 v41, 0, v41
	v_mul_f32_e32 v34, v34, v34
	v_mul_f32_e32 v35, v35, v35
	v_mul_f32_e32 v36, v36, v36
	v_mul_f32_e32 v37, v37, v37
	v_mul_f32_e32 v38, v38, v38
	v_mul_f32_e32 v39, v39, v39
	v_mul_f32_e32 v40, v40, v40
	v_mul_f32_e32 v41, v41, v41
	v_ashrrev_i32_e32 v147, 31, v146
	v_lshl_add_u64 v[78:79], v[146:147], 1, v[78:79]
	v_cvt_pk_bf16_f32 v34, v34, v35
	v_cvt_pk_bf16_f32 v35, v38, v39
	v_cvt_pk_bf16_f32 v36, v36, v37
	v_cvt_pk_bf16_f32 v37, v40, v41
	global_store_dwordx4 v[78:79], v[34:37], off offset:256
	s_mov_b64 s[50:51], 0

.LBB0_953:
	s_waitcnt vmcnt(0)
	v_add_f32_e32 v76, v42, v36
	v_add_f32_e32 v77, v43, v37
	v_add_f32_e32 v78, v44, v34
	v_add_f32_e32 v79, v45, v35
	v_add_f32_e32 v40, v70, v40
	v_add_f32_e32 v41, v71, v41
	v_add_f32_e32 v38, v72, v38
	v_add_f32_e32 v39, v73, v39
	v_cvt_pk_bf16_f32 v34, v78, v79
	v_cvt_pk_bf16_f32 v35, v76, v77
	v_cvt_pk_bf16_f32 v36, v38, v39
	v_cvt_pk_bf16_f32 v37, v40, v41
	global_store_dwordx4 v[68:69], v[34:37], off
	v_mul_f32_e32 v38, v38, v38
	v_mul_f32_e32 v39, v39, v39
	s_nop 0
	v_mul_f32_e32 v34, v76, v76
	v_mul_f32_e32 v35, v77, v77
	v_mul_f32_e32 v36, v78, v78
	v_mul_f32_e32 v37, v79, v79
	s_nop 0
	v_pk_mov_b32 v[68:69], v[36:37], v[34:35] op_sel:[1,0]
	v_mov_b32_e32 v37, v35
	v_add_f32_e32 v34, v68, v36
	v_add_f32_e32 v35, v69, v37
	v_mul_f32_e32 v36, v40, v40
	v_mul_f32_e32 v37, v41, v41
	v_mov_b32_e32 v41, v38
	v_mov_b32_e32 v40, v36
	v_mov_b32_e32 v38, v37
	v_add_f32_e32 v36, v40, v38
	v_add_f32_e32 v37, v41, v39
	v_add_f32_e32 v34, v34, v35
	v_add_f32_e32 v34, v34, v37
	v_add_f32_e32 v34, v36, v34
	v_add_f32_e32 v34, v88, v34

.LBB0_959:
	s_waitcnt vmcnt(0)
	v_cvt_f32_ubyte3_e32 v77, v38
	v_cvt_f32_ubyte2_e32 v76, v38
	v_cvt_f32_ubyte1_e32 v79, v38
	v_cvt_f32_ubyte0_e32 v78, v38
	v_mul_f32_e32 v78, s26, v78
	v_mul_f32_e32 v79, s26, v79
	v_mul_f32_e32 v76, s26, v76
	v_mul_f32_e32 v77, s26, v77
	v_fma_f32 v66, v44, v78, v66
	v_fma_f32 v67, v45, v79, v67
	v_fma_f32 v68, v42, v76, v68
	v_fma_f32 v69, v43, v77, v69
	v_cvt_f32_ubyte3_e32 v77, v39
	v_cvt_f32_ubyte2_e32 v76, v39
	v_cvt_f32_ubyte1_e32 v79, v39
	v_cvt_f32_ubyte0_e32 v78, v39
	v_mul_f32_e32 v38, s26, v78
	v_mul_f32_e32 v39, s26, v79
	v_mul_f32_e32 v76, s26, v76
	v_mul_f32_e32 v77, s26, v77
	v_fma_f32 v38, v72, v38, v36
	v_fma_f32 v39, v73, v39, v37
	v_fma_f32 v40, v70, v76, v40
	v_fma_f32 v41, v71, v77, v41
	v_cvt_pk_bf16_f32 v36, v66, v67
	v_cvt_pk_bf16_f32 v37, v68, v69
	v_cvt_pk_bf16_f32 v38, v38, v39
	v_cvt_pk_bf16_f32 v39, v40, v41
	s_mov_b64 s[50:51], 0
	global_store_dwordx4 v[34:35], v[36:39], off

.LBB0_971:
	s_andn2_b64 vcc, exec, s[50:51]
	s_cbranch_vccnz .LBB0_976
	s_andn2_b64 vcc, exec, s[6:7]
	s_mov_b64 s[50:51], -1
	s_cbranch_vccnz .LBB0_974
	global_load_dwordx4 v[34:37], v[54:55], off offset:16
	global_load_dwordx4 v[38:41], v[54:55], off
	v_readlane_b32 s11, v243, 49
	s_lshl_b32 s84, s11, 1
	s_mov_b64 s[50:51], 0x6800380
	s_waitcnt vmcnt(0)
	v_mov_b32_e32 v61, v40
	v_mov_b32_e32 v40, v39
	v_mov_b32_e32 v60, v38
	v_mul_f32_e32 v38, v72, v40
	v_mul_f32_e32 v39, v73, v41
	v_mul_f32_e32 v40, v44, v40
	v_mul_f32_e32 v41, v45, v41
	v_fma_f32 v38, v44, v60, -v38
	v_fma_f32 v39, v45, v61, -v39
	v_fma_f32 v40, v72, v60, v40
	v_fma_f32 v41, v73, v61, v41
	v_mov_b32_e32 v61, v36
	v_mov_b32_e32 v36, v35
	v_mov_b32_e32 v60, v34
	v_mul_f32_e32 v34, v70, v36
	v_mul_f32_e32 v35, v71, v37
	v_mul_f32_e32 v36, v42, v36
	v_mul_f32_e32 v37, v43, v37
	v_fma_f32 v34, v42, v60, -v34
	v_fma_f32 v35, v43, v61, -v35
	v_fma_f32 v36, v70, v60, v36
	v_fma_f32 v37, v71, v61, v37
	v_cvt_pk_bf16_f32 v38, v38, v39
	v_cvt_pk_bf16_f32 v39, v34, v35
	v_cvt_pk_bf16_f32 v35, v36, v37
	v_lshl_add_u64 v[36:37], v[56:57], 0, s[84:85]
	v_lshl_add_u64 v[36:37], v[126:127], 1, v[36:37]
	v_cvt_pk_bf16_f32 v34, v40, v41
	v_lshl_add_u64 v[40:41], v[36:37], 0, s[50:51]
	v_add_co_u32_e32 v36, vcc, 0x6800000, v36
	s_mov_b64 s[50:51], 0
	s_nop 0
	v_addc_co_u32_e32 v37, vcc, 0, v37, vcc
	global_store_dwordx2 v[36:37], v[38:39], off offset:896
	global_store_dwordx2 v[40:41], v[34:35], off offset:32

.LBB0_977:
	s_andn2_b64 vcc, exec, s[50:51]
	s_cbranch_vccnz .LBB0_1004
	s_cmp_lg_u32 s62, 1
	s_mov_b64 s[50:51], -1
	s_cbranch_scc0 .LBB0_997
	s_andn2_b64 vcc, exec, s[14:15]
	s_cbranch_vccnz .LBB0_994
	s_andn2_b64 vcc, exec, s[16:17]
	s_cbranch_vccnz .LBB0_990
	s_andn2_b64 vcc, exec, s[8:9]
	s_cbranch_vccnz .LBB0_987
	v_readlane_b32 s50, v242, 16
	v_readlane_b32 s51, v242, 17
	s_andn2_b64 vcc, exec, s[50:51]
	s_mov_b64 s[50:51], -1
	s_cbranch_vccnz .LBB0_984
	s_mov_b32 s50, 0x3e0293ee
	v_ashrrev_i32_e32 v147, 31, v146
	v_mul_f32_e32 v36, s50, v42
	v_mul_f32_e32 v37, s50, v43
	v_mul_f32_e32 v34, s50, v44
	v_mul_f32_e32 v35, s50, v45
	v_mul_f32_e32 v40, s50, v70
	v_mul_f32_e32 v41, s50, v71
	v_mul_f32_e32 v60, s50, v72
	v_mul_f32_e32 v61, s50, v73
	v_lshl_add_u64 v[38:39], v[146:147], 1, v[62:63]
	v_cvt_pk_bf16_f32 v34, v34, v35
	v_cvt_pk_bf16_f32 v35, v36, v37
	v_cvt_pk_bf16_f32 v36, v60, v61
	v_cvt_pk_bf16_f32 v37, v40, v41
	s_mov_b64 s[50:51], 0
	global_store_dwordx4 v[38:39], v[34:37], off offset:256

.LBB0_987:
	s_andn2_b64 vcc, exec, s[50:51]
	s_cbranch_vccnz .LBB0_989
	s_mov_b32 s50, 0x3e38aa3b
	v_ashrrev_i32_e32 v147, 31, v146
	v_mul_f32_e32 v36, s50, v42
	v_mul_f32_e32 v37, s50, v43
	v_mul_f32_e32 v34, s50, v44
	v_mul_f32_e32 v35, s50, v45
	v_mul_f32_e32 v40, s50, v70
	v_mul_f32_e32 v41, s50, v71
	v_mul_f32_e32 v50, s50, v72
	v_mul_f32_e32 v51, s50, v73
	v_lshl_add_u64 v[38:39], v[146:147], 1, v[58:59]
	v_cvt_pk_bf16_f32 v34, v34, v35
	v_cvt_pk_bf16_f32 v35, v36, v37
	v_cvt_pk_bf16_f32 v36, v50, v51
	v_cvt_pk_bf16_f32 v37, v40, v41
	global_store_dwordx4 v[38:39], v[34:37], off offset:256

.LBB0_990:
	s_andn2_b64 vcc, exec, s[50:51]
	s_cbranch_vccnz .LBB0_993
	v_readlane_b32 s50, v243, 47
	v_readlane_b32 s51, v243, 48
	s_andn2_b64 vcc, exec, s[50:51]
	s_cbranch_vccnz .LBB0_993
	global_load_dwordx4 v[34:37], v[54:55], off offset:16
	global_load_dwordx4 v[38:41], v[54:55], off
	v_lshl_add_u64 v[50:51], v[126:127], 1, v[56:57]
	s_brev_b32 s11, 16
	s_mov_b64 s[50:51], 0x8000080
	v_lshl_add_u64 v[56:57], v[50:51], 0, s[50:51]
	s_waitcnt vmcnt(0)
	v_mov_b32_e32 v55, v40
	v_mov_b32_e32 v40, v39
	v_mov_b32_e32 v54, v38
	v_mul_f32_e32 v38, v72, v40
	v_mul_f32_e32 v39, v73, v41
	v_mul_f32_e32 v40, v44, v40
	v_mul_f32_e32 v41, v45, v41
	v_fma_f32 v38, v44, v54, -v38
	v_fma_f32 v39, v45, v55, -v39
	v_fma_f32 v40, v72, v54, v40
	v_fma_f32 v41, v73, v55, v41
	v_mov_b32_e32 v55, v36
	v_mov_b32_e32 v36, v35
	v_mov_b32_e32 v54, v34
	v_mul_f32_e32 v34, v70, v36
	v_mul_f32_e32 v35, v71, v37
	v_mul_f32_e32 v36, v42, v36
	v_mul_f32_e32 v37, v43, v37
	v_fma_f32 v34, v42, v54, -v34
	v_fma_f32 v35, v43, v55, -v35
	v_fma_f32 v36, v70, v54, v36
	v_fma_f32 v37, v71, v55, v37
	v_cvt_pk_bf16_f32 v38, v38, v39
	v_cvt_pk_bf16_f32 v39, v34, v35
	v_cvt_pk_bf16_f32 v35, v36, v37
	v_add_co_u32_e32 v36, vcc, s11, v50
	v_cvt_pk_bf16_f32 v34, v40, v41
	s_nop 0
	v_addc_co_u32_e32 v37, vcc, 0, v51, vcc
	global_store_dwordx2 v[36:37], v[38:39], off offset:128
	global_store_dwordx2 v[56:57], v[34:35], off offset:32
	global_store_dwordx2 v[56:57], v[38:39], off offset:192
	global_store_dwordx2 v[56:57], v[34:35], off offset:224
	global_store_dwordx2 v[56:57], v[38:39], off offset:384
	global_store_dwordx2 v[56:57], v[34:35], off offset:416
	global_store_dwordx2 v[56:57], v[38:39], off offset:576
	global_store_dwordx2 v[56:57], v[34:35], off offset:608
	global_store_dwordx2 v[56:57], v[38:39], off offset:768
	global_store_dwordx2 v[56:57], v[34:35], off offset:800
	global_store_dwordx2 v[56:57], v[38:39], off offset:960
	global_store_dwordx2 v[56:57], v[34:35], off offset:992
	global_store_dwordx2 v[56:57], v[38:39], off offset:1152
	global_store_dwordx2 v[56:57], v[34:35], off offset:1184
	global_store_dwordx2 v[56:57], v[38:39], off offset:1344
	global_store_dwordx2 v[56:57], v[34:35], off offset:1376

.LBB0_994:
	s_andn2_b64 vcc, exec, s[50:51]
	v_mov_b32_e32 v34, v88
	s_cbranch_vccnz .LBB0_996
	v_ashrrev_i32_e32 v147, 31, v146
	v_lshl_add_u64 v[38:39], v[146:147], 1, v[52:53]
	v_cvt_pk_bf16_f32 v34, v44, v45
	v_cvt_pk_bf16_f32 v35, v42, v43
	v_cvt_pk_bf16_f32 v36, v72, v73
	v_cvt_pk_bf16_f32 v37, v70, v71
	global_store_dwordx4 v[38:39], v[34:37], off offset:256
	s_nop 1
	v_mul_f32_e32 v34, v42, v42
	v_mul_f32_e32 v35, v43, v43
	v_mul_f32_e32 v36, v44, v44
	v_mul_f32_e32 v37, v45, v45
	s_nop 0
	v_pk_mov_b32 v[38:39], v[36:37], v[34:35] op_sel:[1,0]
	v_mov_b32_e32 v37, v35
	v_add_f32_e32 v34, v38, v36
	v_add_f32_e32 v35, v39, v37
	v_mul_f32_e32 v36, v70, v70
	v_mul_f32_e32 v37, v71, v71
	v_mul_f32_e32 v38, v72, v72
	v_mul_f32_e32 v39, v73, v73
	v_mov_b32_e32 v40, v36
	v_mov_b32_e32 v41, v38
	v_mov_b32_e32 v38, v37
	v_add_f32_e32 v36, v40, v38
	v_add_f32_e32 v37, v41, v39
	v_add_f32_e32 v34, v34, v35
	v_add_f32_e32 v34, v37, v34
	v_add_f32_e32 v34, v36, v34
	v_add_f32_e32 v34, v34, v88

.LBB0_1013:
	v_mul_f32_e32 v37, 0x3e16c740, v36
	v_lshlrev_b64 v[38:39], 11, v[34:35]
	v_cndmask_b32_e64 v56, v36, v37, s[52:53]
	v_lshlrev_b64 v[36:37], 10, v[34:35]
	v_lshl_add_u64 v[52:53], s[88:89], 0, v[38:39]
	v_lshlrev_b64 v[40:41], 12, v[34:35]
	v_lshl_add_u64 v[50:51], s[34:35], 0, v[38:39]
	v_lshlrev_b64 v[38:39], 13, v[34:35]
	v_lshl_add_u64 v[60:61], v[148:149], 0, v[40:41]
	v_lshl_add_u64 v[44:45], s[2:3], 0, v[36:37]
	v_lshl_add_u64 v[62:63], s[28:29], 0, v[38:39]
	v_mul_f32_e32 v54, v32, v56
	v_mul_f32_e32 v55, v33, v56
	v_mul_f32_e32 v66, v30, v56
	v_mul_f32_e32 v67, v31, v56
	v_mul_f32_e32 v68, v28, v56
	v_mul_f32_e32 v69, v29, v56
	v_mul_f32_e32 v70, v26, v56
	v_mul_f32_e32 v71, v27, v56
	s_cmp_lt_i32 s62, 4
	s_mov_b64 s[50:51], -1
	s_cbranch_scc1 .LBB0_1032
	s_cmp_lt_i32 s62, 6
	s_cbranch_scc1 .LBB0_1023
	s_cmp_gt_i32 s62, 6
	s_cbranch_scc0 .LBB0_1017
	v_max_f32_e32 v27, v70, v70
	v_max_f32_e32 v31, v68, v68
	v_max_f32_e32 v26, v66, v66
	v_max_f32_e32 v28, 0, v27
	v_max_f32_e32 v27, v67, v67
	v_max_f32_e32 v29, v71, v71
	v_max_f32_e32 v30, v54, v54
	v_max_f32_e32 v32, 0, v31
	v_max_f32_e32 v31, v55, v55
	v_max_f32_e32 v33, v69, v69
	v_max_f32_e32 v26, 0, v26
	v_max_f32_e32 v27, 0, v27
	v_max_f32_e32 v29, 0, v29
	v_max_f32_e32 v30, 0, v30
	v_max_f32_e32 v31, 0, v31
	v_max_f32_e32 v33, 0, v33
	v_mul_f32_e32 v26, v26, v26
	v_mul_f32_e32 v27, v27, v27
	v_mul_f32_e32 v28, v28, v28
	v_mul_f32_e32 v29, v29, v29
	v_mul_f32_e32 v30, v30, v30
	v_mul_f32_e32 v31, v31, v31
	v_mul_f32_e32 v32, v32, v32
	v_mul_f32_e32 v33, v33, v33
	v_ashrrev_i32_e32 v147, 31, v146
	v_lshl_add_u64 v[38:39], v[146:147], 1, v[62:63]
	v_cvt_pk_bf16_f32 v26, v26, v27
	v_cvt_pk_bf16_f32 v27, v30, v31
	v_cvt_pk_bf16_f32 v28, v28, v29
	v_cvt_pk_bf16_f32 v29, v32, v33
	global_store_dwordx4 v[38:39], v[26:29], off
	s_mov_b64 s[50:51], 0

.LBB0_1021:
	s_waitcnt vmcnt(0)
	v_add_f32_e32 v40, v54, v28
	v_add_f32_e32 v41, v55, v29
	v_add_f32_e32 v42, v66, v26
	v_add_f32_e32 v43, v67, v27
	v_add_f32_e32 v32, v68, v32
	v_add_f32_e32 v33, v69, v33
	v_add_f32_e32 v30, v70, v30
	v_add_f32_e32 v31, v71, v31
	v_cvt_pk_bf16_f32 v26, v42, v43
	v_cvt_pk_bf16_f32 v27, v40, v41
	v_cvt_pk_bf16_f32 v28, v30, v31
	v_cvt_pk_bf16_f32 v29, v32, v33
	global_store_dwordx4 v[38:39], v[26:29], off
	v_mul_f32_e32 v30, v30, v30
	v_mul_f32_e32 v31, v31, v31
	s_nop 0
	v_mul_f32_e32 v26, v40, v40
	v_mul_f32_e32 v27, v41, v41
	v_mul_f32_e32 v28, v42, v42
	v_mul_f32_e32 v29, v43, v43
	s_nop 0
	v_pk_mov_b32 v[38:39], v[28:29], v[26:27] op_sel:[1,0]
	v_mov_b32_e32 v29, v27
	v_add_f32_e32 v26, v38, v28
	v_add_f32_e32 v27, v39, v29
	v_mul_f32_e32 v28, v32, v32
	v_mul_f32_e32 v29, v33, v33
	v_mov_b32_e32 v33, v30
	v_mov_b32_e32 v32, v28
	v_mov_b32_e32 v30, v29
	v_add_f32_e32 v28, v32, v30
	v_add_f32_e32 v29, v33, v31
	v_add_f32_e32 v26, v26, v27
	v_add_f32_e32 v26, v26, v29
	v_add_f32_e32 v72, v28, v26

.LBB0_1027:
	s_waitcnt vmcnt(0)
	v_cvt_f32_ubyte3_e32 v43, v30
	v_cvt_f32_ubyte2_e32 v42, v30
	v_cvt_f32_ubyte1_e32 v47, v30
	v_cvt_f32_ubyte0_e32 v46, v30
	v_mul_f32_e32 v46, s26, v46
	v_mul_f32_e32 v47, s26, v47
	v_mul_f32_e32 v42, s26, v42
	v_mul_f32_e32 v43, s26, v43
	v_fma_f32 v38, v66, v46, v38
	v_fma_f32 v39, v67, v47, v39
	v_fma_f32 v40, v54, v42, v40
	v_fma_f32 v41, v55, v43, v41
	v_cvt_f32_ubyte3_e32 v43, v31
	v_cvt_f32_ubyte2_e32 v42, v31
	v_cvt_f32_ubyte1_e32 v47, v31
	v_cvt_f32_ubyte0_e32 v46, v31
	v_mul_f32_e32 v30, s26, v46
	v_mul_f32_e32 v31, s26, v47
	v_mul_f32_e32 v42, s26, v42
	v_mul_f32_e32 v43, s26, v43
	v_fma_f32 v30, v70, v30, v28
	v_fma_f32 v31, v71, v31, v29
	v_fma_f32 v32, v68, v42, v32
	v_fma_f32 v33, v69, v43, v33
	v_cvt_pk_bf16_f32 v28, v38, v39
	v_cvt_pk_bf16_f32 v29, v40, v41
	v_cvt_pk_bf16_f32 v30, v30, v31
	v_cvt_pk_bf16_f32 v31, v32, v33
	s_mov_b64 s[50:51], 0
	global_store_dwordx4 v[26:27], v[28:31], off

.LBB0_1040:
	s_andn2_b64 vcc, exec, s[50:51]
	s_cbranch_vccnz .LBB0_1045
	s_andn2_b64 vcc, exec, s[6:7]
	s_mov_b64 s[50:51], -1
	s_cbranch_vccnz .LBB0_1043
	global_load_dwordx4 v[26:29], v[38:39], off offset:16
	global_load_dwordx4 v[72:75], v[38:39], off
	v_readlane_b32 s11, v243, 49
	s_lshl_b32 s84, s11, 1
	s_mov_b64 s[50:51], 0x6800080
	s_waitcnt vmcnt(0)
	v_mov_b32_e32 v77, v74
	v_mov_b32_e32 v74, v73
	v_mov_b32_e32 v76, v72
	v_mul_f32_e32 v72, v70, v74
	v_mul_f32_e32 v73, v71, v75
	v_mul_f32_e32 v74, v66, v74
	v_mul_f32_e32 v75, v67, v75
	v_fma_f32 v72, v66, v76, -v72
	v_fma_f32 v73, v67, v77, -v73
	v_fma_f32 v74, v70, v76, v74
	v_fma_f32 v75, v71, v77, v75
	v_mov_b32_e32 v77, v28
	v_mov_b32_e32 v28, v27
	v_mov_b32_e32 v76, v26
	v_mul_f32_e32 v26, v68, v28
	v_mul_f32_e32 v27, v69, v29
	v_mul_f32_e32 v28, v54, v28
	v_mul_f32_e32 v29, v55, v29
	v_fma_f32 v26, v54, v76, -v26
	v_fma_f32 v27, v55, v77, -v27
	v_fma_f32 v28, v68, v76, v28
	v_fma_f32 v29, v69, v77, v29
	v_cvt_pk_bf16_f32 v72, v72, v73
	v_cvt_pk_bf16_f32 v73, v26, v27
	v_cvt_pk_bf16_f32 v27, v28, v29
	v_lshl_add_u64 v[28:29], v[40:41], 0, s[84:85]
	v_lshl_add_u64 v[28:29], v[126:127], 1, v[28:29]
	v_cvt_pk_bf16_f32 v26, v74, v75
	v_lshl_add_u64 v[74:75], v[28:29], 0, s[50:51]
	v_add_co_u32_e32 v28, vcc, 0x6800000, v28
	s_mov_b64 s[50:51], 0
	s_nop 0
	v_addc_co_u32_e32 v29, vcc, 0, v29, vcc
	global_store_dwordx2 v[28:29], v[72:73], off offset:128
	global_store_dwordx2 v[74:75], v[26:27], off offset:32

.LBB0_1046:
	s_andn2_b64 vcc, exec, s[50:51]
	v_mov_b32_e32 v72, 0
	s_cbranch_vccnz .LBB0_1070
	s_cmp_lg_u32 s62, 1
	s_mov_b64 s[50:51], -1
	s_cbranch_scc0 .LBB0_1064
	s_andn2_b64 vcc, exec, s[14:15]
	v_ashrrev_i32_e32 v147, 31, v146
	s_cbranch_vccnz .LBB0_1289
	v_lshlrev_b64 v[26:27], 8, v[34:35]
	s_andn2_b64 vcc, exec, s[16:17]
	s_cbranch_vccnz .LBB0_1059
	s_andn2_b64 vcc, exec, s[8:9]
	s_cbranch_vccnz .LBB0_1056
	v_readlane_b32 s50, v242, 16
	v_readlane_b32 s51, v242, 17
	s_andn2_b64 vcc, exec, s[50:51]
	s_mov_b64 s[50:51], -1
	s_cbranch_vccnz .LBB0_1053
	s_mov_b32 s50, 0x3e0293ee
	v_mul_f32_e32 v74, s50, v54
	v_mul_f32_e32 v75, s50, v55
	v_mul_f32_e32 v72, s50, v66
	v_mul_f32_e32 v73, s50, v67
	v_mul_f32_e32 v76, s50, v68
	v_mul_f32_e32 v77, s50, v69
	v_mul_f32_e32 v78, s50, v70
	v_mul_f32_e32 v79, s50, v71
	v_lshl_add_u64 v[28:29], v[146:147], 1, v[46:47]
	v_cvt_pk_bf16_f32 v72, v72, v73
	v_cvt_pk_bf16_f32 v73, v74, v75
	v_cvt_pk_bf16_f32 v74, v78, v79
	v_cvt_pk_bf16_f32 v75, v76, v77
	s_mov_b64 s[50:51], 0
	global_store_dwordx4 v[28:29], v[72:75], off

.LBB0_1056:
	s_andn2_b64 vcc, exec, s[50:51]
	s_cbranch_vccnz .LBB0_1058
	s_mov_b32 s50, 0x3e38aa3b
	v_mul_f32_e32 v74, s50, v54
	v_mul_f32_e32 v75, s50, v55
	v_mul_f32_e32 v72, s50, v66
	v_mul_f32_e32 v73, s50, v67
	v_mul_f32_e32 v76, s50, v68
	v_mul_f32_e32 v77, s50, v69
	v_mul_f32_e32 v78, s50, v70
	v_mul_f32_e32 v79, s50, v71
	v_lshl_add_u64 v[28:29], v[146:147], 1, v[42:43]
	v_cvt_pk_bf16_f32 v72, v72, v73
	v_cvt_pk_bf16_f32 v73, v74, v75
	v_cvt_pk_bf16_f32 v74, v78, v79
	v_cvt_pk_bf16_f32 v75, v76, v77
	global_store_dwordx4 v[28:29], v[72:75], off

.LBB0_1059:
	s_andn2_b64 vcc, exec, s[50:51]
	v_mov_b32_e32 v72, 0
	s_cbranch_vccnz .LBB0_1061
	v_readlane_b32 s50, v242, 13
	v_readlane_b32 s51, v242, 14
	v_cvt_pk_bf16_f32 v28, v70, v71
	v_cvt_pk_bf16_f32 v29, v68, v69
	v_lshl_add_u64 v[26:27], s[50:51], 0, v[26:27]
	v_lshl_add_u64 v[72:73], v[146:147], 1, v[26:27]
	v_cvt_pk_bf16_f32 v26, v66, v67
	v_cvt_pk_bf16_f32 v27, v54, v55
	global_store_dwordx4 v[72:73], v[26:29], off
	s_nop 1
	v_mul_f32_e32 v26, v54, v54
	v_mul_f32_e32 v27, v55, v55
	v_mul_f32_e32 v28, v66, v66
	v_mul_f32_e32 v29, v67, v67
	s_nop 0
	v_pk_mov_b32 v[72:73], v[28:29], v[26:27] op_sel:[1,0]
	v_mov_b32_e32 v29, v27
	v_add_f32_e32 v26, v72, v28
	v_add_f32_e32 v27, v73, v29
	v_mul_f32_e32 v28, v68, v68
	v_mul_f32_e32 v29, v69, v69
	v_mul_f32_e32 v72, v70, v70
	v_mul_f32_e32 v73, v71, v71
	v_mov_b32_e32 v74, v28
	v_mov_b32_e32 v75, v72
	v_mov_b32_e32 v72, v29
	v_add_f32_e32 v28, v74, v72
	v_add_f32_e32 v29, v75, v73
	v_add_f32_e32 v26, v26, v27
	v_add_f32_e32 v26, v29, v26
	v_add_f32_e32 v72, v28, v26

.LBB0_1062:
	v_lshl_add_u64 v[72:73], v[146:147], 1, v[36:37]
	v_cvt_pk_bf16_f32 v26, v66, v67
	v_cvt_pk_bf16_f32 v27, v54, v55
	v_cvt_pk_bf16_f32 v28, v70, v71
	v_cvt_pk_bf16_f32 v29, v68, v69
	global_store_dwordx4 v[72:73], v[26:29], off
	s_nop 1
	v_mul_f32_e32 v26, v54, v54
	v_mul_f32_e32 v27, v55, v55
	v_mul_f32_e32 v28, v66, v66
	v_mul_f32_e32 v29, v67, v67
	s_nop 0
	v_pk_mov_b32 v[72:73], v[28:29], v[26:27] op_sel:[1,0]
	v_mov_b32_e32 v29, v27
	v_add_f32_e32 v26, v72, v28
	v_add_f32_e32 v27, v73, v29
	v_mul_f32_e32 v28, v68, v68
	v_mul_f32_e32 v29, v69, v69
	v_mul_f32_e32 v72, v70, v70
	v_mul_f32_e32 v73, v71, v71
	v_mov_b32_e32 v74, v28
	v_mov_b32_e32 v75, v72
	v_mov_b32_e32 v72, v29
	v_add_f32_e32 v28, v74, v72
	v_add_f32_e32 v29, v75, v73
	v_add_f32_e32 v26, v26, v27
	v_add_f32_e32 v26, v29, v26
	v_add_f32_e32 v72, v28, v26

.LBB0_1070:
	v_mov_b32_e32 v57, v56
	v_mov_b32_e32 v54, v56
	v_mov_b32_e32 v55, v56
	v_mul_f32_e32 v26, v24, v54
	v_mul_f32_e32 v27, v25, v55
	v_mul_f32_e32 v28, v22, v56
	v_mul_f32_e32 v29, v23, v57
	v_mul_f32_e32 v54, v20, v54
	v_mul_f32_e32 v55, v21, v55
	v_mul_f32_e32 v56, v18, v56
	v_mul_f32_e32 v57, v19, v57
	s_cmp_lt_i32 s62, 4
	s_mov_b64 s[50:51], -1
	s_cbranch_scc0 .LBB0_1076
	s_andn2_b64 vcc, exec, s[50:51]
	s_cbranch_vccz .LBB0_1094

.LBB0_1076:
	s_cmp_lt_i32 s62, 6
	s_cbranch_scc1 .LBB0_1085
	s_cmp_gt_i32 s62, 6
	s_cbranch_scc0 .LBB0_1079
	v_max_f32_e32 v19, v56, v56
	v_max_f32_e32 v23, v54, v54
	v_max_f32_e32 v18, v28, v28
	v_max_f32_e32 v20, 0, v19
	v_max_f32_e32 v19, v29, v29
	v_max_f32_e32 v21, v57, v57
	v_max_f32_e32 v22, v26, v26
	v_max_f32_e32 v24, 0, v23
	v_max_f32_e32 v23, v27, v27
	v_max_f32_e32 v25, v55, v55
	v_max_f32_e32 v18, 0, v18
	v_max_f32_e32 v19, 0, v19
	v_max_f32_e32 v21, 0, v21
	v_max_f32_e32 v22, 0, v22
	v_max_f32_e32 v23, 0, v23
	v_max_f32_e32 v25, 0, v25
	v_mul_f32_e32 v18, v18, v18
	v_mul_f32_e32 v19, v19, v19
	v_mul_f32_e32 v20, v20, v20
	v_mul_f32_e32 v21, v21, v21
	v_mul_f32_e32 v22, v22, v22
	v_mul_f32_e32 v23, v23, v23
	v_mul_f32_e32 v24, v24, v24
	v_mul_f32_e32 v25, v25, v25
	v_ashrrev_i32_e32 v147, 31, v146
	v_lshl_add_u64 v[62:63], v[146:147], 1, v[62:63]
	v_cvt_pk_bf16_f32 v18, v18, v19
	v_cvt_pk_bf16_f32 v19, v22, v23
	v_cvt_pk_bf16_f32 v20, v20, v21
	v_cvt_pk_bf16_f32 v21, v24, v25
	global_store_dwordx4 v[62:63], v[18:21], off offset:256
	s_mov_b64 s[50:51], 0

.LBB0_1083:
	s_waitcnt vmcnt(0)
	v_add_f32_e32 v60, v26, v20
	v_add_f32_e32 v61, v27, v21
	v_add_f32_e32 v62, v28, v18
	v_add_f32_e32 v63, v29, v19
	v_add_f32_e32 v24, v54, v24
	v_add_f32_e32 v25, v55, v25
	v_add_f32_e32 v22, v56, v22
	v_add_f32_e32 v23, v57, v23
	v_cvt_pk_bf16_f32 v18, v62, v63
	v_cvt_pk_bf16_f32 v19, v60, v61
	v_cvt_pk_bf16_f32 v20, v22, v23
	v_cvt_pk_bf16_f32 v21, v24, v25
	global_store_dwordx4 v[52:53], v[18:21], off
	v_mul_f32_e32 v22, v22, v22
	v_mul_f32_e32 v23, v23, v23
	s_nop 0
	v_mul_f32_e32 v18, v60, v60
	v_mul_f32_e32 v19, v61, v61
	v_mul_f32_e32 v20, v62, v62
	v_mul_f32_e32 v21, v63, v63
	s_nop 0
	v_pk_mov_b32 v[52:53], v[20:21], v[18:19] op_sel:[1,0]
	v_mov_b32_e32 v21, v19
	v_add_f32_e32 v18, v52, v20
	v_add_f32_e32 v19, v53, v21
	v_mul_f32_e32 v20, v24, v24
	v_mul_f32_e32 v21, v25, v25
	v_mov_b32_e32 v25, v22
	v_mov_b32_e32 v24, v20
	v_mov_b32_e32 v22, v21
	v_add_f32_e32 v20, v24, v22
	v_add_f32_e32 v21, v25, v23
	v_add_f32_e32 v18, v18, v19
	v_add_f32_e32 v18, v18, v21
	v_add_f32_e32 v18, v20, v18
	v_add_f32_e32 v18, v72, v18

.LBB0_1089:
	s_waitcnt vmcnt(0)
	v_cvt_f32_ubyte3_e32 v61, v22
	v_cvt_f32_ubyte2_e32 v60, v22
	v_cvt_f32_ubyte1_e32 v63, v22
	v_cvt_f32_ubyte0_e32 v62, v22
	v_mul_f32_e32 v62, s26, v62
	v_mul_f32_e32 v63, s26, v63
	v_mul_f32_e32 v60, s26, v60
	v_mul_f32_e32 v61, s26, v61
	v_fma_f32 v50, v28, v62, v50
	v_fma_f32 v51, v29, v63, v51
	v_fma_f32 v52, v26, v60, v52
	v_fma_f32 v53, v27, v61, v53
	v_cvt_f32_ubyte3_e32 v61, v23
	v_cvt_f32_ubyte2_e32 v60, v23
	v_cvt_f32_ubyte1_e32 v63, v23
	v_cvt_f32_ubyte0_e32 v62, v23
	v_mul_f32_e32 v22, s26, v62
	v_mul_f32_e32 v23, s26, v63
	v_mul_f32_e32 v60, s26, v60
	v_mul_f32_e32 v61, s26, v61
	v_fma_f32 v22, v56, v22, v20
	v_fma_f32 v23, v57, v23, v21
	v_fma_f32 v24, v54, v60, v24
	v_fma_f32 v25, v55, v61, v25
	v_cvt_pk_bf16_f32 v20, v50, v51
	v_cvt_pk_bf16_f32 v21, v52, v53
	v_cvt_pk_bf16_f32 v22, v22, v23
	v_cvt_pk_bf16_f32 v23, v24, v25
	s_mov_b64 s[50:51], 0
	global_store_dwordx4 v[18:19], v[20:23], off

.LBB0_1101:
	s_andn2_b64 vcc, exec, s[50:51]
	s_cbranch_vccnz .LBB0_1106
	s_andn2_b64 vcc, exec, s[6:7]
	s_mov_b64 s[50:51], -1
	s_cbranch_vccnz .LBB0_1104
	global_load_dwordx4 v[18:21], v[38:39], off offset:16
	global_load_dwordx4 v[22:25], v[38:39], off
	v_readlane_b32 s11, v243, 49
	s_lshl_b32 s84, s11, 1
	s_mov_b64 s[50:51], 0x6800380
	s_waitcnt vmcnt(0)
	v_mov_b32_e32 v45, v24
	v_mov_b32_e32 v24, v23
	v_mov_b32_e32 v44, v22
	v_mul_f32_e32 v22, v56, v24
	v_mul_f32_e32 v23, v57, v25
	v_mul_f32_e32 v24, v28, v24
	v_mul_f32_e32 v25, v29, v25
	v_fma_f32 v22, v28, v44, -v22
	v_fma_f32 v23, v29, v45, -v23
	v_fma_f32 v24, v56, v44, v24
	v_fma_f32 v25, v57, v45, v25
	v_mov_b32_e32 v45, v20
	v_mov_b32_e32 v20, v19
	v_mov_b32_e32 v44, v18
	v_mul_f32_e32 v18, v54, v20
	v_mul_f32_e32 v19, v55, v21
	v_mul_f32_e32 v20, v26, v20
	v_mul_f32_e32 v21, v27, v21
	v_fma_f32 v18, v26, v44, -v18
	v_fma_f32 v19, v27, v45, -v19
	v_fma_f32 v20, v54, v44, v20
	v_fma_f32 v21, v55, v45, v21
	v_cvt_pk_bf16_f32 v22, v22, v23
	v_cvt_pk_bf16_f32 v23, v18, v19
	v_cvt_pk_bf16_f32 v19, v20, v21
	v_lshl_add_u64 v[20:21], v[40:41], 0, s[84:85]
	v_lshl_add_u64 v[20:21], v[126:127], 1, v[20:21]
	v_cvt_pk_bf16_f32 v18, v24, v25
	v_lshl_add_u64 v[24:25], v[20:21], 0, s[50:51]
	v_add_co_u32_e32 v20, vcc, 0x6800000, v20
	s_mov_b64 s[50:51], 0
	s_nop 0
	v_addc_co_u32_e32 v21, vcc, 0, v21, vcc
	global_store_dwordx2 v[20:21], v[22:23], off offset:896
	global_store_dwordx2 v[24:25], v[18:19], off offset:32

.LBB0_1107:
	s_andn2_b64 vcc, exec, s[50:51]
	s_cbranch_vccnz .LBB0_1134
	s_cmp_lg_u32 s62, 1
	s_mov_b64 s[50:51], -1
	s_cbranch_scc0 .LBB0_1127
	s_andn2_b64 vcc, exec, s[14:15]
	s_cbranch_vccnz .LBB0_1124
	s_andn2_b64 vcc, exec, s[16:17]
	s_cbranch_vccnz .LBB0_1120
	s_andn2_b64 vcc, exec, s[8:9]
	s_cbranch_vccnz .LBB0_1117
	v_readlane_b32 s50, v242, 16
	v_readlane_b32 s51, v242, 17
	s_andn2_b64 vcc, exec, s[50:51]
	s_mov_b64 s[50:51], -1
	s_cbranch_vccnz .LBB0_1114
	s_mov_b32 s50, 0x3e0293ee
	v_ashrrev_i32_e32 v147, 31, v146
	v_mul_f32_e32 v20, s50, v26
	v_mul_f32_e32 v21, s50, v27
	v_mul_f32_e32 v18, s50, v28
	v_mul_f32_e32 v19, s50, v29
	v_mul_f32_e32 v24, s50, v54
	v_mul_f32_e32 v25, s50, v55
	v_mul_f32_e32 v44, s50, v56
	v_mul_f32_e32 v45, s50, v57
	v_lshl_add_u64 v[22:23], v[146:147], 1, v[46:47]
	v_cvt_pk_bf16_f32 v18, v18, v19
	v_cvt_pk_bf16_f32 v19, v20, v21
	v_cvt_pk_bf16_f32 v20, v44, v45
	v_cvt_pk_bf16_f32 v21, v24, v25
	s_mov_b64 s[50:51], 0
	global_store_dwordx4 v[22:23], v[18:21], off offset:256

.LBB0_1117:
	s_andn2_b64 vcc, exec, s[50:51]
	s_cbranch_vccnz .LBB0_1119
	s_mov_b32 s50, 0x3e38aa3b
	v_ashrrev_i32_e32 v147, 31, v146
	v_mul_f32_e32 v20, s50, v26
	v_mul_f32_e32 v21, s50, v27
	v_mul_f32_e32 v18, s50, v28
	v_mul_f32_e32 v19, s50, v29
	v_mul_f32_e32 v24, s50, v54
	v_mul_f32_e32 v25, s50, v55
	v_mul_f32_e32 v34, s50, v56
	v_mul_f32_e32 v35, s50, v57
	v_lshl_add_u64 v[22:23], v[146:147], 1, v[42:43]
	v_cvt_pk_bf16_f32 v18, v18, v19
	v_cvt_pk_bf16_f32 v19, v20, v21
	v_cvt_pk_bf16_f32 v20, v34, v35
	v_cvt_pk_bf16_f32 v21, v24, v25
	global_store_dwordx4 v[22:23], v[18:21], off offset:256

.LBB0_1120:
	s_andn2_b64 vcc, exec, s[50:51]
	s_cbranch_vccnz .LBB0_1123
	v_readlane_b32 s50, v243, 47
	v_readlane_b32 s51, v243, 48
	s_andn2_b64 vcc, exec, s[50:51]
	s_cbranch_vccnz .LBB0_1123
	global_load_dwordx4 v[18:21], v[38:39], off offset:16
	global_load_dwordx4 v[22:25], v[38:39], off
	v_lshl_add_u64 v[34:35], v[126:127], 1, v[40:41]
	s_brev_b32 s11, 16
	s_mov_b64 s[50:51], 0x8000080
	v_lshl_add_u64 v[40:41], v[34:35], 0, s[50:51]
	s_waitcnt vmcnt(0)
	v_mov_b32_e32 v39, v24
	v_mov_b32_e32 v24, v23
	v_mov_b32_e32 v38, v22
	v_mul_f32_e32 v22, v56, v24
	v_mul_f32_e32 v23, v57, v25
	v_mul_f32_e32 v24, v28, v24
	v_mul_f32_e32 v25, v29, v25
	v_fma_f32 v22, v28, v38, -v22
	v_fma_f32 v23, v29, v39, -v23
	v_fma_f32 v24, v56, v38, v24
	v_fma_f32 v25, v57, v39, v25
	v_mov_b32_e32 v39, v20
	v_mov_b32_e32 v20, v19
	v_mov_b32_e32 v38, v18
	v_mul_f32_e32 v18, v54, v20
	v_mul_f32_e32 v19, v55, v21
	v_mul_f32_e32 v20, v26, v20
	v_mul_f32_e32 v21, v27, v21
	v_fma_f32 v18, v26, v38, -v18
	v_fma_f32 v19, v27, v39, -v19
	v_fma_f32 v20, v54, v38, v20
	v_fma_f32 v21, v55, v39, v21
	v_cvt_pk_bf16_f32 v22, v22, v23
	v_cvt_pk_bf16_f32 v23, v18, v19
	v_cvt_pk_bf16_f32 v19, v20, v21
	v_add_co_u32_e32 v20, vcc, s11, v34
	v_cvt_pk_bf16_f32 v18, v24, v25
	s_nop 0
	v_addc_co_u32_e32 v21, vcc, 0, v35, vcc
	global_store_dwordx2 v[20:21], v[22:23], off offset:128
	global_store_dwordx2 v[40:41], v[18:19], off offset:32
	global_store_dwordx2 v[40:41], v[22:23], off offset:192
	global_store_dwordx2 v[40:41], v[18:19], off offset:224
	global_store_dwordx2 v[40:41], v[22:23], off offset:384
	global_store_dwordx2 v[40:41], v[18:19], off offset:416
	global_store_dwordx2 v[40:41], v[22:23], off offset:576
	global_store_dwordx2 v[40:41], v[18:19], off offset:608
	global_store_dwordx2 v[40:41], v[22:23], off offset:768
	global_store_dwordx2 v[40:41], v[18:19], off offset:800
	global_store_dwordx2 v[40:41], v[22:23], off offset:960
	global_store_dwordx2 v[40:41], v[18:19], off offset:992
	global_store_dwordx2 v[40:41], v[22:23], off offset:1152
	global_store_dwordx2 v[40:41], v[18:19], off offset:1184
	global_store_dwordx2 v[40:41], v[22:23], off offset:1344
	global_store_dwordx2 v[40:41], v[18:19], off offset:1376

.LBB0_1124:
	s_andn2_b64 vcc, exec, s[50:51]
	v_mov_b32_e32 v18, v72
	s_cbranch_vccnz .LBB0_1126
	v_ashrrev_i32_e32 v147, 31, v146
	v_lshl_add_u64 v[22:23], v[146:147], 1, v[36:37]
	v_cvt_pk_bf16_f32 v18, v28, v29
	v_cvt_pk_bf16_f32 v19, v26, v27
	v_cvt_pk_bf16_f32 v20, v56, v57
	v_cvt_pk_bf16_f32 v21, v54, v55
	global_store_dwordx4 v[22:23], v[18:21], off offset:256
	s_nop 1
	v_mul_f32_e32 v18, v26, v26
	v_mul_f32_e32 v19, v27, v27
	v_mul_f32_e32 v20, v28, v28
	v_mul_f32_e32 v21, v29, v29
	s_nop 0
	v_pk_mov_b32 v[22:23], v[20:21], v[18:19] op_sel:[1,0]
	v_mov_b32_e32 v21, v19
	v_add_f32_e32 v18, v22, v20
	v_add_f32_e32 v19, v23, v21
	v_mul_f32_e32 v20, v54, v54
	v_mul_f32_e32 v21, v55, v55
	v_mul_f32_e32 v22, v56, v56
	v_mul_f32_e32 v23, v57, v57
	v_mov_b32_e32 v24, v20
	v_mov_b32_e32 v25, v22
	v_mov_b32_e32 v22, v21
	v_add_f32_e32 v20, v24, v22
	v_add_f32_e32 v21, v25, v23
	v_add_f32_e32 v18, v18, v19
	v_add_f32_e32 v18, v21, v18
	v_add_f32_e32 v18, v20, v18
	v_add_f32_e32 v18, v18, v72

.LBB0_1143:
	v_mul_f32_e32 v21, 0x3e16c740, v20
	v_lshlrev_b64 v[22:23], 11, v[18:19]
	v_cndmask_b32_e64 v40, v20, v21, s[52:53]
	v_lshlrev_b64 v[20:21], 10, v[18:19]
	v_lshl_add_u64 v[36:37], s[88:89], 0, v[22:23]
	v_lshlrev_b64 v[24:25], 12, v[18:19]
	v_lshl_add_u64 v[34:35], s[34:35], 0, v[22:23]
	v_lshlrev_b64 v[22:23], 13, v[18:19]
	v_lshl_add_u64 v[44:45], v[148:149], 0, v[24:25]
	v_lshl_add_u64 v[28:29], s[2:3], 0, v[20:21]
	v_lshl_add_u64 v[46:47], s[28:29], 0, v[22:23]
	v_mul_f32_e32 v38, v16, v40
	v_mul_f32_e32 v39, v17, v40
	v_mul_f32_e32 v50, v14, v40
	v_mul_f32_e32 v51, v15, v40
	v_mul_f32_e32 v52, v12, v40
	v_mul_f32_e32 v53, v13, v40
	v_mul_f32_e32 v54, v10, v40
	v_mul_f32_e32 v55, v11, v40
	s_cmp_lt_i32 s62, 4
	s_mov_b64 s[28:29], -1
	s_cbranch_scc1 .LBB0_1162
	s_cmp_lt_i32 s62, 6
	s_cbranch_scc1 .LBB0_1153
	s_cmp_gt_i32 s62, 6
	s_cbranch_scc0 .LBB0_1147
	v_max_f32_e32 v11, v54, v54
	v_max_f32_e32 v15, v52, v52
	v_max_f32_e32 v10, v50, v50
	v_max_f32_e32 v12, 0, v11
	v_max_f32_e32 v11, v51, v51
	v_max_f32_e32 v13, v55, v55
	v_max_f32_e32 v14, v38, v38
	v_max_f32_e32 v16, 0, v15
	v_max_f32_e32 v15, v39, v39
	v_max_f32_e32 v17, v53, v53
	v_max_f32_e32 v10, 0, v10
	v_max_f32_e32 v11, 0, v11
	v_max_f32_e32 v13, 0, v13
	v_max_f32_e32 v14, 0, v14
	v_max_f32_e32 v15, 0, v15
	v_max_f32_e32 v17, 0, v17
	v_mul_f32_e32 v10, v10, v10
	v_mul_f32_e32 v11, v11, v11
	v_mul_f32_e32 v12, v12, v12
	v_mul_f32_e32 v13, v13, v13
	v_mul_f32_e32 v14, v14, v14
	v_mul_f32_e32 v15, v15, v15
	v_mul_f32_e32 v16, v16, v16
	v_mul_f32_e32 v17, v17, v17
	v_ashrrev_i32_e32 v147, 31, v146
	v_lshl_add_u64 v[22:23], v[146:147], 1, v[46:47]
	v_cvt_pk_bf16_f32 v10, v10, v11
	v_cvt_pk_bf16_f32 v11, v14, v15
	v_cvt_pk_bf16_f32 v12, v12, v13
	v_cvt_pk_bf16_f32 v13, v16, v17
	global_store_dwordx4 v[22:23], v[10:13], off
	s_mov_b64 s[28:29], 0

.LBB0_1151:
	s_waitcnt vmcnt(0)
	v_add_f32_e32 v24, v38, v12
	v_add_f32_e32 v25, v39, v13
	v_add_f32_e32 v26, v50, v10
	v_add_f32_e32 v27, v51, v11
	v_add_f32_e32 v16, v52, v16
	v_add_f32_e32 v17, v53, v17
	v_add_f32_e32 v14, v54, v14
	v_add_f32_e32 v15, v55, v15
	v_cvt_pk_bf16_f32 v10, v26, v27
	v_cvt_pk_bf16_f32 v11, v24, v25
	v_cvt_pk_bf16_f32 v12, v14, v15
	v_cvt_pk_bf16_f32 v13, v16, v17
	global_store_dwordx4 v[22:23], v[10:13], off
	v_mul_f32_e32 v14, v14, v14
	v_mul_f32_e32 v15, v15, v15
	s_nop 0
	v_mul_f32_e32 v10, v24, v24
	v_mul_f32_e32 v11, v25, v25
	v_mul_f32_e32 v12, v26, v26
	v_mul_f32_e32 v13, v27, v27
	s_nop 0
	v_pk_mov_b32 v[22:23], v[12:13], v[10:11] op_sel:[1,0]
	v_mov_b32_e32 v13, v11
	v_add_f32_e32 v10, v22, v12
	v_add_f32_e32 v11, v23, v13
	v_mul_f32_e32 v12, v16, v16
	v_mul_f32_e32 v13, v17, v17
	v_mov_b32_e32 v17, v14
	v_mov_b32_e32 v16, v12
	v_mov_b32_e32 v14, v13
	v_add_f32_e32 v12, v16, v14
	v_add_f32_e32 v13, v17, v15
	v_add_f32_e32 v10, v10, v11
	v_add_f32_e32 v10, v10, v13
	v_add_f32_e32 v56, v12, v10

.LBB0_1157:
	s_waitcnt vmcnt(0)
	v_cvt_f32_ubyte3_e32 v27, v14
	v_cvt_f32_ubyte2_e32 v26, v14
	v_cvt_f32_ubyte1_e32 v31, v14
	v_cvt_f32_ubyte0_e32 v30, v14
	v_mul_f32_e32 v30, s26, v30
	v_mul_f32_e32 v31, s26, v31
	v_mul_f32_e32 v26, s26, v26
	v_mul_f32_e32 v27, s26, v27
	v_fma_f32 v22, v50, v30, v22
	v_fma_f32 v23, v51, v31, v23
	v_fma_f32 v24, v38, v26, v24
	v_fma_f32 v25, v39, v27, v25
	v_cvt_f32_ubyte3_e32 v27, v15
	v_cvt_f32_ubyte2_e32 v26, v15
	v_cvt_f32_ubyte1_e32 v31, v15
	v_cvt_f32_ubyte0_e32 v30, v15
	v_mul_f32_e32 v14, s26, v30
	v_mul_f32_e32 v15, s26, v31
	v_mul_f32_e32 v26, s26, v26
	v_mul_f32_e32 v27, s26, v27
	v_fma_f32 v14, v54, v14, v12
	v_fma_f32 v15, v55, v15, v13
	v_fma_f32 v16, v52, v26, v16
	v_fma_f32 v17, v53, v27, v17
	v_cvt_pk_bf16_f32 v12, v22, v23
	v_cvt_pk_bf16_f32 v13, v24, v25
	v_cvt_pk_bf16_f32 v14, v14, v15
	v_cvt_pk_bf16_f32 v15, v16, v17
	s_mov_b64 s[28:29], 0
	global_store_dwordx4 v[10:11], v[12:15], off

.LBB0_1170:
	s_andn2_b64 vcc, exec, s[20:21]
	s_cbranch_vccnz .LBB0_1175
	s_andn2_b64 vcc, exec, s[6:7]
	s_mov_b64 s[20:21], -1
	s_cbranch_vccnz .LBB0_1173
	global_load_dwordx4 v[10:13], v[22:23], off offset:16
	global_load_dwordx4 v[56:59], v[22:23], off
	v_readlane_b32 s11, v243, 49
	s_lshl_b32 s84, s11, 1
	s_mov_b64 s[20:21], 0x6800080
	s_waitcnt vmcnt(0)
	v_mov_b32_e32 v61, v58
	v_mov_b32_e32 v58, v57
	v_mov_b32_e32 v60, v56
	v_mul_f32_e32 v56, v54, v58
	v_mul_f32_e32 v57, v55, v59
	v_mul_f32_e32 v58, v50, v58
	v_mul_f32_e32 v59, v51, v59
	v_fma_f32 v56, v50, v60, -v56
	v_fma_f32 v57, v51, v61, -v57
	v_fma_f32 v58, v54, v60, v58
	v_fma_f32 v59, v55, v61, v59
	v_mov_b32_e32 v61, v12
	v_mov_b32_e32 v12, v11
	v_mov_b32_e32 v60, v10
	v_mul_f32_e32 v10, v52, v12
	v_mul_f32_e32 v11, v53, v13
	v_mul_f32_e32 v12, v38, v12
	v_mul_f32_e32 v13, v39, v13
	v_fma_f32 v10, v38, v60, -v10
	v_fma_f32 v11, v39, v61, -v11
	v_fma_f32 v12, v52, v60, v12
	v_fma_f32 v13, v53, v61, v13
	v_cvt_pk_bf16_f32 v56, v56, v57
	v_cvt_pk_bf16_f32 v57, v10, v11
	v_cvt_pk_bf16_f32 v11, v12, v13
	v_lshl_add_u64 v[12:13], v[24:25], 0, s[84:85]
	v_lshl_add_u64 v[12:13], v[126:127], 1, v[12:13]
	v_cvt_pk_bf16_f32 v10, v58, v59
	v_lshl_add_u64 v[58:59], v[12:13], 0, s[20:21]
	v_add_co_u32_e32 v12, vcc, 0x6800000, v12
	s_mov_b64 s[20:21], 0
	s_nop 0
	v_addc_co_u32_e32 v13, vcc, 0, v13, vcc
	global_store_dwordx2 v[12:13], v[56:57], off offset:128
	global_store_dwordx2 v[58:59], v[10:11], off offset:32

.LBB0_1176:
	s_andn2_b64 vcc, exec, s[20:21]
	v_mov_b32_e32 v56, 0
	s_cbranch_vccnz .LBB0_1200
	s_cmp_lg_u32 s62, 1
	s_mov_b64 s[20:21], -1
	s_cbranch_scc0 .LBB0_1194
	s_andn2_b64 vcc, exec, s[14:15]
	v_ashrrev_i32_e32 v147, 31, v146
	s_cbranch_vccnz .LBB0_1292
	v_lshlrev_b64 v[10:11], 8, v[18:19]
	s_andn2_b64 vcc, exec, s[16:17]
	s_cbranch_vccnz .LBB0_1189
	s_andn2_b64 vcc, exec, s[8:9]
	s_cbranch_vccnz .LBB0_1186
	v_readlane_b32 s20, v242, 16
	v_readlane_b32 s21, v242, 17
	s_andn2_b64 vcc, exec, s[20:21]
	s_mov_b64 s[20:21], -1
	s_cbranch_vccnz .LBB0_1183
	s_mov_b32 s20, 0x3e0293ee
	v_mul_f32_e32 v58, s20, v38
	v_mul_f32_e32 v59, s20, v39
	v_mul_f32_e32 v56, s20, v50
	v_mul_f32_e32 v57, s20, v51
	v_mul_f32_e32 v60, s20, v52
	v_mul_f32_e32 v61, s20, v53
	v_mul_f32_e32 v62, s20, v54
	v_mul_f32_e32 v63, s20, v55
	v_lshl_add_u64 v[12:13], v[146:147], 1, v[30:31]
	v_cvt_pk_bf16_f32 v56, v56, v57
	v_cvt_pk_bf16_f32 v57, v58, v59
	v_cvt_pk_bf16_f32 v58, v62, v63
	v_cvt_pk_bf16_f32 v59, v60, v61
	s_mov_b64 s[20:21], 0
	global_store_dwordx4 v[12:13], v[56:59], off

.LBB0_1186:
	s_andn2_b64 vcc, exec, s[20:21]
	s_cbranch_vccnz .LBB0_1188
	s_mov_b32 s20, 0x3e38aa3b
	v_mul_f32_e32 v58, s20, v38
	v_mul_f32_e32 v59, s20, v39
	v_mul_f32_e32 v56, s20, v50
	v_mul_f32_e32 v57, s20, v51
	v_mul_f32_e32 v60, s20, v52
	v_mul_f32_e32 v61, s20, v53
	v_mul_f32_e32 v62, s20, v54
	v_mul_f32_e32 v63, s20, v55
	v_lshl_add_u64 v[12:13], v[146:147], 1, v[26:27]
	v_cvt_pk_bf16_f32 v56, v56, v57
	v_cvt_pk_bf16_f32 v57, v58, v59
	v_cvt_pk_bf16_f32 v58, v62, v63
	v_cvt_pk_bf16_f32 v59, v60, v61
	global_store_dwordx4 v[12:13], v[56:59], off

.LBB0_1189:
	s_andn2_b64 vcc, exec, s[20:21]
	v_mov_b32_e32 v56, 0
	s_cbranch_vccnz .LBB0_1191
	v_readlane_b32 s20, v242, 13
	v_readlane_b32 s21, v242, 14
	v_cvt_pk_bf16_f32 v12, v54, v55
	v_cvt_pk_bf16_f32 v13, v52, v53
	v_lshl_add_u64 v[10:11], s[20:21], 0, v[10:11]
	v_lshl_add_u64 v[56:57], v[146:147], 1, v[10:11]
	v_cvt_pk_bf16_f32 v10, v50, v51
	v_cvt_pk_bf16_f32 v11, v38, v39
	global_store_dwordx4 v[56:57], v[10:13], off
	s_nop 1
	v_mul_f32_e32 v10, v38, v38
	v_mul_f32_e32 v11, v39, v39
	v_mul_f32_e32 v12, v50, v50
	v_mul_f32_e32 v13, v51, v51
	s_nop 0
	v_pk_mov_b32 v[56:57], v[12:13], v[10:11] op_sel:[1,0]
	v_mov_b32_e32 v13, v11
	v_add_f32_e32 v10, v56, v12
	v_add_f32_e32 v11, v57, v13
	v_mul_f32_e32 v12, v52, v52
	v_mul_f32_e32 v13, v53, v53
	v_mul_f32_e32 v56, v54, v54
	v_mul_f32_e32 v57, v55, v55
	v_mov_b32_e32 v58, v12
	v_mov_b32_e32 v59, v56
	v_mov_b32_e32 v56, v13
	v_add_f32_e32 v12, v58, v56
	v_add_f32_e32 v13, v59, v57
	v_add_f32_e32 v10, v10, v11
	v_add_f32_e32 v10, v13, v10
	v_add_f32_e32 v56, v12, v10

.LBB0_1192:
	v_lshl_add_u64 v[56:57], v[146:147], 1, v[20:21]
	v_cvt_pk_bf16_f32 v10, v50, v51
	v_cvt_pk_bf16_f32 v11, v38, v39
	v_cvt_pk_bf16_f32 v12, v54, v55
	v_cvt_pk_bf16_f32 v13, v52, v53
	global_store_dwordx4 v[56:57], v[10:13], off
	s_nop 1
	v_mul_f32_e32 v10, v38, v38
	v_mul_f32_e32 v11, v39, v39
	v_mul_f32_e32 v12, v50, v50
	v_mul_f32_e32 v13, v51, v51
	s_nop 0
	v_pk_mov_b32 v[56:57], v[12:13], v[10:11] op_sel:[1,0]
	v_mov_b32_e32 v13, v11
	v_add_f32_e32 v10, v56, v12
	v_add_f32_e32 v11, v57, v13
	v_mul_f32_e32 v12, v52, v52
	v_mul_f32_e32 v13, v53, v53
	v_mul_f32_e32 v56, v54, v54
	v_mul_f32_e32 v57, v55, v55
	v_mov_b32_e32 v58, v12
	v_mov_b32_e32 v59, v56
	v_mov_b32_e32 v56, v13
	v_add_f32_e32 v12, v58, v56
	v_add_f32_e32 v13, v59, v57
	v_add_f32_e32 v10, v10, v11
	v_add_f32_e32 v10, v13, v10
	v_add_f32_e32 v56, v12, v10

.LBB0_1200:
	v_mov_b32_e32 v41, v40
	v_mov_b32_e32 v38, v40
	v_mov_b32_e32 v39, v40
	v_mul_f32_e32 v10, v8, v38
	v_mul_f32_e32 v11, v9, v39
	v_mul_f32_e32 v12, v6, v40
	v_mul_f32_e32 v13, v7, v41
	v_mul_f32_e32 v38, v4, v38
	v_mul_f32_e32 v39, v5, v39
	v_mul_f32_e32 v40, v2, v40
	v_mul_f32_e32 v41, v3, v41
	s_cmp_lt_i32 s62, 4
	s_mov_b64 s[20:21], -1
	s_cbranch_scc0 .LBB0_1207
	s_andn2_b64 vcc, exec, s[20:21]
	s_cbranch_vccz .LBB0_1225

.LBB0_1207:
	s_cmp_lt_i32 s62, 6
	s_cbranch_scc1 .LBB0_1216
	s_cmp_gt_i32 s62, 6
	s_cbranch_scc0 .LBB0_1210
	v_max_f32_e32 v3, v40, v40
	v_max_f32_e32 v7, v38, v38
	v_max_f32_e32 v2, v12, v12
	v_max_f32_e32 v4, 0, v3
	v_max_f32_e32 v3, v13, v13
	v_max_f32_e32 v5, v41, v41
	v_max_f32_e32 v6, v10, v10
	v_max_f32_e32 v8, 0, v7
	v_max_f32_e32 v7, v11, v11
	v_max_f32_e32 v9, v39, v39
	v_max_f32_e32 v2, 0, v2
	v_max_f32_e32 v3, 0, v3
	v_max_f32_e32 v5, 0, v5
	v_max_f32_e32 v6, 0, v6
	v_max_f32_e32 v7, 0, v7
	v_max_f32_e32 v9, 0, v9
	v_mul_f32_e32 v2, v2, v2
	v_mul_f32_e32 v3, v3, v3
	v_mul_f32_e32 v4, v4, v4
	v_mul_f32_e32 v5, v5, v5
	v_mul_f32_e32 v6, v6, v6
	v_mul_f32_e32 v7, v7, v7
	v_mul_f32_e32 v8, v8, v8
	v_mul_f32_e32 v9, v9, v9
	v_ashrrev_i32_e32 v147, 31, v146
	v_lshl_add_u64 v[46:47], v[146:147], 1, v[46:47]
	v_cvt_pk_bf16_f32 v2, v2, v3
	v_cvt_pk_bf16_f32 v3, v6, v7
	v_cvt_pk_bf16_f32 v4, v4, v5
	v_cvt_pk_bf16_f32 v5, v8, v9
	global_store_dwordx4 v[46:47], v[2:5], off offset:256
	s_mov_b64 s[20:21], 0

.LBB0_1214:
	s_waitcnt vmcnt(0)
	v_add_f32_e32 v44, v10, v4
	v_add_f32_e32 v45, v11, v5
	v_add_f32_e32 v46, v12, v2
	v_add_f32_e32 v47, v13, v3
	v_add_f32_e32 v8, v38, v8
	v_add_f32_e32 v9, v39, v9
	v_add_f32_e32 v6, v40, v6
	v_add_f32_e32 v7, v41, v7
	v_cvt_pk_bf16_f32 v2, v46, v47
	v_cvt_pk_bf16_f32 v3, v44, v45
	v_cvt_pk_bf16_f32 v4, v6, v7
	v_cvt_pk_bf16_f32 v5, v8, v9
	global_store_dwordx4 v[36:37], v[2:5], off
	v_mul_f32_e32 v6, v6, v6
	v_mul_f32_e32 v7, v7, v7
	s_nop 0
	v_mul_f32_e32 v2, v44, v44
	v_mul_f32_e32 v3, v45, v45
	v_mul_f32_e32 v4, v46, v46
	v_mul_f32_e32 v5, v47, v47
	s_nop 0
	v_pk_mov_b32 v[36:37], v[4:5], v[2:3] op_sel:[1,0]
	v_mov_b32_e32 v5, v3
	v_add_f32_e32 v2, v36, v4
	v_add_f32_e32 v3, v37, v5
	v_mul_f32_e32 v4, v8, v8
	v_mul_f32_e32 v5, v9, v9
	v_mov_b32_e32 v9, v6
	v_mov_b32_e32 v8, v4
	v_mov_b32_e32 v6, v5
	v_add_f32_e32 v4, v8, v6
	v_add_f32_e32 v5, v9, v7
	v_add_f32_e32 v2, v2, v3
	v_add_f32_e32 v2, v2, v5
	v_add_f32_e32 v2, v4, v2
	v_add_f32_e32 v2, v56, v2

.LBB0_1220:
	s_waitcnt vmcnt(0)
	v_cvt_f32_ubyte3_e32 v45, v6
	v_cvt_f32_ubyte2_e32 v44, v6
	v_cvt_f32_ubyte1_e32 v47, v6
	v_cvt_f32_ubyte0_e32 v46, v6
	v_mul_f32_e32 v46, s26, v46
	v_mul_f32_e32 v47, s26, v47
	v_mul_f32_e32 v44, s26, v44
	v_mul_f32_e32 v45, s26, v45
	v_fma_f32 v34, v12, v46, v34
	v_fma_f32 v35, v13, v47, v35
	v_fma_f32 v36, v10, v44, v36
	v_fma_f32 v37, v11, v45, v37
	v_cvt_f32_ubyte3_e32 v45, v7
	v_cvt_f32_ubyte2_e32 v44, v7
	v_cvt_f32_ubyte1_e32 v47, v7
	v_cvt_f32_ubyte0_e32 v46, v7
	v_mul_f32_e32 v6, s26, v46
	v_mul_f32_e32 v7, s26, v47
	v_mul_f32_e32 v44, s26, v44
	v_mul_f32_e32 v45, s26, v45
	v_fma_f32 v6, v40, v6, v4
	v_fma_f32 v7, v41, v7, v5
	v_fma_f32 v8, v38, v44, v8
	v_fma_f32 v9, v39, v45, v9
	v_cvt_pk_bf16_f32 v4, v34, v35
	v_cvt_pk_bf16_f32 v5, v36, v37
	v_cvt_pk_bf16_f32 v6, v6, v7
	v_cvt_pk_bf16_f32 v7, v8, v9
	s_mov_b64 s[20:21], 0
	global_store_dwordx4 v[2:3], v[4:7], off

.LBB0_1232:
	s_andn2_b64 vcc, exec, s[20:21]
	s_cbranch_vccnz .LBB0_1237
	s_andn2_b64 vcc, exec, s[6:7]
	s_mov_b64 s[18:19], -1
	s_cbranch_vccnz .LBB0_1235
	global_load_dwordx4 v[2:5], v[22:23], off offset:16
	global_load_dwordx4 v[6:9], v[22:23], off
	v_readlane_b32 s11, v243, 49
	s_lshl_b32 s84, s11, 1
	s_mov_b64 s[18:19], 0x6800380
	s_waitcnt vmcnt(0)
	v_mov_b32_e32 v29, v8
	v_mov_b32_e32 v8, v7
	v_mov_b32_e32 v28, v6
	v_mul_f32_e32 v6, v40, v8
	v_mul_f32_e32 v7, v41, v9
	v_mul_f32_e32 v8, v12, v8
	v_mul_f32_e32 v9, v13, v9
	v_fma_f32 v6, v12, v28, -v6
	v_fma_f32 v7, v13, v29, -v7
	v_fma_f32 v8, v40, v28, v8
	v_fma_f32 v9, v41, v29, v9
	v_mov_b32_e32 v29, v4
	v_mov_b32_e32 v4, v3
	v_mov_b32_e32 v28, v2
	v_mul_f32_e32 v2, v38, v4
	v_mul_f32_e32 v3, v39, v5
	v_mul_f32_e32 v4, v10, v4
	v_mul_f32_e32 v5, v11, v5
	v_fma_f32 v2, v10, v28, -v2
	v_fma_f32 v3, v11, v29, -v3
	v_fma_f32 v4, v38, v28, v4
	v_fma_f32 v5, v39, v29, v5
	v_cvt_pk_bf16_f32 v6, v6, v7
	v_cvt_pk_bf16_f32 v7, v2, v3
	v_cvt_pk_bf16_f32 v3, v4, v5
	v_lshl_add_u64 v[4:5], v[24:25], 0, s[84:85]
	v_lshl_add_u64 v[4:5], v[126:127], 1, v[4:5]
	v_cvt_pk_bf16_f32 v2, v8, v9
	v_lshl_add_u64 v[8:9], v[4:5], 0, s[18:19]
	v_add_co_u32_e32 v4, vcc, 0x6800000, v4
	s_mov_b64 s[18:19], 0
	s_nop 0
	v_addc_co_u32_e32 v5, vcc, 0, v5, vcc
	global_store_dwordx2 v[4:5], v[6:7], off offset:896
	global_store_dwordx2 v[8:9], v[2:3], off offset:32

.LBB0_1238:
	s_andn2_b64 vcc, exec, s[20:21]
	s_cbranch_vccnz .LBB0_1264
	s_cmp_lg_u32 s62, 1
	s_mov_b64 s[10:11], -1
	s_cbranch_scc0 .LBB0_1257
	s_andn2_b64 vcc, exec, s[14:15]
	s_cbranch_vccnz .LBB0_1294
	s_andn2_b64 vcc, exec, s[16:17]
	s_cbranch_vccnz .LBB0_1251
	s_andn2_b64 vcc, exec, s[8:9]
	s_cbranch_vccnz .LBB0_1248
	v_readlane_b32 s8, v242, 16
	v_readlane_b32 s9, v242, 17
	s_andn2_b64 vcc, exec, s[8:9]
	s_mov_b64 s[8:9], -1
	s_cbranch_vccnz .LBB0_1245
	s_mov_b32 s8, 0x3e0293ee
	v_ashrrev_i32_e32 v147, 31, v146
	v_mul_f32_e32 v4, s8, v10
	v_mul_f32_e32 v5, s8, v11
	v_mul_f32_e32 v2, s8, v12
	v_mul_f32_e32 v3, s8, v13
	v_mul_f32_e32 v8, s8, v38
	v_mul_f32_e32 v9, s8, v39
	v_mul_f32_e32 v28, s8, v40
	v_mul_f32_e32 v29, s8, v41
	v_lshl_add_u64 v[6:7], v[146:147], 1, v[30:31]
	v_cvt_pk_bf16_f32 v2, v2, v3
	v_cvt_pk_bf16_f32 v3, v4, v5
	v_cvt_pk_bf16_f32 v4, v28, v29
	v_cvt_pk_bf16_f32 v5, v8, v9
	s_mov_b64 s[8:9], 0
	global_store_dwordx4 v[6:7], v[2:5], off offset:256

.LBB0_1248:
	s_andn2_b64 vcc, exec, s[10:11]
	s_cbranch_vccnz .LBB0_1250
	s_mov_b32 s8, 0x3e38aa3b
	v_ashrrev_i32_e32 v147, 31, v146
	v_mul_f32_e32 v4, s8, v10
	v_mul_f32_e32 v5, s8, v11
	v_mul_f32_e32 v2, s8, v12
	v_mul_f32_e32 v3, s8, v13
	v_mul_f32_e32 v8, s8, v38
	v_mul_f32_e32 v9, s8, v39
	v_mul_f32_e32 v18, s8, v40
	v_mul_f32_e32 v19, s8, v41
	v_lshl_add_u64 v[6:7], v[146:147], 1, v[26:27]
	v_cvt_pk_bf16_f32 v2, v2, v3
	v_cvt_pk_bf16_f32 v3, v4, v5
	v_cvt_pk_bf16_f32 v4, v18, v19
	v_cvt_pk_bf16_f32 v5, v8, v9
	global_store_dwordx4 v[6:7], v[2:5], off offset:256

.LBB0_1251:
	s_andn2_b64 vcc, exec, s[10:11]
	s_cbranch_vccnz .LBB0_1254
	v_readlane_b32 s8, v243, 47
	v_readlane_b32 s9, v243, 48
	s_andn2_b64 vcc, exec, s[8:9]
	s_cbranch_vccnz .LBB0_1254
	global_load_dwordx4 v[2:5], v[22:23], off offset:16
	global_load_dwordx4 v[6:9], v[22:23], off
	v_lshl_add_u64 v[18:19], v[126:127], 1, v[24:25]
	s_mov_b64 s[8:9], 0x8000080
	v_lshl_add_u64 v[24:25], v[18:19], 0, s[8:9]
	s_brev_b32 s8, 16
	s_waitcnt vmcnt(0)
	v_mov_b32_e32 v23, v8
	v_mov_b32_e32 v8, v7
	v_mov_b32_e32 v22, v6
	v_mul_f32_e32 v6, v40, v8
	v_mul_f32_e32 v7, v41, v9
	v_mul_f32_e32 v8, v12, v8
	v_mul_f32_e32 v9, v13, v9
	v_fma_f32 v6, v12, v22, -v6
	v_fma_f32 v7, v13, v23, -v7
	v_fma_f32 v8, v40, v22, v8
	v_fma_f32 v9, v41, v23, v9
	v_mov_b32_e32 v23, v4
	v_mov_b32_e32 v4, v3
	v_mov_b32_e32 v22, v2
	v_mul_f32_e32 v2, v38, v4
	v_mul_f32_e32 v3, v39, v5
	v_mul_f32_e32 v4, v10, v4
	v_mul_f32_e32 v5, v11, v5
	v_fma_f32 v2, v10, v22, -v2
	v_fma_f32 v3, v11, v23, -v3
	v_fma_f32 v4, v38, v22, v4
	v_fma_f32 v5, v39, v23, v5
	v_cvt_pk_bf16_f32 v6, v6, v7
	v_cvt_pk_bf16_f32 v7, v2, v3
	v_cvt_pk_bf16_f32 v3, v4, v5
	v_add_co_u32_e32 v4, vcc, s8, v18
	v_cvt_pk_bf16_f32 v2, v8, v9
	s_nop 0
	v_addc_co_u32_e32 v5, vcc, 0, v19, vcc
	global_store_dwordx2 v[4:5], v[6:7], off offset:128
	global_store_dwordx2 v[24:25], v[2:3], off offset:32
	global_store_dwordx2 v[24:25], v[6:7], off offset:192
	global_store_dwordx2 v[24:25], v[2:3], off offset:224
	global_store_dwordx2 v[24:25], v[6:7], off offset:384
	global_store_dwordx2 v[24:25], v[2:3], off offset:416
	global_store_dwordx2 v[24:25], v[6:7], off offset:576
	global_store_dwordx2 v[24:25], v[2:3], off offset:608
	global_store_dwordx2 v[24:25], v[6:7], off offset:768
	global_store_dwordx2 v[24:25], v[2:3], off offset:800
	global_store_dwordx2 v[24:25], v[6:7], off offset:960
	global_store_dwordx2 v[24:25], v[2:3], off offset:992
	global_store_dwordx2 v[24:25], v[6:7], off offset:1152
	global_store_dwordx2 v[24:25], v[2:3], off offset:1184
	global_store_dwordx2 v[24:25], v[6:7], off offset:1344
	global_store_dwordx2 v[24:25], v[2:3], off offset:1376

.LBB0_1255:
	v_ashrrev_i32_e32 v147, 31, v146
	v_lshl_add_u64 v[6:7], v[146:147], 1, v[20:21]
	v_cvt_pk_bf16_f32 v2, v12, v13
	v_cvt_pk_bf16_f32 v3, v10, v11
	v_cvt_pk_bf16_f32 v4, v40, v41
	v_cvt_pk_bf16_f32 v5, v38, v39
	global_store_dwordx4 v[6:7], v[2:5], off offset:256
	s_nop 1
	v_mul_f32_e32 v2, v10, v10
	v_mul_f32_e32 v3, v11, v11
	v_mul_f32_e32 v4, v12, v12
	v_mul_f32_e32 v5, v13, v13
	s_nop 0
	v_pk_mov_b32 v[6:7], v[4:5], v[2:3] op_sel:[1,0]
	v_mov_b32_e32 v5, v3
	v_add_f32_e32 v2, v6, v4
	v_add_f32_e32 v3, v7, v5
	v_mul_f32_e32 v4, v38, v38
	v_mul_f32_e32 v5, v39, v39
	v_mul_f32_e32 v6, v40, v40
	v_mul_f32_e32 v7, v41, v41
	v_mov_b32_e32 v8, v4
	v_mov_b32_e32 v9, v6
	v_mov_b32_e32 v6, v5
	v_add_f32_e32 v4, v8, v6
	v_add_f32_e32 v5, v9, v7
	v_add_f32_e32 v2, v2, v3
	v_add_f32_e32 v2, v5, v2
	v_add_f32_e32 v2, v4, v2
	v_add_f32_e32 v2, v2, v56

.LBB0_1302:
	v_mov_b32_e32 v1, v171
	s_nop 1
	v_permlane32_swap_b32_e32 v171, v1
	v_add_f32_e32 v1, v171, v1
	v_div_scale_f32 v34, s[10:11], v1, v1, 1.0
	v_rcp_f32_e32 v35, v34
	v_mov_b32_e32 v39, v0
	s_mov_b64 s[10:11], 0
	v_fma_f32 v36, -v34, v35, 1.0
	v_fmac_f32_e32 v35, v36, v35
	v_div_scale_f32 v36, vcc, 1.0, v1, 1.0
	v_mul_f32_e32 v37, v36, v35
	v_fma_f32 v38, -v34, v37, v36
	v_fmac_f32_e32 v37, v38, v35
	v_fma_f32 v34, -v34, v37, v36
	v_div_fmas_f32 v34, v34, v35, v37
	v_div_fixup_f32 v34, v34, v1, 1.0
	v_lshlrev_b64 v[36:37], 10, v[198:199]
	v_lshl_add_u64 v[36:37], s[6:7], 0, v[36:37]
	v_lshlrev_b32_e32 v38, 1, v150
	v_mul_f32_e32 v18, v18, v34
	v_mul_f32_e32 v19, v19, v34
	v_mul_f32_e32 v20, v20, v34
	v_mul_f32_e32 v21, v21, v34
	v_mul_f32_e32 v2, v2, v34
	v_mul_f32_e32 v3, v3, v34
	v_mul_f32_e32 v4, v4, v34
	v_mul_f32_e32 v5, v5, v34
	v_lshl_add_u64 v[36:37], v[36:37], 0, v[38:39]
	v_cvt_pk_bf16_f32 v18, v18, v19
	v_cvt_pk_bf16_f32 v19, v20, v21
	v_cvt_pk_bf16_f32 v2, v2, v3
	v_cvt_pk_bf16_f32 v3, v4, v5
	global_store_dwordx2 v[36:37], v[18:19], off
	v_mul_f32_e32 v18, v22, v34
	v_mul_f32_e32 v19, v23, v34
	v_mul_f32_e32 v20, v24, v34
	v_mul_f32_e32 v21, v25, v34
	global_store_dwordx2 v[36:37], v[2:3], off offset:64
	v_mul_f32_e32 v2, v6, v34
	v_mul_f32_e32 v3, v7, v34
	v_mul_f32_e32 v4, v8, v34
	v_mul_f32_e32 v5, v9, v34
	v_cvt_pk_bf16_f32 v18, v18, v19
	v_cvt_pk_bf16_f32 v19, v20, v21
	v_cvt_pk_bf16_f32 v2, v2, v3
	v_cvt_pk_bf16_f32 v3, v4, v5
	global_store_dwordx2 v[36:37], v[18:19], off offset:16
	v_mul_f32_e32 v18, v26, v34
	v_mul_f32_e32 v19, v27, v34
	v_mul_f32_e32 v20, v28, v34
	v_mul_f32_e32 v21, v29, v34
	global_store_dwordx2 v[36:37], v[2:3], off offset:80
	v_mul_f32_e32 v2, v10, v34
	v_mul_f32_e32 v3, v11, v34
	v_mul_f32_e32 v4, v12, v34
	v_mul_f32_e32 v5, v13, v34
	v_cvt_pk_bf16_f32 v18, v18, v19
	v_cvt_pk_bf16_f32 v19, v20, v21
	v_cvt_pk_bf16_f32 v2, v2, v3
	v_cvt_pk_bf16_f32 v3, v4, v5
	global_store_dwordx2 v[36:37], v[18:19], off offset:32
	v_mul_f32_e32 v18, v30, v34
	v_mul_f32_e32 v19, v31, v34
	v_mul_f32_e32 v20, v32, v34
	v_mul_f32_e32 v21, v33, v34
	global_store_dwordx2 v[36:37], v[2:3], off offset:96
	v_mul_f32_e32 v2, v14, v34
	v_mul_f32_e32 v3, v15, v34
	v_mul_f32_e32 v4, v16, v34
	v_mul_f32_e32 v5, v17, v34
	v_cvt_pk_bf16_f32 v18, v18, v19
	v_cvt_pk_bf16_f32 v19, v20, v21
	v_cvt_pk_bf16_f32 v2, v2, v3
	v_cvt_pk_bf16_f32 v3, v4, v5
	s_and_b64 vcc, exec, s[8:9]
	global_store_dwordx2 v[36:37], v[18:19], off offset:48
	global_store_dwordx2 v[36:37], v[2:3], off offset:112
	s_cbranch_vccnz .LBB0_1300

.LBB0_1379:
	s_andn2_b64 vcc, exec, s[14:15]
	s_cbranch_vccnz .LBB0_1383
	v_max_f32_e32 v157, v1, v1
	s_and_b64 vcc, exec, s[42:43]
	v_max_f32_e32 v157, 0, v157
	s_cbranch_vccnz .LBB0_1382
	v_exp_f32_e64 v158, -v157
	s_nop 0
	v_mul_f32_e32 v171, v171, v158
	v_mul_f32_e32 v32, v32, v158
	v_mul_f32_e32 v33, v33, v158
	v_mul_f32_e32 v30, v30, v158
	v_mul_f32_e32 v31, v31, v158
	v_mul_f32_e32 v28, v28, v158
	v_mul_f32_e32 v29, v29, v158
	v_mul_f32_e32 v26, v26, v158
	v_mul_f32_e32 v27, v27, v158
	v_mul_f32_e32 v24, v24, v158
	v_mul_f32_e32 v25, v25, v158
	v_mul_f32_e32 v22, v22, v158
	v_mul_f32_e32 v23, v23, v158
	v_mul_f32_e32 v20, v20, v158
	v_mul_f32_e32 v21, v21, v158
	v_mul_f32_e32 v18, v18, v158
	v_mul_f32_e32 v19, v19, v158
	v_mul_f32_e32 v16, v16, v158
	v_mul_f32_e32 v17, v17, v158
	v_mul_f32_e32 v14, v14, v158
	v_mul_f32_e32 v15, v15, v158
	v_mul_f32_e32 v12, v12, v158
	v_mul_f32_e32 v13, v13, v158
	v_mul_f32_e32 v10, v10, v158
	v_mul_f32_e32 v11, v11, v158
	v_mul_f32_e32 v8, v8, v158
	v_mul_f32_e32 v9, v9, v158
	v_mul_f32_e32 v6, v6, v158
	v_mul_f32_e32 v7, v7, v158
	v_mul_f32_e32 v4, v4, v158
	v_mul_f32_e32 v5, v5, v158
	v_mul_f32_e32 v2, v2, v158
	v_mul_f32_e32 v3, v3, v158

.LBB0_1392:
	v_exp_f32_e32 v66, v66
	v_exp_f32_e32 v67, v67
	v_exp_f32_e32 v161, v70
	s_mul_i32 s16, s42, 0x2400
	v_add_f32_e32 v1, 0, v66
	v_cvt_pk_bf16_f32 v70, v66, v67
	v_exp_f32_e32 v66, v82
	v_exp_f32_e32 v159, v68
	v_exp_f32_e32 v69, v69
	v_exp_f32_e32 v163, v71
	v_exp_f32_e32 v165, v72
	v_exp_f32_e32 v167, v73
	v_exp_f32_e32 v179, v78
	v_exp_f32_e32 v181, v79
	v_add_f32_e32 v78, v66, v0
	v_add_f32_e32 v79, v67, v1
	v_add_u32_e32 v1, s16, v217
	v_exp_f32_e32 v158, v83
	v_exp_f32_e32 v68, v84
	v_exp_f32_e32 v160, v85
	v_exp_f32_e32 v162, v86
	v_exp_f32_e32 v164, v87
	v_exp_f32_e32 v166, v88
	v_exp_f32_e32 v168, v89
	ds_read_b128 v[82:85], v1 offset:26624
	ds_read_b128 v[86:89], v1 offset:26656
	v_cvt_pk_bf16_f32 v71, v159, v69
	v_cvt_pk_bf16_f32 v72, v161, v163
	v_cvt_pk_bf16_f32 v73, v165, v167
	v_add_f32_e32 v78, v158, v78
	v_add_f32_e32 v79, v159, v79
	v_exp_f32_e32 v169, v74
	s_waitcnt lgkmcnt(1)
	v_mfma_f32_32x32x16_bf16 v[18:33], v[82:85], v[70:73], v[18:33]
	v_add_f32_e64 v78, v68, v78
	v_add_f32_e64 v79, v69, v79
	v_exp_f32_e32 v173, v75
	v_add_f32_e32 v78, v160, v78
	v_add_f32_e32 v79, v161, v79
	v_exp_f32_e32 v175, v76
	v_exp_f32_e32 v177, v77
	v_exp_f32_e32 v183, v80
	v_exp_f32_e32 v185, v81
	v_exp_f32_e32 v172, v90
	v_add_f32_e32 v78, v162, v78
	v_add_f32_e32 v79, v163, v79
	v_exp_f32_e32 v174, v91
	v_add_f32_e32 v78, v164, v78
	v_add_f32_e32 v79, v165, v79
	v_exp_f32_e32 v176, v92
	v_add_f32_e32 v78, v166, v78
	v_add_f32_e32 v79, v167, v79
	v_exp_f32_e32 v178, v93
	v_add_f32_e32 v78, v168, v78
	v_add_f32_e32 v79, v169, v79
	v_cvt_pk_bf16_f32 v74, v169, v173
	v_cvt_pk_bf16_f32 v75, v175, v177
	v_cvt_pk_bf16_f32 v76, v179, v181
	v_cvt_pk_bf16_f32 v77, v183, v185
	v_exp_f32_e32 v180, v94
	v_add_f32_e32 v78, v172, v78
	v_add_f32_e32 v79, v173, v79
	ds_read_b128 v[82:85], v1 offset:26688
	v_exp_f32_e32 v182, v95
	v_add_f32_e32 v78, v174, v78
	v_add_f32_e32 v79, v175, v79
	s_waitcnt lgkmcnt(1)
	v_mfma_f32_32x32x16_bf16 v[18:33], v[86:89], v[74:77], v[18:33]
	v_exp_f32_e32 v184, v96
	v_add_f32_e32 v78, v176, v78
	v_add_f32_e32 v79, v177, v79
	v_exp_f32_e32 v170, v97
	v_add_f32_e32 v78, v178, v78
	v_add_f32_e32 v79, v179, v79
	v_cvt_pk_bf16_f32 v80, v162, v164
	v_add_f32_e32 v78, v180, v78
	v_add_f32_e32 v79, v181, v79
	v_cvt_pk_bf16_f32 v81, v166, v168
	v_add_f32_e32 v78, v182, v78
	v_add_f32_e32 v79, v183, v79
	v_cvt_pk_bf16_f32 v67, v176, v178
	v_add_f32_e32 v78, v184, v78
	v_add_f32_e32 v79, v185, v79
	v_cvt_pk_bf16_f32 v69, v184, v170
	v_add_f32_e32 v78, v170, v78
	v_add_f32_e32 v79, v171, v79
	s_nop 0
	v_add_f32_e32 v171, v78, v79
	v_cvt_pk_bf16_f32 v78, v66, v158
	v_cvt_pk_bf16_f32 v79, v68, v160
	v_cvt_pk_bf16_f32 v66, v172, v174
	v_cvt_pk_bf16_f32 v68, v180, v182
	s_waitcnt lgkmcnt(0)
	v_mfma_f32_32x32x16_bf16 v[18:33], v[82:85], v[78:81], v[18:33]
	ds_read_b128 v[82:85], v1 offset:26720
	s_waitcnt lgkmcnt(0)
	v_mfma_f32_32x32x16_bf16 v[18:33], v[82:85], v[66:69], v[18:33]
	ds_read_b128 v[82:85], v1 offset:31232
	s_waitcnt lgkmcnt(0)
	v_mfma_f32_32x32x16_bf16 v[2:17], v[82:85], v[70:73], v[2:17]
	ds_read_b128 v[70:73], v1 offset:31264
	s_waitcnt lgkmcnt(0)
	v_mfma_f32_32x32x16_bf16 v[2:17], v[70:73], v[74:77], v[2:17]
	ds_read_b128 v[70:73], v1 offset:31296
	s_waitcnt lgkmcnt(0)
	v_mfma_f32_32x32x16_bf16 v[2:17], v[70:73], v[78:81], v[2:17]
	ds_read_b128 v[70:73], v1 offset:31328
	s_waitcnt lgkmcnt(0)
	v_mfma_f32_32x32x16_bf16 v[2:17], v[70:73], v[66:69], v[2:17]
	s_andn2_b64 vcc, exec, s[12:13]
	s_cbranch_vccnz .LBB0_1387

.LBB0_1400:
	ds_bpermute_b32 v34, v111, v117
	v_mov_b32_e32 v101, v0
	s_add_i32 s18, s18, s78
	s_add_i32 s17, s17, s78
	s_cmpk_gt_i32 s18, 0x1ff
	s_waitcnt lgkmcnt(0)
	v_add_f32_e32 v34, v117, v34
	v_div_scale_f32 v35, s[0:1], v34, v34, 1.0
	v_rcp_f32_e32 v36, v35
	s_nop 0
	v_fma_f32 v37, -v35, v36, 1.0
	v_fmac_f32_e32 v36, v37, v36
	v_div_scale_f32 v37, vcc, 1.0, v34, 1.0
	v_mul_f32_e32 v38, v37, v36
	v_fma_f32 v39, -v35, v38, v37
	v_fmac_f32_e32 v38, v39, v36
	v_fma_f32 v35, -v35, v38, v37
	v_div_fmas_f32 v35, v35, v36, v38
	v_div_fixup_f32 v34, v35, v34, 1.0
	v_mul_f32_e32 v18, v18, v34
	v_mul_f32_e32 v19, v19, v34
	v_mul_f32_e32 v20, v20, v34
	v_mul_f32_e32 v21, v21, v34
	v_mul_f32_e32 v2, v2, v34
	v_mul_f32_e32 v3, v3, v34
	v_mul_f32_e32 v4, v4, v34
	v_mul_f32_e32 v5, v5, v34
	v_lshl_add_u64 v[36:37], v[102:103], 0, v[100:101]
	v_cvt_pk_bf16_f32 v18, v18, v19
	v_cvt_pk_bf16_f32 v19, v20, v21
	v_cvt_pk_bf16_f32 v2, v2, v3
	v_cvt_pk_bf16_f32 v3, v4, v5
	global_store_dwordx2 v[36:37], v[18:19], off
	v_mul_f32_e32 v18, v22, v34
	v_mul_f32_e32 v19, v23, v34
	v_mul_f32_e32 v20, v24, v34
	v_mul_f32_e32 v21, v25, v34
	global_store_dwordx2 v[36:37], v[2:3], off offset:64
	v_mul_f32_e32 v2, v6, v34
	v_mul_f32_e32 v3, v7, v34
	v_mul_f32_e32 v4, v8, v34
	v_mul_f32_e32 v5, v9, v34
	v_cvt_pk_bf16_f32 v18, v18, v19
	v_cvt_pk_bf16_f32 v19, v20, v21
	v_cvt_pk_bf16_f32 v2, v2, v3
	v_cvt_pk_bf16_f32 v3, v4, v5
	global_store_dwordx2 v[36:37], v[18:19], off offset:16
	v_mul_f32_e32 v18, v26, v34
	v_mul_f32_e32 v19, v27, v34
	v_mul_f32_e32 v20, v28, v34
	v_mul_f32_e32 v21, v29, v34
	global_store_dwordx2 v[36:37], v[2:3], off offset:80
	v_mul_f32_e32 v2, v10, v34
	v_mul_f32_e32 v3, v11, v34
	v_mul_f32_e32 v4, v12, v34
	v_mul_f32_e32 v5, v13, v34
	v_cvt_pk_bf16_f32 v18, v18, v19
	v_cvt_pk_bf16_f32 v19, v20, v21
	v_cvt_pk_bf16_f32 v2, v2, v3
	v_cvt_pk_bf16_f32 v3, v4, v5
	global_store_dwordx2 v[36:37], v[18:19], off offset:32
	v_mul_f32_e32 v18, v30, v34
	v_mul_f32_e32 v19, v31, v34
	v_mul_f32_e32 v20, v32, v34
	v_mul_f32_e32 v21, v33, v34
	global_store_dwordx2 v[36:37], v[2:3], off offset:96
	v_mul_f32_e32 v2, v14, v34
	v_mul_f32_e32 v3, v15, v34
	v_mul_f32_e32 v4, v16, v34
	v_mul_f32_e32 v5, v17, v34
	v_cvt_pk_bf16_f32 v18, v18, v19
	v_cvt_pk_bf16_f32 v19, v20, v21
	v_cvt_pk_bf16_f32 v2, v2, v3
	v_cvt_pk_bf16_f32 v3, v4, v5
	global_store_dwordx2 v[36:37], v[18:19], off offset:48
	global_store_dwordx2 v[36:37], v[2:3], off offset:112
	s_cbranch_scc1 .LBB0_1453

.LBB0_1446:
	s_or_b64 exec, exec, s[6:7]
	v_add_u32_e32 v64, 0xffffff81, v101
	v_cmp_gt_u32_e32 vcc, s91, v64
	s_waitcnt lgkmcnt(1)
	v_add_f32_e32 v48, v48, v63
	v_add_u32_e32 v63, 0xffffff82, v101
	v_cndmask_b32_e32 v48, v213, v48, vcc
	v_cmp_gt_u32_e32 vcc, s91, v63
	v_add_f32_e32 v47, v47, v137
	v_add_u32_e32 v63, 0xffffff83, v101
	v_cndmask_b32_e32 v47, v213, v47, vcc
	v_cmp_gt_u32_e32 vcc, s91, v63
	v_add_f32_e32 v46, v46, v136
	v_add_u32_e32 v63, 0xffffff88, v101
	v_cndmask_b32_e32 v46, v213, v46, vcc
	v_cmp_gt_u32_e32 vcc, s91, v63
	v_add_f32_e32 v45, v45, v135
	v_add_f32_e32 v44, v44, v134
	v_cndmask_b32_e32 v63, v213, v45, vcc
	v_add_u32_e32 v45, 0xffffff89, v101
	v_cmp_gt_u32_e32 vcc, s91, v45
	v_add_f32_e32 v43, v43, v133
	v_add_f32_e32 v42, v42, v132
	v_cndmask_b32_e32 v134, v213, v44, vcc
	v_add_u32_e32 v44, 0xffffff8a, v101
	v_cmp_gt_u32_e32 vcc, s91, v44
	v_add_f32_e32 v41, v41, v131
	v_add_f32_e32 v40, v40, v130
	v_cndmask_b32_e32 v133, v213, v43, vcc
	v_add_u32_e32 v43, 0xffffff8b, v101
	v_cmp_gt_u32_e32 vcc, s91, v43
	v_add_f32_e32 v39, v39, v129
	v_add_f32_e32 v38, v38, v128
	v_cndmask_b32_e32 v64, v213, v42, vcc
	v_add_u32_e32 v42, 0xffffff90, v101
	v_cmp_gt_u32_e32 vcc, s91, v42
	v_add_u32_e32 v42, 0xffffff91, v101
	v_add_f32_e32 v37, v37, v127
	v_cndmask_b32_e32 v41, v213, v41, vcc
	v_cmp_gt_u32_e32 vcc, s91, v42
	v_add_f32_e32 v36, v36, v51
	v_add_f32_e32 v35, v35, v126
	v_cndmask_b32_e32 v44, v213, v40, vcc
	v_add_u32_e32 v40, 0xffffff92, v101
	v_cmp_gt_u32_e32 vcc, s91, v40
	v_add_f32_e32 v34, v34, v125
	s_nop 0
	v_cndmask_b32_e32 v45, v213, v39, vcc
	v_add_u32_e32 v39, 0xffffff93, v101
	v_cmp_gt_u32_e32 vcc, s91, v39
	v_max_f32_e32 v39, v50, v50
	s_nop 0
	v_cndmask_b32_e32 v42, v213, v38, vcc
	v_add_u32_e32 v38, 0xffffff98, v101
	v_cmp_gt_u32_e32 vcc, s91, v38
	s_nop 1
	v_cndmask_b32_e32 v40, v213, v37, vcc
	v_add_u32_e32 v37, 0xffffff99, v101
	v_cmp_gt_u32_e32 vcc, s91, v37
	v_max_f32_e32 v37, v122, v122
	v_max_f32_e32 v39, v39, v40
	v_cndmask_b32_e32 v38, v213, v36, vcc
	v_add_u32_e32 v36, 0xffffff9a, v101
	v_cmp_gt_u32_e32 vcc, s91, v36
	v_add_u32_e32 v36, 0xffffff9b, v101
	v_max_f32_e32 v37, v37, v38
	v_cndmask_b32_e32 v35, v213, v35, vcc
	v_cmp_gt_u32_e32 vcc, s91, v36
	v_add_u32_e32 v36, 0xffffff80, v101
	s_nop 0
	v_cndmask_b32_e32 v34, v213, v34, vcc
	v_cmp_gt_u32_e32 vcc, s91, v36
	s_waitcnt lgkmcnt(0)
	v_add_f32_e32 v36, v49, v62
	v_cndmask_b32_e32 v49, v213, v36, vcc
	v_max_f32_e32 v36, v120, v120
	v_max_f32_e32 v36, v36, v35
	v_max3_f32 v36, v121, v34, v36
	v_max3_f32 v36, v36, v37, v39
	v_max_f32_e32 v37, v123, v123
	v_max_f32_e32 v39, v52, v52
	v_max_f32_e32 v37, v37, v42
	v_max_f32_e32 v39, v39, v45
	v_max3_f32 v36, v36, v37, v39
	v_max_f32_e32 v37, v124, v124
	v_max_f32_e32 v39, v53, v53
	v_max_f32_e32 v37, v37, v44
	v_max_f32_e32 v39, v39, v41
	v_max3_f32 v36, v36, v37, v39
	v_max_f32_e32 v37, v57, v57
	v_max_f32_e32 v39, v54, v54
	v_max_f32_e32 v37, v37, v64
	v_max_f32_e32 v39, v39, v133
	v_max3_f32 v36, v36, v37, v39
	v_max_f32_e32 v37, v59, v59
	v_max_f32_e32 v39, v55, v55
	v_max_f32_e32 v37, v37, v134
	v_max_f32_e32 v39, v39, v63
	v_max3_f32 v36, v36, v37, v39
	v_max_f32_e32 v37, v60, v60
	v_max_f32_e32 v39, v56, v56
	v_max_f32_e32 v37, v37, v46
	v_max_f32_e32 v39, v39, v47
	v_max3_f32 v36, v36, v37, v39
	v_max_f32_e32 v37, v61, v61
	v_max_f32_e32 v39, v58, v58
	v_max_f32_e32 v37, v37, v48
	v_max_f32_e32 v39, v39, v49
	v_max3_f32 v36, v36, v37, v39
	ds_bpermute_b32 v37, v111, v36
	s_waitcnt lgkmcnt(0)
	v_max3_f32 v51, v119, v36, v37
	v_sub_f32_e32 v34, v34, v51
	v_sub_f32_e32 v36, v121, v51
	v_exp_f32_e32 v127, v34
	v_sub_f32_e32 v34, v120, v51
	v_exp_f32_e32 v126, v36
	v_exp_f32_e32 v36, v34
	v_sub_f32_e32 v34, v35, v51
	v_sub_f32_e32 v35, v122, v51
	v_exp_f32_e32 v128, v35
	v_sub_f32_e32 v35, v38, v51
	v_exp_f32_e32 v129, v35
	v_sub_f32_e32 v35, v50, v51
	v_exp_f32_e32 v38, v35
	v_sub_f32_e32 v35, v40, v51
	v_exp_f32_e32 v40, v35
	v_sub_f32_e32 v35, v123, v51
	v_exp_f32_e32 v130, v35
	v_sub_f32_e32 v35, v42, v51
	v_exp_f32_e32 v131, v35
	v_sub_f32_e32 v35, v52, v51
	v_exp_f32_e32 v42, v35
	v_sub_f32_e32 v35, v45, v51
	v_exp_f32_e32 v52, v35
	v_sub_f32_e32 v35, v124, v51
	v_exp_f32_e32 v132, v35
	v_sub_f32_e32 v35, v44, v51
	v_exp_f32_e32 v135, v35
	v_sub_f32_e32 v35, v53, v51
	v_exp_f32_e32 v44, v35
	v_sub_f32_e32 v35, v41, v51
	v_exp_f32_e32 v62, v35
	v_sub_f32_e32 v35, v57, v51
	v_exp_f32_e32 v136, v35
	v_sub_f32_e32 v35, v64, v51
	v_exp_f32_e32 v137, v35
	v_sub_f32_e32 v35, v54, v51
	v_exp_f32_e32 v64, v35
	v_sub_f32_e32 v35, v133, v51
	v_exp_f32_e32 v54, v35
	v_sub_f32_e32 v35, v59, v51
	v_exp_f32_e32 v133, v35
	v_sub_f32_e32 v35, v134, v51
	v_exp_f32_e32 v134, v35
	v_sub_f32_e32 v35, v55, v51
	v_exp_f32_e32 v120, v35
	v_sub_f32_e32 v35, v63, v51
	v_exp_f32_e32 v122, v35
	v_sub_f32_e32 v35, v60, v51
	v_exp_f32_e32 v138, v35
	v_sub_f32_e32 v35, v46, v51
	v_exp_f32_e32 v139, v35
	v_sub_f32_e32 v35, v56, v51
	v_exp_f32_e32 v56, v35
	v_sub_f32_e32 v35, v47, v51
	v_exp_f32_e32 v60, v35
	v_sub_f32_e32 v35, v61, v51
	v_exp_f32_e32 v34, v34
	v_exp_f32_e32 v140, v35
	v_sub_f32_e32 v35, v48, v51
	v_exp_f32_e32 v141, v35
	v_sub_f32_e32 v35, v58, v51
	v_exp_f32_e32 v58, v35
	v_sub_f32_e32 v35, v49, v51
	v_add_f32_e32 v37, v126, v127
	v_exp_f32_e32 v124, v35
	v_mov_b32_e32 v35, v0
	v_add_f32_e32 v46, v36, v34
	v_add_f32_e32 v47, v37, v35
	v_add_f32_e32 v39, v128, v129
	v_add_f32_e32 v47, v46, v47
	v_add_f32_e32 v46, v46, v46
	v_mov_b32_e32 v41, v47
	v_add_f32_e32 v46, v38, v40
	v_add_f32_e32 v47, v39, v41
	v_add_f32_e32 v43, v130, v131
	v_add_f32_e32 v47, v46, v47
	v_add_f32_e32 v46, v46, v46
	v_mov_b32_e32 v53, v47
	v_add_f32_e32 v46, v42, v52
	v_add_f32_e32 v47, v43, v53
	v_add_f32_e32 v45, v132, v135
	v_add_f32_e32 v47, v46, v47
	v_add_f32_e32 v46, v46, v46
	v_mov_b32_e32 v63, v47
	v_add_f32_e32 v46, v44, v62
	v_add_f32_e32 v47, v45, v63
	v_add_f32_e32 v65, v136, v137
	v_add_f32_e32 v47, v46, v47
	v_add_f32_e32 v46, v46, v46
	v_mov_b32_e32 v55, v47
	v_add_f32_e32 v46, v64, v54
	v_add_f32_e32 v47, v65, v55
	v_add_f32_e32 v121, v133, v134
	v_add_f32_e32 v47, v46, v47
	v_add_f32_e32 v46, v46, v46
	v_mov_b32_e32 v123, v47
	v_add_f32_e32 v46, v120, v122
	v_add_f32_e32 v47, v121, v123
	v_add_f32_e32 v57, v138, v139
	v_add_f32_e32 v47, v46, v47
	v_add_f32_e32 v46, v46, v46
	v_mov_b32_e32 v61, v47
	v_add_f32_e32 v46, v56, v60
	v_add_f32_e32 v47, v57, v61
	v_sub_f32_e32 v119, v119, v51
	v_add_f32_e32 v47, v46, v47
	v_add_f32_e32 v46, v46, v46
	v_add_f32_e32 v59, v140, v141
	v_mov_b32_e32 v125, v47
	v_exp_f32_e32 v50, v119
	v_add_f32_e32 v46, v58, v124
	v_add_f32_e32 v47, v59, v125
	v_cvt_pk_bf16_f32 v49, v132, v44
	v_add_f32_e32 v53, v46, v47
	v_cvt_pk_bf16_f32 v46, v126, v36
	v_cvt_pk_bf16_f32 v47, v128, v38
	v_cvt_pk_bf16_f32 v44, v138, v56
	v_cvt_pk_bf16_f32 v45, v140, v58
	v_cvt_pk_bf16_f32 v38, v127, v34
	v_cvt_pk_bf16_f32 v34, v137, v54
	v_cvt_pk_bf16_f32 v36, v139, v60
	ds_read_b128 v[54:57], v118 offset:18432
	ds_read_b128 v[58:61], v118 offset:18464
	v_mul_f32_e32 v18, v18, v50
	v_mul_f32_e32 v19, v19, v50
	v_mul_f32_e32 v20, v20, v50
	v_mul_f32_e32 v21, v21, v50
	v_mul_f32_e32 v22, v22, v50
	v_mul_f32_e32 v23, v23, v50
	v_mul_f32_e32 v24, v24, v50
	v_mul_f32_e32 v25, v25, v50
	v_mul_f32_e32 v26, v26, v50
	v_mul_f32_e32 v27, v27, v50
	v_mul_f32_e32 v28, v28, v50
	v_mul_f32_e32 v29, v29, v50
	v_mul_f32_e32 v30, v30, v50
	v_mul_f32_e32 v31, v31, v50
	v_mul_f32_e32 v32, v32, v50
	v_mul_f32_e32 v33, v33, v50
	v_cvt_pk_bf16_f32 v48, v130, v42
	v_cvt_pk_bf16_f32 v42, v136, v64
	v_cvt_pk_bf16_f32 v43, v133, v120
	s_waitcnt lgkmcnt(1)
	v_mfma_f32_32x32x16_bf16 v[18:33], v[54:57], v[46:49], v[18:33]
	ds_read_b128 v[54:57], v118 offset:18496
	v_cvt_pk_bf16_f32 v39, v129, v40
	v_cvt_pk_bf16_f32 v40, v131, v52
	v_cvt_pk_bf16_f32 v41, v135, v62
	v_cvt_pk_bf16_f32 v35, v134, v122
	v_cvt_pk_bf16_f32 v37, v141, v124
	v_mul_f32_e32 v2, v2, v50
	v_mul_f32_e32 v3, v3, v50
	s_waitcnt lgkmcnt(1)
	v_mfma_f32_32x32x16_bf16 v[18:33], v[58:61], v[42:45], v[18:33]
	v_mul_f32_e64 v4, v4, v50
	v_mul_f32_e64 v5, v5, v50
	v_mul_f32_e64 v6, v6, v50
	v_mul_f32_e64 v7, v7, v50
	v_mul_f32_e64 v8, v8, v50
	v_mul_f32_e64 v9, v9, v50
	v_mul_f32_e32 v10, v10, v50
	v_mul_f32_e32 v11, v11, v50
	v_mul_f32_e32 v12, v12, v50
	v_mul_f32_e32 v13, v13, v50
	v_mul_f32_e32 v14, v14, v50
	v_mul_f32_e32 v15, v15, v50
	v_mul_f32_e32 v16, v16, v50
	v_mul_f32_e32 v17, v17, v50
	s_waitcnt lgkmcnt(0)
	v_mfma_f32_32x32x16_bf16 v[18:33], v[54:57], v[38:41], v[18:33]
	ds_read_b128 v[54:57], v118 offset:18528
	v_fmac_f32_e32 v53, v117, v50
	v_mov_b32_e32 v119, v51
	v_mov_b32_e32 v117, v53
	s_waitcnt lgkmcnt(0)
	v_mfma_f32_32x32x16_bf16 v[18:33], v[54:57], v[34:37], v[18:33]
	ds_read_b128 v[54:57], v118 offset:23040
	s_waitcnt lgkmcnt(0)
	v_mfma_f32_32x32x16_bf16 v[2:17], v[54:57], v[46:49], v[2:17]
	ds_read_b128 v[46:49], v118 offset:23072
	s_waitcnt lgkmcnt(0)
	v_mfma_f32_32x32x16_bf16 v[2:17], v[46:49], v[42:45], v[2:17]
	ds_read_b128 v[42:45], v118 offset:23104
	s_waitcnt lgkmcnt(0)
	v_mfma_f32_32x32x16_bf16 v[2:17], v[42:45], v[38:41], v[2:17]
	ds_read_b128 v[38:41], v118 offset:23136
	s_waitcnt lgkmcnt(0)
	v_mfma_f32_32x32x16_bf16 v[2:17], v[38:41], v[34:37], v[2:17]

.LBB0_1455:
	ds_bpermute_b32 v67, v182, v66
	v_mov_b32_e32 v165, v0
	s_add_i32 s13, s13, s78
	s_waitcnt lgkmcnt(0)
	v_add_f32_e32 v66, v66, v67
	v_div_scale_f32 v67, s[0:1], v66, v66, 1.0
	v_rcp_f32_e32 v68, v67
	v_readlane_b32 s0, v243, 5
	s_add_i32 s12, s12, s0
	s_cmpk_gt_i32 s13, 0xff
	v_fma_f32 v69, -v67, v68, 1.0
	v_fmac_f32_e32 v68, v69, v68
	v_div_scale_f32 v69, vcc, 1.0, v66, 1.0
	v_mul_f32_e32 v70, v69, v68
	v_fma_f32 v71, -v67, v70, v69
	v_fmac_f32_e32 v70, v71, v68
	v_fma_f32 v67, -v67, v70, v69
	v_div_fmas_f32 v67, v67, v68, v70
	v_div_fixup_f32 v66, v67, v66, 1.0
	v_mul_f32_e32 v50, v50, v66
	v_mul_f32_e32 v51, v51, v66
	v_mul_f32_e32 v52, v52, v66
	v_mul_f32_e32 v53, v53, v66
	v_mul_f32_e32 v34, v34, v66
	v_mul_f32_e32 v35, v35, v66
	v_mul_f32_e32 v36, v36, v66
	v_mul_f32_e32 v37, v37, v66
	v_mul_f32_e32 v18, v18, v66
	v_mul_f32_e32 v19, v19, v66
	v_mul_f32_e32 v20, v20, v66
	v_mul_f32_e32 v21, v21, v66
	v_mul_f32_e32 v2, v2, v66
	v_mul_f32_e32 v3, v3, v66
	v_mul_f32_e32 v4, v4, v66
	v_mul_f32_e32 v5, v5, v66
	v_lshl_add_u64 v[68:69], v[166:167], 0, v[164:165]
	v_cvt_pk_bf16_f32 v50, v50, v51
	v_cvt_pk_bf16_f32 v51, v52, v53
	v_cvt_pk_bf16_f32 v34, v34, v35
	v_cvt_pk_bf16_f32 v35, v36, v37
	v_cvt_pk_bf16_f32 v18, v18, v19
	v_cvt_pk_bf16_f32 v19, v20, v21
	v_cvt_pk_bf16_f32 v2, v2, v3
	v_cvt_pk_bf16_f32 v3, v4, v5
	global_store_dwordx2 v[68:69], v[50:51], off
	v_mul_f32_e32 v50, v54, v66
	v_mul_f32_e32 v51, v55, v66
	v_mul_f32_e32 v52, v56, v66
	v_mul_f32_e32 v53, v57, v66
	global_store_dwordx2 v[68:69], v[34:35], off offset:64
	v_mul_f32_e32 v34, v38, v66
	v_mul_f32_e32 v35, v39, v66
	v_mul_f32_e32 v36, v40, v66
	v_mul_f32_e32 v37, v41, v66
	global_store_dwordx2 v[68:69], v[18:19], off offset:128
	v_mul_f32_e32 v18, v22, v66
	v_mul_f32_e32 v19, v23, v66
	v_mul_f32_e32 v20, v24, v66
	v_mul_f32_e32 v21, v25, v66
	global_store_dwordx2 v[68:69], v[2:3], off offset:192
	v_mul_f32_e32 v2, v6, v66
	v_mul_f32_e32 v3, v7, v66
	v_mul_f32_e32 v4, v8, v66
	v_mul_f32_e32 v5, v9, v66
	v_cvt_pk_bf16_f32 v50, v50, v51
	v_cvt_pk_bf16_f32 v51, v52, v53
	v_cvt_pk_bf16_f32 v34, v34, v35
	v_cvt_pk_bf16_f32 v35, v36, v37
	v_cvt_pk_bf16_f32 v18, v18, v19
	v_cvt_pk_bf16_f32 v19, v20, v21
	v_cvt_pk_bf16_f32 v2, v2, v3
	v_cvt_pk_bf16_f32 v3, v4, v5
	global_store_dwordx2 v[68:69], v[50:51], off offset:16
	v_mul_f32_e32 v50, v58, v66
	v_mul_f32_e32 v51, v59, v66
	v_mul_f32_e32 v52, v60, v66
	v_mul_f32_e32 v53, v61, v66
	global_store_dwordx2 v[68:69], v[34:35], off offset:80
	v_mul_f32_e32 v34, v42, v66
	v_mul_f32_e32 v35, v43, v66
	v_mul_f32_e32 v36, v44, v66
	v_mul_f32_e32 v37, v45, v66
	global_store_dwordx2 v[68:69], v[18:19], off offset:144
	v_mul_f32_e32 v18, v26, v66
	v_mul_f32_e32 v19, v27, v66
	v_mul_f32_e32 v20, v28, v66
	v_mul_f32_e32 v21, v29, v66
	global_store_dwordx2 v[68:69], v[2:3], off offset:208
	v_mul_f32_e32 v2, v10, v66
	v_mul_f32_e32 v3, v11, v66
	v_mul_f32_e32 v4, v12, v66
	v_mul_f32_e32 v5, v13, v66
	v_cvt_pk_bf16_f32 v50, v50, v51
	v_cvt_pk_bf16_f32 v51, v52, v53
	v_cvt_pk_bf16_f32 v34, v34, v35
	v_cvt_pk_bf16_f32 v35, v36, v37
	v_cvt_pk_bf16_f32 v18, v18, v19
	v_cvt_pk_bf16_f32 v19, v20, v21
	v_cvt_pk_bf16_f32 v2, v2, v3
	v_cvt_pk_bf16_f32 v3, v4, v5
	global_store_dwordx2 v[68:69], v[50:51], off offset:32
	v_mul_f32_e32 v50, v62, v66
	v_mul_f32_e32 v51, v63, v66
	v_mul_f32_e32 v52, v64, v66
	v_mul_f32_e32 v53, v65, v66
	global_store_dwordx2 v[68:69], v[34:35], off offset:96
	v_mul_f32_e32 v34, v46, v66
	v_mul_f32_e32 v35, v47, v66
	v_mul_f32_e32 v36, v48, v66
	v_mul_f32_e32 v37, v49, v66
	global_store_dwordx2 v[68:69], v[18:19], off offset:160
	v_mul_f32_e32 v18, v30, v66
	v_mul_f32_e32 v19, v31, v66
	v_mul_f32_e32 v20, v32, v66
	v_mul_f32_e32 v21, v33, v66
	global_store_dwordx2 v[68:69], v[2:3], off offset:224
	v_mul_f32_e32 v2, v14, v66
	v_mul_f32_e32 v3, v15, v66
	v_mul_f32_e32 v4, v16, v66
	v_mul_f32_e32 v5, v17, v66
	v_cvt_pk_bf16_f32 v50, v50, v51
	v_cvt_pk_bf16_f32 v51, v52, v53
	v_cvt_pk_bf16_f32 v34, v34, v35
	v_cvt_pk_bf16_f32 v35, v36, v37
	v_cvt_pk_bf16_f32 v18, v18, v19
	v_cvt_pk_bf16_f32 v19, v20, v21
	v_cvt_pk_bf16_f32 v2, v2, v3
	v_cvt_pk_bf16_f32 v3, v4, v5
	global_store_dwordx2 v[68:69], v[50:51], off offset:48
	global_store_dwordx2 v[68:69], v[34:35], off offset:112
	global_store_dwordx2 v[68:69], v[18:19], off offset:176
	global_store_dwordx2 v[68:69], v[2:3], off offset:240
	s_cbranch_scc1 .LBB0_1478

.LBB0_1470:
	s_and_b32 s4, s16, 1
	s_mul_i32 s5, s4, 0x4400
	v_add_u32_e32 v163, s5, v181
	ds_read_b128 v[66:69], v163 offset:8704
	ds_read_b128 v[70:73], v163
	ds_read_b128 v[186:189], v163 offset:32
	ds_read_b128 v[190:193], v163 offset:8736
	s_mul_i32 s5, s4, 0x4800
	v_add_u32_e32 v201, s5, v183
	s_waitcnt lgkmcnt(2)
	v_mfma_f32_32x32x16_bf16 v[82:97], v[70:73], v[98:101], 0
	s_andn2_b64 vcc, exec, s[2:3]
	v_mfma_f32_32x32x16_bf16 v[66:81], v[66:69], v[98:101], 0
	s_waitcnt lgkmcnt(1)
	v_mfma_f32_32x32x16_bf16 v[82:97], v[186:189], v[102:105], v[82:97]
	s_waitcnt lgkmcnt(0)
	v_mfma_f32_32x32x16_bf16 v[66:81], v[190:193], v[102:105], v[66:81]
	ds_read_b128 v[186:189], v163 offset:64
	ds_read_b128 v[190:193], v163 offset:8768
	s_waitcnt lgkmcnt(1)
	v_mfma_f32_32x32x16_bf16 v[82:97], v[186:189], v[106:109], v[82:97]
	s_waitcnt lgkmcnt(0)
	v_mfma_f32_32x32x16_bf16 v[66:81], v[190:193], v[106:109], v[66:81]
	ds_read_b128 v[186:189], v163 offset:96
	ds_read_b128 v[190:193], v163 offset:8800
	s_waitcnt lgkmcnt(1)
	v_mfma_f32_32x32x16_bf16 v[82:97], v[186:189], v[110:113], v[82:97]
	s_waitcnt lgkmcnt(0)
	v_mfma_f32_32x32x16_bf16 v[66:81], v[190:193], v[110:113], v[66:81]
	ds_read_b128 v[186:189], v163 offset:128
	ds_read_b128 v[190:193], v163 offset:8832
	s_waitcnt lgkmcnt(1)
	v_mfma_f32_32x32x16_bf16 v[82:97], v[186:189], v[114:117], v[82:97]
	s_waitcnt lgkmcnt(0)
	v_mfma_f32_32x32x16_bf16 v[66:81], v[190:193], v[114:117], v[66:81]
	ds_read_b128 v[186:189], v163 offset:160
	ds_read_b128 v[190:193], v163 offset:8864
	s_waitcnt lgkmcnt(1)
	v_mfma_f32_32x32x16_bf16 v[82:97], v[186:189], v[118:121], v[82:97]
	s_waitcnt lgkmcnt(0)
	v_mfma_f32_32x32x16_bf16 v[66:81], v[190:193], v[118:121], v[66:81]
	ds_read_b128 v[186:189], v163 offset:192
	ds_read_b128 v[190:193], v163 offset:8896
	s_waitcnt lgkmcnt(1)
	v_mfma_f32_32x32x16_bf16 v[82:97], v[186:189], v[122:125], v[82:97]
	s_waitcnt lgkmcnt(0)
	v_mfma_f32_32x32x16_bf16 v[66:81], v[190:193], v[122:125], v[66:81]
	ds_read_b128 v[186:189], v163 offset:224
	ds_read_b128 v[190:193], v163 offset:8928
	ds_read_b128 v[204:207], v201 offset:34816
	ds_read_b128 v[214:217], v201 offset:34848
	s_waitcnt lgkmcnt(3)
	v_mfma_f32_32x32x16_bf16 v[82:97], v[186:189], v[126:129], v[82:97]
	s_waitcnt lgkmcnt(2)
	v_mfma_f32_32x32x16_bf16 v[66:81], v[190:193], v[126:129], v[66:81]
	s_nop 9
	v_max_f32_e32 v174, v83, v83
	v_max_f32_e32 v186, v84, v84
	v_max_f32_e32 v187, v85, v85
	v_max_f32_e32 v163, v67, v67
	v_max_f32_e32 v163, v174, v163
	v_max_f32_e32 v174, v68, v68
	v_max_f32_e32 v174, v186, v174
	v_max_f32_e32 v186, v69, v69
	v_max3_f32 v163, v82, v66, v163
	v_max_f32_e32 v186, v187, v186
	v_max3_f32 v163, v163, v174, v186
	v_max_f32_e32 v174, v70, v70
	v_max_f32_e32 v186, v86, v86
	v_max_f32_e32 v174, v186, v174
	v_max_f32_e32 v186, v71, v71
	v_max_f32_e32 v187, v87, v87
	v_max_f32_e32 v186, v187, v186
	v_max3_f32 v163, v163, v174, v186
	v_max_f32_e32 v174, v72, v72
	v_max_f32_e32 v186, v88, v88
	v_max_f32_e32 v174, v186, v174
	v_max_f32_e32 v186, v73, v73
	v_max_f32_e32 v187, v89, v89
	v_max_f32_e32 v186, v187, v186
	v_max3_f32 v163, v163, v174, v186
	v_max_f32_e32 v174, v74, v74
	v_max_f32_e32 v186, v90, v90
	v_max_f32_e32 v174, v186, v174
	v_max_f32_e32 v186, v75, v75
	v_max_f32_e32 v187, v91, v91
	v_max_f32_e32 v186, v187, v186
	v_max3_f32 v163, v163, v174, v186
	v_max_f32_e32 v174, v76, v76
	v_max_f32_e32 v186, v92, v92
	v_max_f32_e32 v174, v186, v174
	v_max_f32_e32 v186, v77, v77
	v_max_f32_e32 v187, v93, v93
	v_max_f32_e32 v186, v187, v186
	v_max3_f32 v163, v163, v174, v186
	v_max_f32_e32 v174, v78, v78
	v_max_f32_e32 v186, v94, v94
	v_max_f32_e32 v174, v186, v174
	v_max_f32_e32 v186, v79, v79
	v_max_f32_e32 v187, v95, v95
	v_max_f32_e32 v186, v187, v186
	v_max3_f32 v163, v163, v174, v186
	v_max_f32_e32 v174, v80, v80
	v_max_f32_e32 v186, v96, v96
	v_max_f32_e32 v174, v186, v174
	v_max_f32_e32 v186, v81, v81
	v_max_f32_e32 v187, v97, v97
	v_max_f32_e32 v186, v187, v186
	v_max3_f32 v163, v163, v174, v186
	ds_bpermute_b32 v174, v182, v163
	s_waitcnt lgkmcnt(0)
	v_max3_f32 v163, v165, v163, v174
	v_sub_f32_e32 v165, v165, v163
	v_sub_f32_e32 v66, v66, v163
	v_exp_f32_e32 v174, v165
	v_exp_f32_e32 v165, v66
	v_sub_f32_e32 v66, v83, v163
	v_exp_f32_e32 v83, v66
	v_sub_f32_e32 v66, v67, v163
	v_exp_f32_e32 v186, v66
	v_sub_f32_e32 v66, v84, v163
	v_exp_f32_e32 v84, v66
	v_sub_f32_e32 v66, v68, v163
	v_exp_f32_e32 v187, v66
	v_sub_f32_e32 v66, v85, v163
	v_exp_f32_e32 v85, v66
	v_sub_f32_e32 v66, v69, v163
	v_exp_f32_e32 v188, v66
	v_sub_f32_e32 v66, v86, v163
	v_exp_f32_e32 v86, v66
	v_sub_f32_e32 v66, v70, v163
	v_exp_f32_e32 v189, v66
	v_sub_f32_e32 v66, v87, v163
	v_exp_f32_e32 v87, v66
	v_sub_f32_e32 v66, v71, v163
	v_exp_f32_e32 v190, v66
	v_sub_f32_e32 v66, v88, v163
	v_exp_f32_e32 v88, v66
	v_sub_f32_e32 v66, v72, v163
	v_exp_f32_e32 v191, v66
	v_sub_f32_e32 v66, v89, v163
	v_exp_f32_e32 v89, v66
	v_sub_f32_e32 v66, v73, v163
	v_exp_f32_e32 v192, v66
	v_sub_f32_e32 v66, v90, v163
	v_exp_f32_e32 v90, v66
	v_sub_f32_e32 v66, v74, v163
	v_exp_f32_e32 v193, v66
	v_sub_f32_e32 v66, v91, v163
	v_exp_f32_e32 v91, v66
	v_sub_f32_e32 v66, v75, v163
	v_exp_f32_e32 v194, v66
	v_sub_f32_e32 v66, v92, v163
	v_exp_f32_e32 v92, v66
	v_sub_f32_e32 v66, v76, v163
	v_exp_f32_e32 v195, v66
	v_sub_f32_e32 v66, v93, v163
	v_exp_f32_e32 v93, v66
	v_sub_f32_e32 v66, v77, v163
	v_exp_f32_e32 v196, v66
	v_sub_f32_e32 v66, v94, v163
	v_exp_f32_e32 v94, v66
	v_sub_f32_e32 v66, v78, v163
	v_sub_f32_e32 v82, v82, v163
	v_exp_f32_e32 v197, v66
	v_sub_f32_e32 v66, v95, v163
	v_exp_f32_e32 v82, v82
	v_exp_f32_e32 v95, v66
	v_sub_f32_e32 v66, v79, v163
	v_exp_f32_e32 v198, v66
	v_sub_f32_e32 v66, v96, v163
	v_exp_f32_e32 v96, v66
	v_sub_f32_e32 v66, v80, v163
	v_exp_f32_e32 v199, v66
	v_sub_f32_e32 v66, v97, v163
	v_exp_f32_e32 v97, v66
	v_sub_f32_e32 v66, v81, v163
	v_mul_f32_e32 v64, v64, v174
	v_mul_f32_e32 v65, v65, v174
	v_mul_f32_e32 v62, v62, v174
	v_mul_f32_e32 v63, v63, v174
	v_mul_f32_e32 v60, v60, v174
	v_mul_f32_e32 v61, v61, v174
	v_mul_f32_e32 v58, v58, v174
	v_mul_f32_e32 v59, v59, v174
	v_mul_f32_e32 v56, v56, v174
	v_mul_f32_e32 v57, v57, v174
	v_mul_f32_e32 v54, v54, v174
	v_mul_f32_e32 v55, v55, v174
	v_mul_f32_e32 v52, v52, v174
	v_mul_f32_e32 v53, v53, v174
	v_mul_f32_e32 v50, v50, v174
	v_mul_f32_e32 v51, v51, v174
	v_cvt_pk_bf16_f32 v78, v82, v83
	v_cvt_pk_bf16_f32 v79, v84, v85
	v_cvt_pk_bf16_f32 v80, v86, v87
	v_cvt_pk_bf16_f32 v81, v88, v89
	v_cvt_pk_bf16_f32 v70, v90, v91
	v_cvt_pk_bf16_f32 v71, v92, v93
	v_mfma_f32_32x32x16_bf16 v[50:65], v[204:207], v[78:81], v[50:65]
	v_cvt_pk_bf16_f32 v72, v94, v95
	v_cvt_pk_bf16_f32 v73, v96, v97
	ds_read_b128 v[204:207], v201 offset:34880
	v_cvt_pk_bf16_f32 v74, v165, v186
	v_cvt_pk_bf16_f32 v75, v187, v188
	v_cvt_pk_bf16_f32 v76, v189, v190
	v_cvt_pk_bf16_f32 v77, v191, v192
	v_mfma_f32_32x32x16_bf16 v[50:65], v[214:217], v[70:73], v[50:65]
	v_exp_f32_e32 v200, v66
	v_cvt_pk_bf16_f32 v66, v193, v194
	v_cvt_pk_bf16_f32 v67, v195, v196
	v_cvt_pk_bf16_f32 v68, v197, v198
	v_cvt_pk_bf16_f32 v69, v199, v200
	v_mul_f32_e32 v48, v48, v174
	v_mul_f32_e32 v49, v49, v174
	v_mul_f32_e32 v46, v46, v174
	v_mul_f32_e32 v47, v47, v174
	s_waitcnt lgkmcnt(0)
	v_mfma_f32_32x32x16_bf16 v[50:65], v[204:207], v[74:77], v[50:65]
	ds_read_b128 v[204:207], v201 offset:34912
	v_mul_f32_e64 v44, v44, v174
	v_mul_f32_e64 v45, v45, v174
	v_mul_f32_e64 v42, v42, v174
	v_mul_f32_e64 v43, v43, v174
	v_mul_f32_e32 v40, v40, v174
	v_mul_f32_e32 v41, v41, v174
	v_mul_f32_e32 v38, v38, v174
	v_mul_f32_e32 v39, v39, v174
	v_mul_f32_e32 v36, v36, v174
	v_mul_f32_e32 v37, v37, v174
	v_mul_f32_e32 v34, v34, v174
	v_mul_f32_e32 v35, v35, v174
	s_waitcnt lgkmcnt(0)
	v_mfma_f32_32x32x16_bf16 v[50:65], v[204:207], v[66:69], v[50:65]
	ds_read_b128 v[204:207], v201 offset:39424
	v_mul_f32_e64 v32, v32, v174
	v_mul_f32_e64 v33, v33, v174
	v_mul_f32_e64 v30, v30, v174
	v_mul_f32_e64 v31, v31, v174
	v_mul_f32_e32 v28, v28, v174
	v_mul_f32_e32 v29, v29, v174
	v_mul_f32_e32 v26, v26, v174
	v_mul_f32_e32 v27, v27, v174
	v_mul_f32_e32 v24, v24, v174
	v_mul_f32_e32 v25, v25, v174
	v_mul_f32_e32 v22, v22, v174
	v_mul_f32_e32 v23, v23, v174
	s_waitcnt lgkmcnt(0)
	v_mfma_f32_32x32x16_bf16 v[34:49], v[204:207], v[78:81], v[34:49]
	ds_read_b128 v[204:207], v201 offset:39456
	v_mul_f32_e64 v20, v20, v174
	v_mul_f32_e64 v21, v21, v174
	v_mul_f32_e64 v18, v18, v174
	v_mul_f32_e64 v19, v19, v174
	v_mul_f32_e32 v16, v16, v174
	v_mul_f32_e32 v17, v17, v174
	v_mul_f32_e32 v14, v14, v174
	v_mul_f32_e32 v15, v15, v174
	v_mul_f32_e32 v12, v12, v174
	v_mul_f32_e32 v13, v13, v174
	v_mul_f32_e32 v10, v10, v174
	v_mul_f32_e32 v11, v11, v174
	s_waitcnt lgkmcnt(0)
	v_mfma_f32_32x32x16_bf16 v[34:49], v[204:207], v[70:73], v[34:49]
	ds_read_b128 v[204:207], v201 offset:39488
	v_mul_f32_e64 v8, v8, v174
	v_mul_f32_e64 v9, v9, v174
	v_mul_f32_e64 v6, v6, v174
	v_mul_f32_e64 v7, v7, v174
	v_mul_f32_e32 v4, v4, v174
	v_mul_f32_e32 v5, v5, v174
	v_mul_f32_e32 v2, v2, v174
	v_mul_f32_e32 v3, v3, v174
	s_waitcnt lgkmcnt(0)
	v_mfma_f32_32x32x16_bf16 v[34:49], v[204:207], v[74:77], v[34:49]
	ds_read_b128 v[204:207], v201 offset:39520
	s_waitcnt lgkmcnt(0)
	v_mfma_f32_32x32x16_bf16 v[34:49], v[204:207], v[66:69], v[34:49]
	ds_read_b128 v[204:207], v201 offset:44032
	s_waitcnt lgkmcnt(0)
	v_mfma_f32_32x32x16_bf16 v[18:33], v[204:207], v[78:81], v[18:33]
	ds_read_b128 v[204:207], v201 offset:44064
	s_waitcnt lgkmcnt(0)
	v_mfma_f32_32x32x16_bf16 v[18:33], v[204:207], v[70:73], v[18:33]
	ds_read_b128 v[204:207], v201 offset:44096
	s_waitcnt lgkmcnt(0)
	v_mfma_f32_32x32x16_bf16 v[18:33], v[204:207], v[74:77], v[18:33]
	ds_read_b128 v[204:207], v201 offset:44128
	s_waitcnt lgkmcnt(0)
	v_mfma_f32_32x32x16_bf16 v[18:33], v[204:207], v[66:69], v[18:33]
	ds_read_b128 v[204:207], v201 offset:48640
	s_waitcnt lgkmcnt(0)
	v_mfma_f32_32x32x16_bf16 v[2:17], v[204:207], v[78:81], v[2:17]
	ds_read_b128 v[78:81], v201 offset:48672
	s_waitcnt lgkmcnt(0)
	v_mfma_f32_32x32x16_bf16 v[2:17], v[78:81], v[70:73], v[2:17]
	ds_read_b128 v[70:73], v201 offset:48704
	s_waitcnt lgkmcnt(0)
	v_mfma_f32_32x32x16_bf16 v[2:17], v[70:73], v[74:77], v[2:17]
	ds_read_b128 v[70:73], v201 offset:48736
	s_waitcnt lgkmcnt(0)
	v_mfma_f32_32x32x16_bf16 v[2:17], v[70:73], v[66:69], v[2:17]
	s_cbranch_vccnz .LBB0_1476
	s_xor_b32 s4, s4, 1
	s_mul_i32 s2, s4, 0x4400
	s_add_i32 s5, s2, 0
	s_and_saveexec_b64 s[2:3], s[36:37]
	s_cbranch_execz .LBB0_1473
	v_add3_u32 v66, s5, v176, v177
	s_waitcnt vmcnt(2)
	ds_write_b128 v66, v[130:133]

.LBB0_1535:
	global_load_dwordx2 v[14:15], v1, s[2:3]
	global_load_dwordx2 v[16:17], v[6:7], off offset:-1024 nt
	global_load_dwordx4 v[10:13], v[2:3], off
	s_add_i32 s10, s10, s88
	s_add_u32 s2, s2, s4
	s_addc_u32 s3, s3, s5
	s_cmpk_gt_i32 s10, 0x3fff
	s_waitcnt vmcnt(0)
	v_ffbh_u32_e32 v9, v15
	v_min_u32_e32 v9, 32, v9
	v_lshlrev_b64 v[14:15], v9, v[14:15]
	v_min_u32_e32 v14, 1, v14
	v_or_b32_e32 v14, v15, v14
	v_cvt_f32_u32_e32 v14, v14
	v_sub_u32_e32 v9, 32, v9
	s_waitcnt vmcnt(1)
	v_lshlrev_b32_e32 v18, 16, v16
	v_and_b32_e32 v19, 0xffff0000, v16
	v_ldexp_f32 v9, v14, v9
	v_mul_f32_e32 v9, 0x35800000, v9
	v_fmamk_f32 v9, v9, 0x3a800000, v8
	v_mul_f32_e32 v14, 0x4f800000, v9
	v_cmp_gt_f32_e32 vcc, s11, v9
	v_lshlrev_b32_e32 v16, 16, v17
	v_and_b32_e32 v17, 0xffff0000, v17
	v_cndmask_b32_e32 v9, v9, v14, vcc
	v_sqrt_f32_e32 v14, v9
	s_nop 0
	v_add_u32_e32 v15, -1, v14
	v_add_u32_e32 v20, 1, v14
	v_fma_f32 v21, -v15, v14, v9
	v_fma_f32 v22, -v20, v14, v9
	v_cmp_ge_f32_e64 s[0:1], 0, v21
	s_nop 1
	v_cndmask_b32_e64 v14, v14, v15, s[0:1]
	v_cmp_lt_f32_e64 s[0:1], 0, v22
	s_nop 1
	v_cndmask_b32_e64 v14, v14, v20, s[0:1]
	v_mul_f32_e32 v15, 0x37800000, v14
	v_cndmask_b32_e32 v14, v14, v15, vcc
	v_cmp_class_f32_e32 vcc, v9, v0
	s_nop 1
	v_cndmask_b32_e32 v9, v14, v9, vcc
	v_div_scale_f32 v14, s[0:1], v9, v9, 1.0
	v_rcp_f32_e32 v20, v14
	v_div_scale_f32 v15, vcc, 1.0, v9, 1.0
	v_fma_f32 v21, -v14, v20, 1.0
	v_fmac_f32_e32 v20, v21, v20
	v_mul_f32_e32 v21, v15, v20
	v_fma_f32 v22, -v14, v21, v15
	v_fmac_f32_e32 v21, v22, v20
	v_fma_f32 v14, -v14, v21, v15
	v_div_fmas_f32 v14, v14, v20, v21
	v_div_fixup_f32 v14, v14, v9, 1.0
	v_mul_f32_e32 v18, v14, v18
	v_mul_f32_e32 v19, v14, v19
	v_mul_f32_e32 v16, v14, v16
	v_mul_f32_e32 v17, v14, v17
	s_waitcnt vmcnt(0)
	v_mul_f32_e32 v12, v12, v16
	v_mul_f32_e32 v13, v13, v17
	v_mul_f32_e32 v10, v10, v18
	v_mul_f32_e32 v11, v11, v19
	flat_store_dwordx4 v[4:5], v[10:13] nt
	global_load_dwordx2 v[16:17], v[6:7], off offset:-512 nt
	s_nop 0
	global_load_dwordx4 v[10:13], v[2:3], off offset:1024
	s_waitcnt vmcnt(0)
	v_lshlrev_b32_e32 v18, 16, v16
	v_and_b32_e32 v19, 0xffff0000, v16
	v_lshlrev_b32_e32 v16, 16, v17
	v_and_b32_e32 v17, 0xffff0000, v17
	v_mul_f32_e32 v18, v14, v18
	v_mul_f32_e32 v19, v14, v19
	v_mul_f32_e32 v16, v14, v16
	v_mul_f32_e32 v17, v14, v17
	v_mul_f32_e32 v12, v12, v16
	v_mul_f32_e32 v13, v13, v17
	v_mul_f32_e32 v10, v10, v18
	v_mul_f32_e32 v11, v11, v19
	flat_store_dwordx4 v[4:5], v[10:13] offset:1024 nt
	global_load_dwordx2 v[16:17], v[6:7], off nt
	s_nop 0
	global_load_dwordx4 v[10:13], v[2:3], off offset:2048
	s_waitcnt vmcnt(0)
	v_lshlrev_b32_e32 v18, 16, v16
	v_and_b32_e32 v19, 0xffff0000, v16
	v_lshlrev_b32_e32 v16, 16, v17
	v_and_b32_e32 v17, 0xffff0000, v17
	v_mul_f32_e32 v18, v14, v18
	v_mul_f32_e32 v19, v14, v19
	v_mul_f32_e32 v16, v14, v16
	v_mul_f32_e32 v17, v14, v17
	v_mul_f32_e32 v12, v12, v16
	v_mul_f32_e32 v13, v13, v17
	v_mul_f32_e32 v10, v10, v18
	v_mul_f32_e32 v11, v11, v19
	flat_store_dwordx4 v[4:5], v[10:13] offset:2048 nt
	global_load_dwordx2 v[16:17], v[6:7], off offset:512 nt
	s_nop 0
	global_load_dwordx4 v[10:13], v[2:3], off offset:3072
	v_lshl_add_u64 v[6:7], v[6:7], 0, s[8:9]
	s_waitcnt vmcnt(0)
	v_lshlrev_b32_e32 v18, 16, v16
	v_and_b32_e32 v19, 0xffff0000, v16
	v_lshlrev_b32_e32 v16, 16, v17
	v_and_b32_e32 v17, 0xffff0000, v17
	v_mul_f32_e32 v18, v14, v18
	v_mul_f32_e32 v19, v14, v19
	v_mul_f32_e32 v15, v14, v17
	v_mul_f32_e32 v14, v14, v16
	v_mul_f32_e32 v12, v12, v14
	v_mul_f32_e32 v13, v13, v15
	v_mul_f32_e32 v10, v10, v18
	v_mul_f32_e32 v11, v11, v19
	flat_store_dwordx4 v[4:5], v[10:13] offset:3072 nt
	v_lshl_add_u64 v[4:5], v[4:5], 0, s[6:7]
	s_cbranch_scc0 .LBB0_1535
